# tail converter f32 source loads with default cache policy instead of nt
# baseline (speedup 1.0000x reference)
; #define LAS __attribute__((address_space(3)))
; __device__ __forceinline__ void tr_load(const float* W, int N, int item, int lane, float (&wv)[32]) {
;     const int nblk = N / 32, kb = item / nblk, nb = item % nblk, k0 = 64 * kb, n0 = 32 * nb;
; #pragma unroll
;     for (int i = 0; i < 32; ++i) { const int kk = 2 * i + (lane >> 5); wv[i] = __builtin_nontemporal_load(W + (size_t)(k0 + kk) * N + n0 + (lane & 31)); }
; template <int MAP, bool HASG = false, bool PERMW = false>
; __device__ __forceinline__ void transpose_mat(const float* W, int K, int N, bf16_t* WT, LAS float* scr, int gw, int ngw, int lane, const float* gk = nullptr) {
;     const int nitems = (K / 64) * (N / 32);
;     int it = gw;
;     if (it >= nitems) return;
;     float wv[32];
;     tr_load(W, N, it, lane, wv);
.LBB0_158:
	s_lshr_b32 vcc_lo, s78, 1
	s_cmp_lt_u32 s2, vcc_lo
	s_cbranch_scc1 .Ltc1_done
	v_writelane_b32 v255, s4, 24
	v_writelane_b32 v255, s5, 25
	v_writelane_b32 v255, s6, 26
	v_writelane_b32 v255, s7, 27
	v_writelane_b32 v255, s8, 28
	v_writelane_b32 v255, s9, 29
	v_writelane_b32 v255, s10, 30
	v_writelane_b32 v255, s11, 31
	v_writelane_b32 v255, s12, 32
	v_writelane_b32 v255, s13, 33
	v_writelane_b32 v255, s14, 34
	v_writelane_b32 v255, s15, 35
	v_writelane_b32 v255, s16, 36
	v_writelane_b32 v255, s17, 37
	v_writelane_b32 v255, s18, 38
	v_writelane_b32 v255, s19, 39
	v_writelane_b32 v255, s20, 40
	v_writelane_b32 v255, s21, 41
	v_writelane_b32 v255, s22, 42
	v_writelane_b32 v255, s23, 43
	v_writelane_b32 v255, s24, 44
	v_writelane_b32 v255, s25, 45
	v_writelane_b32 v255, s26, 46
	v_writelane_b32 v255, s27, 47
	v_writelane_b32 v255, s28, 48
	v_writelane_b32 v255, s29, 49
	v_readfirstlane_b32 s8, v234
	s_nop 3
	s_lshr_b32 s8, s8, 6
	s_lshr_b32 s19, s78, 1
	s_sub_u32 s18, s2, s19
	s_lshl_b32 s18, s18, 3
	s_add_u32 s18, s18, s8
	s_sub_u32 s19, s78, s19
	s_lshl_b32 s19, s19, 3
	s_mul_i32 s10, s8, 0x2100
	v_and_b32_e32 v0, 63, v234
	v_and_b32_e32 v1, 31, v0
	v_lshrrev_b32_e32 v2, 5, v0
	v_lshlrev_b32_e32 v3, 13, v2
	v_lshl_add_u32 v3, v1, 2, v3
	v_mul_u32_u24_e32 v4, 33, v2
	v_add_u32_e32 v4, v4, v1
	v_lshl_add_u32 v4, v4, 2, s10
	v_and_b32_e32 v5, 7, v0
	v_lshrrev_b32_e32 v6, 3, v0
	v_mul_u32_u24_e32 v7, 0x108, v5
	v_add_u32_e32 v7, v7, v6
	v_lshl_add_u32 v7, v7, 2, s10
	v_lshrrev_b32_e32 v12, 2, v5
	v_lshlrev_b32_e32 v12, 10, v12
	v_and_b32_e32 v13, 3, v5
	v_lshl_add_u32 v12, v13, 4, v12
	v_lshl_add_u32 v8, v6, 6, v12
	v_xor_b32_e32 v9, 32, v8
	v_add_u32_e32 v9, 0x200, v9
	v_and_b32_e32 v13, 3, v6
	v_lshl_add_u32 v10, v13, 6, v12
	v_bfe_u32 v13, v6, 2, 1
	v_lshl_add_u32 v10, v13, 11, v10
	v_xor_b32_e32 v11, 32, v10
	v_lshlrev_b32_e32 v14, 5, v5
	v_mul_u32_u24_e32 v15, 0x5800, v2
	v_lshl_add_u32 v15, v1, 2, v15
	v_mul_u32_u24_e32 v12, 0xd000, v2
	v_lshl_add_u32 v12, v1, 2, v12
	v_readlane_b32 s4, v255, 4
	v_readlane_b32 s5, v255, 5
	s_nop 3
	s_and_b32 s6, s60, 0x2c00000
	s_add_u32 s4, s4, s6
	s_addc_u32 s5, s5, 0
	s_add_u32 s6, s76, 0x2c00000
	s_addc_u32 s7, s77, 0
	s_mov_b32 s9, s18
	s_cmpk_ge_u32 s9, 0x1600
	s_cbranch_scc1 .Ltc1a_exit
	s_lshr_b32 s11, s9, 6
	s_and_b32 s12, s9, 63
	s_lshl_b32 s13, s11, 19
	s_lshl_b32 s14, s12, 7
	s_add_u32 s13, s13, s14
	s_add_u32 s14, s4, s13
	s_addc_u32 s15, s5, 0
	global_load_dword v16, v3, s[14:15]
	s_add_u32 s14, s14, 0x4000
	s_addc_u32 s15, s15, 0
	global_load_dword v17, v3, s[14:15]
	s_add_u32 s14, s14, 0x4000
	s_addc_u32 s15, s15, 0
	global_load_dword v18, v3, s[14:15]
	s_add_u32 s14, s14, 0x4000
	s_addc_u32 s15, s15, 0
	global_load_dword v19, v3, s[14:15]
	s_add_u32 s14, s14, 0x4000
	s_addc_u32 s15, s15, 0
	global_load_dword v20, v3, s[14:15]
	s_add_u32 s14, s14, 0x4000
	s_addc_u32 s15, s15, 0
	global_load_dword v21, v3, s[14:15]
	s_add_u32 s14, s14, 0x4000
	s_addc_u32 s15, s15, 0
	global_load_dword v22, v3, s[14:15]
	s_add_u32 s14, s14, 0x4000
	s_addc_u32 s15, s15, 0
	global_load_dword v23, v3, s[14:15]
	s_add_u32 s14, s14, 0x4000
	s_addc_u32 s15, s15, 0
	global_load_dword v24, v3, s[14:15]
	s_add_u32 s14, s14, 0x4000
	s_addc_u32 s15, s15, 0
	global_load_dword v25, v3, s[14:15]
	s_add_u32 s14, s14, 0x4000
	s_addc_u32 s15, s15, 0
	global_load_dword v26, v3, s[14:15]
	s_add_u32 s14, s14, 0x4000
	s_addc_u32 s15, s15, 0
	global_load_dword v27, v3, s[14:15]
	s_add_u32 s14, s14, 0x4000
	s_addc_u32 s15, s15, 0
	global_load_dword v28, v3, s[14:15]
	s_add_u32 s14, s14, 0x4000
	s_addc_u32 s15, s15, 0
	global_load_dword v29, v3, s[14:15]
	s_add_u32 s14, s14, 0x4000
	s_addc_u32 s15, s15, 0
	global_load_dword v30, v3, s[14:15]
	s_add_u32 s14, s14, 0x4000
	s_addc_u32 s15, s15, 0
	global_load_dword v31, v3, s[14:15]
	s_add_u32 s14, s14, 0x4000
	s_addc_u32 s15, s15, 0
	global_load_dword v32, v3, s[14:15]
	s_add_u32 s14, s14, 0x4000
	s_addc_u32 s15, s15, 0
	global_load_dword v33, v3, s[14:15]
	s_add_u32 s14, s14, 0x4000
	s_addc_u32 s15, s15, 0
	global_load_dword v34, v3, s[14:15]
	s_add_u32 s14, s14, 0x4000
	s_addc_u32 s15, s15, 0
	global_load_dword v35, v3, s[14:15]
	s_add_u32 s14, s14, 0x4000
	s_addc_u32 s15, s15, 0
	global_load_dword v36, v3, s[14:15]
	s_add_u32 s14, s14, 0x4000
	s_addc_u32 s15, s15, 0
	global_load_dword v37, v3, s[14:15]
	s_add_u32 s14, s14, 0x4000
	s_addc_u32 s15, s15, 0
	global_load_dword v38, v3, s[14:15]
	s_add_u32 s14, s14, 0x4000
	s_addc_u32 s15, s15, 0
	global_load_dword v39, v3, s[14:15]
	s_add_u32 s14, s14, 0x4000
	s_addc_u32 s15, s15, 0
	global_load_dword v40, v3, s[14:15]
	s_add_u32 s14, s14, 0x4000
	s_addc_u32 s15, s15, 0
	global_load_dword v41, v3, s[14:15]
	s_add_u32 s14, s14, 0x4000
	s_addc_u32 s15, s15, 0
	global_load_dword v42, v3, s[14:15]
	s_add_u32 s14, s14, 0x4000
	s_addc_u32 s15, s15, 0
	global_load_dword v43, v3, s[14:15]
	s_add_u32 s14, s14, 0x4000
	s_addc_u32 s15, s15, 0
	global_load_dword v44, v3, s[14:15]
	s_add_u32 s14, s14, 0x4000
	s_addc_u32 s15, s15, 0
	global_load_dword v45, v3, s[14:15]
	s_add_u32 s14, s14, 0x4000
	s_addc_u32 s15, s15, 0
	global_load_dword v46, v3, s[14:15]
	s_add_u32 s14, s14, 0x4000
	s_addc_u32 s15, s15, 0
	global_load_dword v47, v3, s[14:15]
	s_lshr_b32 s16, s12, 2
	s_mul_i32 s16, s16, 0x58
	s_add_u32 s16, s16, s11
	s_lshl_b32 s16, s16, 14
	s_and_b32 s17, s12, 3
	s_lshl_b32 s17, s17, 12
	s_add_u32 s16, s16, s17
	s_add_u32 s16, s6, s16
	s_addc_u32 s17, s7, 0
; #define LAS __attribute__((address_space(3)))
; __device__ __forceinline__ unsigned pk2(float lo, float hi) { f32x2 f = {lo, hi}; bf16x2_t b = __builtin_convertvector(f, bf16x2_t); return __builtin_bit_cast(unsigned, b); }
; template <int MAP, bool HASG, bool PERMW>
; __device__ __forceinline__ void tr_store(int K, int N, bf16_t* WT, LAS float* scr, int item, int lane, const float* gk) {
;     const int nblk = N / 32, kb = item / nblk, nb = item % nblk, k0 = 64 * kb, n0 = 32 * nb;
;     asm volatile("s_waitcnt lgkmcnt(0)" ::: "memory");
;     const int c = lane & 7;
;     f32x4 g0 = {1.f, 1.f, 1.f, 1.f}, g1 = {1.f, 1.f, 1.f, 1.f};
;     if (HASG) { g0 = *(const f32x4*)(gk + k0 + 8 * c); g1 = *(const f32x4*)(gk + k0 + 8 * c + 4); }
; #pragma unroll
;     for (int j = 0; j < 4; ++j) { const int n = (lane >> 3) + 8 * j; const LAS float* s = scr + (8 * c) * 33 + n;
;         u32x4 o; o.x = pk2(s[0 * 33] * g0[0], s[1 * 33] * g0[1]); o.y = pk2(s[2 * 33] * g0[2], s[3 * 33] * g0[3]); o.z = pk2(s[4 * 33] * g1[0], s[5 * 33] * g1[1]); o.w = pk2(s[6 * 33] * g1[2], s[7 * 33] * g1[3]);
;         const int wr_ = rowmap<MAP>(n0 + n), slot_ = PERMW ? ((wr_ & ~31) + invperm32(wr_ & 31)) : wr_;
;         *(u32x4*)((char*)WT + tiled_off(slot_, k0 + 8 * c, K / 64)) = o; }
;     asm volatile("s_waitcnt lgkmcnt(0)" ::: "memory");
; }
; template <int MAP, bool HASG = false, bool PERMW = false>
; __device__ __forceinline__ void transpose_mat(const float* W, int K, int N, bf16_t* WT, LAS float* scr, int gw, int ngw, int lane, const float* gk = nullptr) {
;     const int nitems = (K / 64) * (N / 32);
;     int it = gw;
;     if (it >= nitems) return;
;     float wv[32];
;     tr_load(W, N, it, lane, wv);
;     for (;;) {
;         __builtin_amdgcn_sched_barrier(0);
; #pragma unroll
;         for (int i = 0; i < 32; ++i) { const int kk = 2 * i + (lane >> 5); scr[kk * 33 + (lane & 31)] = wv[i]; }
;         __builtin_amdgcn_sched_barrier(0);
;         const int nx = it + ngw;
;         if (nx < nitems) tr_load(W, N, nx, lane, wv);
;         __builtin_amdgcn_sched_barrier(0);
;         tr_store<MAP, HASG, PERMW>(K, N, WT, scr, it, lane, gk);
;         if (nx >= nitems) break;
;         it = nx;
;     }
.Ltc1a_loop:
	s_add_u32 s9, s9, s19
	s_cmpk_ge_u32 s9, 0x1600
	s_cbranch_scc1 .Ltc1a_lastA
	s_lshr_b32 s11, s9, 6
	s_and_b32 s12, s9, 63
	s_lshl_b32 s13, s11, 19
	s_lshl_b32 s14, s12, 7
	s_add_u32 s13, s13, s14
	s_add_u32 s14, s4, s13
	s_addc_u32 s15, s5, 0
	global_load_dword v88, v3, s[14:15]
	s_add_u32 s14, s14, 0x4000
	s_addc_u32 s15, s15, 0
	global_load_dword v89, v3, s[14:15]
	s_add_u32 s14, s14, 0x4000
	s_addc_u32 s15, s15, 0
	global_load_dword v90, v3, s[14:15]
	s_add_u32 s14, s14, 0x4000
	s_addc_u32 s15, s15, 0
	global_load_dword v91, v3, s[14:15]
	s_add_u32 s14, s14, 0x4000
	s_addc_u32 s15, s15, 0
	global_load_dword v92, v3, s[14:15]
	s_add_u32 s14, s14, 0x4000
	s_addc_u32 s15, s15, 0
	global_load_dword v93, v3, s[14:15]
	s_add_u32 s14, s14, 0x4000
	s_addc_u32 s15, s15, 0
	global_load_dword v94, v3, s[14:15]
	s_add_u32 s14, s14, 0x4000
	s_addc_u32 s15, s15, 0
	global_load_dword v95, v3, s[14:15]
	s_add_u32 s14, s14, 0x4000
	s_addc_u32 s15, s15, 0
	global_load_dword v96, v3, s[14:15]
	s_add_u32 s14, s14, 0x4000
	s_addc_u32 s15, s15, 0
	global_load_dword v97, v3, s[14:15]
	s_add_u32 s14, s14, 0x4000
	s_addc_u32 s15, s15, 0
	global_load_dword v98, v3, s[14:15]
	s_add_u32 s14, s14, 0x4000
	s_addc_u32 s15, s15, 0
	global_load_dword v99, v3, s[14:15]
	s_add_u32 s14, s14, 0x4000
	s_addc_u32 s15, s15, 0
	global_load_dword v100, v3, s[14:15]
	s_add_u32 s14, s14, 0x4000
	s_addc_u32 s15, s15, 0
	global_load_dword v101, v3, s[14:15]
	s_add_u32 s14, s14, 0x4000
	s_addc_u32 s15, s15, 0
	global_load_dword v102, v3, s[14:15]
	s_add_u32 s14, s14, 0x4000
	s_addc_u32 s15, s15, 0
	global_load_dword v103, v3, s[14:15]
	s_add_u32 s14, s14, 0x4000
	s_addc_u32 s15, s15, 0
	global_load_dword v104, v3, s[14:15]
	s_add_u32 s14, s14, 0x4000
	s_addc_u32 s15, s15, 0
	global_load_dword v105, v3, s[14:15]
	s_add_u32 s14, s14, 0x4000
	s_addc_u32 s15, s15, 0
	global_load_dword v106, v3, s[14:15]
	s_add_u32 s14, s14, 0x4000
	s_addc_u32 s15, s15, 0
	global_load_dword v107, v3, s[14:15]
	s_add_u32 s14, s14, 0x4000
	s_addc_u32 s15, s15, 0
	global_load_dword v108, v3, s[14:15]
	s_add_u32 s14, s14, 0x4000
	s_addc_u32 s15, s15, 0
	global_load_dword v109, v3, s[14:15]
	s_add_u32 s14, s14, 0x4000
	s_addc_u32 s15, s15, 0
	global_load_dword v110, v3, s[14:15]
	s_add_u32 s14, s14, 0x4000
	s_addc_u32 s15, s15, 0
	global_load_dword v111, v3, s[14:15]
	s_add_u32 s14, s14, 0x4000
	s_addc_u32 s15, s15, 0
	global_load_dword v112, v3, s[14:15]
	s_add_u32 s14, s14, 0x4000
	s_addc_u32 s15, s15, 0
	global_load_dword v113, v3, s[14:15]
	s_add_u32 s14, s14, 0x4000
	s_addc_u32 s15, s15, 0
	global_load_dword v114, v3, s[14:15]
	s_add_u32 s14, s14, 0x4000
	s_addc_u32 s15, s15, 0
	global_load_dword v115, v3, s[14:15]
	s_add_u32 s14, s14, 0x4000
	s_addc_u32 s15, s15, 0
	global_load_dword v116, v3, s[14:15]
	s_add_u32 s14, s14, 0x4000
	s_addc_u32 s15, s15, 0
	global_load_dword v117, v3, s[14:15]
	s_add_u32 s14, s14, 0x4000
	s_addc_u32 s15, s15, 0
	global_load_dword v118, v3, s[14:15]
	s_add_u32 s14, s14, 0x4000
	s_addc_u32 s15, s15, 0
	global_load_dword v119, v3, s[14:15]
	s_lshr_b32 s24, s12, 2
	s_mul_i32 s24, s24, 0x58
	s_add_u32 s24, s24, s11
	s_lshl_b32 s24, s24, 14
	s_and_b32 s25, s12, 3
	s_lshl_b32 s25, s25, 12
	s_add_u32 s24, s24, s25
	s_add_u32 s24, s6, s24
	s_addc_u32 s25, s7, 0
	s_waitcnt vmcnt(32)
	ds_write_b32 v4, v16
	ds_write_b32 v4, v17 offset:264
	ds_write_b32 v4, v18 offset:528
	ds_write_b32 v4, v19 offset:792
	ds_write_b32 v4, v20 offset:1056
	ds_write_b32 v4, v21 offset:1320
	ds_write_b32 v4, v22 offset:1584
	ds_write_b32 v4, v23 offset:1848
	ds_write_b32 v4, v24 offset:2112
	ds_write_b32 v4, v25 offset:2376
	ds_write_b32 v4, v26 offset:2640
	ds_write_b32 v4, v27 offset:2904
	ds_write_b32 v4, v28 offset:3168
	ds_write_b32 v4, v29 offset:3432
	ds_write_b32 v4, v30 offset:3696
	ds_write_b32 v4, v31 offset:3960
	ds_write_b32 v4, v32 offset:4224
	ds_write_b32 v4, v33 offset:4488
	ds_write_b32 v4, v34 offset:4752
	ds_write_b32 v4, v35 offset:5016
	ds_write_b32 v4, v36 offset:5280
	ds_write_b32 v4, v37 offset:5544
	ds_write_b32 v4, v38 offset:5808
	ds_write_b32 v4, v39 offset:6072
	ds_write_b32 v4, v40 offset:6336
	ds_write_b32 v4, v41 offset:6600
	ds_write_b32 v4, v42 offset:6864
	ds_write_b32 v4, v43 offset:7128
	ds_write_b32 v4, v44 offset:7392
	ds_write_b32 v4, v45 offset:7656
	ds_write_b32 v4, v46 offset:7920
	ds_write_b32 v4, v47 offset:8184
	s_waitcnt lgkmcnt(0)
	ds_read_b32 v48, v7
	ds_read_b32 v49, v7 offset:132
	ds_read_b32 v50, v7 offset:264
	ds_read_b32 v51, v7 offset:396
	ds_read_b32 v52, v7 offset:528
	ds_read_b32 v53, v7 offset:660
	ds_read_b32 v54, v7 offset:792
	ds_read_b32 v55, v7 offset:924
	ds_read_b32 v56, v7 offset:32
	ds_read_b32 v57, v7 offset:164
	ds_read_b32 v58, v7 offset:296
	ds_read_b32 v59, v7 offset:428
	ds_read_b32 v60, v7 offset:560
	ds_read_b32 v61, v7 offset:692
	ds_read_b32 v62, v7 offset:824
	ds_read_b32 v63, v7 offset:956
	ds_read_b32 v64, v7 offset:64
	ds_read_b32 v65, v7 offset:196
	ds_read_b32 v66, v7 offset:328
	ds_read_b32 v67, v7 offset:460
	ds_read_b32 v68, v7 offset:592
	ds_read_b32 v69, v7 offset:724
	ds_read_b32 v70, v7 offset:856
	ds_read_b32 v71, v7 offset:988
	ds_read_b32 v72, v7 offset:96
	ds_read_b32 v73, v7 offset:228
	ds_read_b32 v74, v7 offset:360
	ds_read_b32 v75, v7 offset:492
	ds_read_b32 v76, v7 offset:624
	ds_read_b32 v77, v7 offset:756
	ds_read_b32 v78, v7 offset:888
	ds_read_b32 v79, v7 offset:1020
	s_waitcnt lgkmcnt(0)
	v_cvt_pk_bf16_f32 v48, v48, v49
	v_cvt_pk_bf16_f32 v49, v50, v51
	v_cvt_pk_bf16_f32 v50, v52, v53
	v_cvt_pk_bf16_f32 v51, v54, v55
	global_store_dwordx4 v8, v[48:51], s[16:17]
	v_cvt_pk_bf16_f32 v56, v56, v57
	v_cvt_pk_bf16_f32 v57, v58, v59
	v_cvt_pk_bf16_f32 v58, v60, v61
	v_cvt_pk_bf16_f32 v59, v62, v63
	global_store_dwordx4 v9, v[56:59], s[16:17]
	v_cvt_pk_bf16_f32 v64, v64, v65
	v_cvt_pk_bf16_f32 v65, v66, v67
	v_cvt_pk_bf16_f32 v66, v68, v69
	v_cvt_pk_bf16_f32 v67, v70, v71
	global_store_dwordx4 v8, v[64:67], s[16:17] offset:2048
	v_cvt_pk_bf16_f32 v72, v72, v73
	v_cvt_pk_bf16_f32 v73, v74, v75
	v_cvt_pk_bf16_f32 v74, v76, v77
	v_cvt_pk_bf16_f32 v75, v78, v79
	global_store_dwordx4 v9, v[72:75], s[16:17] offset:2048
	s_add_u32 s9, s9, s19
	s_cmpk_ge_u32 s9, 0x1600
	s_cbranch_scc1 .Ltc1a_lastB
; __device__ __forceinline__ void tr_load(const float* W, int N, int item, int lane, float (&wv)[32]) {
;     const int nblk = N / 32, kb = item / nblk, nb = item % nblk, k0 = 64 * kb, n0 = 32 * nb;
; #pragma unroll
;     for (int i = 0; i < 32; ++i) { const int kk = 2 * i + (lane >> 5); wv[i] = __builtin_nontemporal_load(W + (size_t)(k0 + kk) * N + n0 + (lane & 31)); }
; }
; template <int MAP, bool HASG, bool PERMW>
; __device__ __forceinline__ void tr_store(int K, int N, bf16_t* WT, LAS float* scr, int item, int lane, const float* gk) {
;     const int nblk = N / 32, kb = item / nblk, nb = item % nblk, k0 = 64 * kb, n0 = 32 * nb;
;     asm volatile("s_waitcnt lgkmcnt(0)" ::: "memory");
;     const int c = lane & 7;
;     f32x4 g0 = {1.f, 1.f, 1.f, 1.f}, g1 = {1.f, 1.f, 1.f, 1.f};
;     if (HASG) { g0 = *(const f32x4*)(gk + k0 + 8 * c); g1 = *(const f32x4*)(gk + k0 + 8 * c + 4); }
; #pragma unroll
;     for (int j = 0; j < 4; ++j) { const int n = (lane >> 3) + 8 * j; const LAS float* s = scr + (8 * c) * 33 + n;
;         u32x4 o; o.x = pk2(s[0 * 33] * g0[0], s[1 * 33] * g0[1]); o.y = pk2(s[2 * 33] * g0[2], s[3 * 33] * g0[3]); o.z = pk2(s[4 * 33] * g1[0], s[5 * 33] * g1[1]); o.w = pk2(s[6 * 33] * g1[2], s[7 * 33] * g1[3]);
;         const int wr_ = rowmap<MAP>(n0 + n), slot_ = PERMW ? ((wr_ & ~31) + invperm32(wr_ & 31)) : wr_;
;         *(u32x4*)((char*)WT + tiled_off(slot_, k0 + 8 * c, K / 64)) = o; }
;     asm volatile("s_waitcnt lgkmcnt(0)" ::: "memory");
; }
; template <int MAP, bool HASG = false, bool PERMW = false>
; __device__ __forceinline__ void transpose_mat(const float* W, int K, int N, bf16_t* WT, LAS float* scr, int gw, int ngw, int lane, const float* gk = nullptr) {
;     const int nitems = (K / 64) * (N / 32);
;     int it = gw;
;     if (it >= nitems) return;
;     float wv[32];
;     tr_load(W, N, it, lane, wv);
;     for (;;) {
;         __builtin_amdgcn_sched_barrier(0);
; #pragma unroll
;         for (int i = 0; i < 32; ++i) { const int kk = 2 * i + (lane >> 5); scr[kk * 33 + (lane & 31)] = wv[i]; }
;         __builtin_amdgcn_sched_barrier(0);
;         const int nx = it + ngw;
;         if (nx < nitems) tr_load(W, N, nx, lane, wv);
;         __builtin_amdgcn_sched_barrier(0);
;         tr_store<MAP, HASG, PERMW>(K, N, WT, scr, it, lane, gk);
;         if (nx >= nitems) break;
;         it = nx;
	s_lshr_b32 s11, s9, 6
	s_and_b32 s12, s9, 63
	s_lshl_b32 s13, s11, 19
	s_lshl_b32 s14, s12, 7
	s_add_u32 s13, s13, s14
	s_add_u32 s14, s4, s13
	s_addc_u32 s15, s5, 0
	global_load_dword v16, v3, s[14:15]
	s_add_u32 s14, s14, 0x4000
	s_addc_u32 s15, s15, 0
	global_load_dword v17, v3, s[14:15]
	s_add_u32 s14, s14, 0x4000
	s_addc_u32 s15, s15, 0
	global_load_dword v18, v3, s[14:15]
	s_add_u32 s14, s14, 0x4000
	s_addc_u32 s15, s15, 0
	global_load_dword v19, v3, s[14:15]
	s_add_u32 s14, s14, 0x4000
	s_addc_u32 s15, s15, 0
	global_load_dword v20, v3, s[14:15]
	s_add_u32 s14, s14, 0x4000
	s_addc_u32 s15, s15, 0
	global_load_dword v21, v3, s[14:15]
	s_add_u32 s14, s14, 0x4000
	s_addc_u32 s15, s15, 0
	global_load_dword v22, v3, s[14:15]
	s_add_u32 s14, s14, 0x4000
	s_addc_u32 s15, s15, 0
	global_load_dword v23, v3, s[14:15]
	s_add_u32 s14, s14, 0x4000
	s_addc_u32 s15, s15, 0
	global_load_dword v24, v3, s[14:15]
	s_add_u32 s14, s14, 0x4000
	s_addc_u32 s15, s15, 0
	global_load_dword v25, v3, s[14:15]
	s_add_u32 s14, s14, 0x4000
	s_addc_u32 s15, s15, 0
	global_load_dword v26, v3, s[14:15]
	s_add_u32 s14, s14, 0x4000
	s_addc_u32 s15, s15, 0
	global_load_dword v27, v3, s[14:15]
	s_add_u32 s14, s14, 0x4000
	s_addc_u32 s15, s15, 0
	global_load_dword v28, v3, s[14:15]
	s_add_u32 s14, s14, 0x4000
	s_addc_u32 s15, s15, 0
	global_load_dword v29, v3, s[14:15]
	s_add_u32 s14, s14, 0x4000
	s_addc_u32 s15, s15, 0
	global_load_dword v30, v3, s[14:15]
	s_add_u32 s14, s14, 0x4000
	s_addc_u32 s15, s15, 0
	global_load_dword v31, v3, s[14:15]
	s_add_u32 s14, s14, 0x4000
	s_addc_u32 s15, s15, 0
	global_load_dword v32, v3, s[14:15]
	s_add_u32 s14, s14, 0x4000
	s_addc_u32 s15, s15, 0
	global_load_dword v33, v3, s[14:15]
	s_add_u32 s14, s14, 0x4000
	s_addc_u32 s15, s15, 0
	global_load_dword v34, v3, s[14:15]
	s_add_u32 s14, s14, 0x4000
	s_addc_u32 s15, s15, 0
	global_load_dword v35, v3, s[14:15]
	s_add_u32 s14, s14, 0x4000
	s_addc_u32 s15, s15, 0
	global_load_dword v36, v3, s[14:15]
	s_add_u32 s14, s14, 0x4000
	s_addc_u32 s15, s15, 0
	global_load_dword v37, v3, s[14:15]
	s_add_u32 s14, s14, 0x4000
	s_addc_u32 s15, s15, 0
	global_load_dword v38, v3, s[14:15]
	s_add_u32 s14, s14, 0x4000
	s_addc_u32 s15, s15, 0
	global_load_dword v39, v3, s[14:15]
	s_add_u32 s14, s14, 0x4000
	s_addc_u32 s15, s15, 0
	global_load_dword v40, v3, s[14:15]
	s_add_u32 s14, s14, 0x4000
	s_addc_u32 s15, s15, 0
	global_load_dword v41, v3, s[14:15]
	s_add_u32 s14, s14, 0x4000
	s_addc_u32 s15, s15, 0
	global_load_dword v42, v3, s[14:15]
	s_add_u32 s14, s14, 0x4000
	s_addc_u32 s15, s15, 0
	global_load_dword v43, v3, s[14:15]
	s_add_u32 s14, s14, 0x4000
	s_addc_u32 s15, s15, 0
	global_load_dword v44, v3, s[14:15]
	s_add_u32 s14, s14, 0x4000
	s_addc_u32 s15, s15, 0
	global_load_dword v45, v3, s[14:15]
	s_add_u32 s14, s14, 0x4000
	s_addc_u32 s15, s15, 0
	global_load_dword v46, v3, s[14:15]
	s_add_u32 s14, s14, 0x4000
	s_addc_u32 s15, s15, 0
	global_load_dword v47, v3, s[14:15]
	s_lshr_b32 s16, s12, 2
	s_mul_i32 s16, s16, 0x58
	s_add_u32 s16, s16, s11
	s_lshl_b32 s16, s16, 14
	s_and_b32 s17, s12, 3
	s_lshl_b32 s17, s17, 12
	s_add_u32 s16, s16, s17
	s_add_u32 s16, s6, s16
	s_addc_u32 s17, s7, 0
	s_waitcnt vmcnt(32)
	ds_write_b32 v4, v88
	ds_write_b32 v4, v89 offset:264
	ds_write_b32 v4, v90 offset:528
	ds_write_b32 v4, v91 offset:792
	ds_write_b32 v4, v92 offset:1056
	ds_write_b32 v4, v93 offset:1320
	ds_write_b32 v4, v94 offset:1584
	ds_write_b32 v4, v95 offset:1848
	ds_write_b32 v4, v96 offset:2112
	ds_write_b32 v4, v97 offset:2376
	ds_write_b32 v4, v98 offset:2640
	ds_write_b32 v4, v99 offset:2904
	ds_write_b32 v4, v100 offset:3168
	ds_write_b32 v4, v101 offset:3432
	ds_write_b32 v4, v102 offset:3696
	ds_write_b32 v4, v103 offset:3960
	ds_write_b32 v4, v104 offset:4224
	ds_write_b32 v4, v105 offset:4488
	ds_write_b32 v4, v106 offset:4752
	ds_write_b32 v4, v107 offset:5016
	ds_write_b32 v4, v108 offset:5280
	ds_write_b32 v4, v109 offset:5544
	ds_write_b32 v4, v110 offset:5808
	ds_write_b32 v4, v111 offset:6072
	ds_write_b32 v4, v112 offset:6336
	ds_write_b32 v4, v113 offset:6600
	ds_write_b32 v4, v114 offset:6864
	ds_write_b32 v4, v115 offset:7128
	ds_write_b32 v4, v116 offset:7392
	ds_write_b32 v4, v117 offset:7656
	ds_write_b32 v4, v118 offset:7920
	ds_write_b32 v4, v119 offset:8184
	s_waitcnt lgkmcnt(0)
	ds_read_b32 v48, v7
	ds_read_b32 v49, v7 offset:132
	ds_read_b32 v50, v7 offset:264
	ds_read_b32 v51, v7 offset:396
	ds_read_b32 v52, v7 offset:528
	ds_read_b32 v53, v7 offset:660
	ds_read_b32 v54, v7 offset:792
	ds_read_b32 v55, v7 offset:924
	ds_read_b32 v56, v7 offset:32
	ds_read_b32 v57, v7 offset:164
	ds_read_b32 v58, v7 offset:296
	ds_read_b32 v59, v7 offset:428
	ds_read_b32 v60, v7 offset:560
	ds_read_b32 v61, v7 offset:692
	ds_read_b32 v62, v7 offset:824
	ds_read_b32 v63, v7 offset:956
	ds_read_b32 v64, v7 offset:64
	ds_read_b32 v65, v7 offset:196
	ds_read_b32 v66, v7 offset:328
	ds_read_b32 v67, v7 offset:460
	ds_read_b32 v68, v7 offset:592
	ds_read_b32 v69, v7 offset:724
	ds_read_b32 v70, v7 offset:856
	ds_read_b32 v71, v7 offset:988
	ds_read_b32 v72, v7 offset:96
	ds_read_b32 v73, v7 offset:228
	ds_read_b32 v74, v7 offset:360
	ds_read_b32 v75, v7 offset:492
	ds_read_b32 v76, v7 offset:624
	ds_read_b32 v77, v7 offset:756
	ds_read_b32 v78, v7 offset:888
	ds_read_b32 v79, v7 offset:1020
	s_waitcnt lgkmcnt(0)
	v_cvt_pk_bf16_f32 v48, v48, v49
	v_cvt_pk_bf16_f32 v49, v50, v51
	v_cvt_pk_bf16_f32 v50, v52, v53
	v_cvt_pk_bf16_f32 v51, v54, v55
	global_store_dwordx4 v8, v[48:51], s[24:25]
	v_cvt_pk_bf16_f32 v56, v56, v57
	v_cvt_pk_bf16_f32 v57, v58, v59
	v_cvt_pk_bf16_f32 v58, v60, v61
	v_cvt_pk_bf16_f32 v59, v62, v63
	global_store_dwordx4 v9, v[56:59], s[24:25]
	v_cvt_pk_bf16_f32 v64, v64, v65
	v_cvt_pk_bf16_f32 v65, v66, v67
	v_cvt_pk_bf16_f32 v66, v68, v69
	v_cvt_pk_bf16_f32 v67, v70, v71
	global_store_dwordx4 v8, v[64:67], s[24:25] offset:2048
	v_cvt_pk_bf16_f32 v72, v72, v73
	v_cvt_pk_bf16_f32 v73, v74, v75
	v_cvt_pk_bf16_f32 v74, v76, v77
	v_cvt_pk_bf16_f32 v75, v78, v79
	global_store_dwordx4 v9, v[72:75], s[24:25] offset:2048
	s_branch .Ltc1a_loop

; #define LAS __attribute__((address_space(3)))
; __device__ __forceinline__ unsigned pk2(float lo, float hi) { f32x2 f = {lo, hi}; bf16x2_t b = __builtin_convertvector(f, bf16x2_t); return __builtin_bit_cast(unsigned, b); }
; __device__ __forceinline__ void tr_load(const float* W, int N, int item, int lane, float (&wv)[32]) {
;     const int nblk = N / 32, kb = item / nblk, nb = item % nblk, k0 = 64 * kb, n0 = 32 * nb;
; #pragma unroll
;     for (int i = 0; i < 32; ++i) { const int kk = 2 * i + (lane >> 5); wv[i] = __builtin_nontemporal_load(W + (size_t)(k0 + kk) * N + n0 + (lane & 31)); }
; }
; template <int MAP, bool HASG, bool PERMW>
; __device__ __forceinline__ void tr_store(int K, int N, bf16_t* WT, LAS float* scr, int item, int lane, const float* gk) {
;     const int nblk = N / 32, kb = item / nblk, nb = item % nblk, k0 = 64 * kb, n0 = 32 * nb;
;     asm volatile("s_waitcnt lgkmcnt(0)" ::: "memory");
;     const int c = lane & 7;
;     f32x4 g0 = {1.f, 1.f, 1.f, 1.f}, g1 = {1.f, 1.f, 1.f, 1.f};
;     if (HASG) { g0 = *(const f32x4*)(gk + k0 + 8 * c); g1 = *(const f32x4*)(gk + k0 + 8 * c + 4); }
; #pragma unroll
;     for (int j = 0; j < 4; ++j) { const int n = (lane >> 3) + 8 * j; const LAS float* s = scr + (8 * c) * 33 + n;
;         u32x4 o; o.x = pk2(s[0 * 33] * g0[0], s[1 * 33] * g0[1]); o.y = pk2(s[2 * 33] * g0[2], s[3 * 33] * g0[3]); o.z = pk2(s[4 * 33] * g1[0], s[5 * 33] * g1[1]); o.w = pk2(s[6 * 33] * g1[2], s[7 * 33] * g1[3]);
;         const int wr_ = rowmap<MAP>(n0 + n), slot_ = PERMW ? ((wr_ & ~31) + invperm32(wr_ & 31)) : wr_;
;         *(u32x4*)((char*)WT + tiled_off(slot_, k0 + 8 * c, K / 64)) = o; }
;     asm volatile("s_waitcnt lgkmcnt(0)" ::: "memory");
; }
; template <int MAP, bool HASG = false, bool PERMW = false>
; __device__ __forceinline__ void transpose_mat(const float* W, int K, int N, bf16_t* WT, LAS float* scr, int gw, int ngw, int lane, const float* gk = nullptr) {
;     const int nitems = (K / 64) * (N / 32);
;     int it = gw;
;     if (it >= nitems) return;
;     float wv[32];
;     tr_load(W, N, it, lane, wv);
; __global__ void __launch_bounds__(512, 2) mega_fwd(Params p) {
;     ...
;             transpose_mat<3, true, true>(p.in[6] + (size_t)l * D * INW, D, INW, P_W(WS_WIN), scr, gw, ngw, lane, p.in[5] + l * D);
.Ltc1a_exit:
	v_readlane_b32 s4, v255, 8
	v_readlane_b32 s5, v255, 9
	v_readlane_b32 s20, v255, 6
	v_readlane_b32 s21, v255, 7
	s_nop 3
	s_and_b32 s6, s60, 0x6800000
	s_add_u32 s4, s4, s6
	s_addc_u32 s5, s5, 0
	s_and_b32 s6, s60, 0x2000
	s_add_u32 s20, s20, s6
	s_addc_u32 s21, s21, 0
	s_add_u32 s6, s76, 0x4200000
	s_addc_u32 s7, s77, 0
	s_mov_b32 s9, s18
	s_cmpk_ge_u32 s9, 0x3400
	s_cbranch_scc1 .Ltc1c_exit
	s_mul_hi_u32 s11, s9, 0x4ec4ec4f
	s_lshr_b32 s11, s11, 7
	s_mul_i32 s12, s11, 0x1a0
	s_sub_u32 s12, s9, s12
	s_mul_i32 s13, s11, 0x340000
	s_lshl_b32 s14, s12, 7
	s_add_u32 s13, s13, s14
	s_add_u32 s14, s4, s13
	s_addc_u32 s15, s5, 0
	global_load_dword v16, v12, s[14:15]
	s_add_u32 s14, s14, 0x1a000
	s_addc_u32 s15, s15, 0
	global_load_dword v17, v12, s[14:15]
	s_add_u32 s14, s14, 0x1a000
	s_addc_u32 s15, s15, 0
	global_load_dword v18, v12, s[14:15]
	s_add_u32 s14, s14, 0x1a000
	s_addc_u32 s15, s15, 0
	global_load_dword v19, v12, s[14:15]
	s_add_u32 s14, s14, 0x1a000
	s_addc_u32 s15, s15, 0
	global_load_dword v20, v12, s[14:15]
	s_add_u32 s14, s14, 0x1a000
	s_addc_u32 s15, s15, 0
	global_load_dword v21, v12, s[14:15]
	s_add_u32 s14, s14, 0x1a000
	s_addc_u32 s15, s15, 0
	global_load_dword v22, v12, s[14:15]
	s_add_u32 s14, s14, 0x1a000
	s_addc_u32 s15, s15, 0
	global_load_dword v23, v12, s[14:15]
	s_add_u32 s14, s14, 0x1a000
	s_addc_u32 s15, s15, 0
	global_load_dword v24, v12, s[14:15]
	s_add_u32 s14, s14, 0x1a000
	s_addc_u32 s15, s15, 0
	global_load_dword v25, v12, s[14:15]
	s_add_u32 s14, s14, 0x1a000
	s_addc_u32 s15, s15, 0
	global_load_dword v26, v12, s[14:15]
	s_add_u32 s14, s14, 0x1a000
	s_addc_u32 s15, s15, 0
	global_load_dword v27, v12, s[14:15]
	s_add_u32 s14, s14, 0x1a000
	s_addc_u32 s15, s15, 0
	global_load_dword v28, v12, s[14:15]
	s_add_u32 s14, s14, 0x1a000
	s_addc_u32 s15, s15, 0
	global_load_dword v29, v12, s[14:15]
	s_add_u32 s14, s14, 0x1a000
	s_addc_u32 s15, s15, 0
	global_load_dword v30, v12, s[14:15]
	s_add_u32 s14, s14, 0x1a000
	s_addc_u32 s15, s15, 0
	global_load_dword v31, v12, s[14:15]
	s_add_u32 s14, s14, 0x1a000
	s_addc_u32 s15, s15, 0
	global_load_dword v32, v12, s[14:15]
	s_add_u32 s14, s14, 0x1a000
	s_addc_u32 s15, s15, 0
	global_load_dword v33, v12, s[14:15]
	s_add_u32 s14, s14, 0x1a000
	s_addc_u32 s15, s15, 0
	global_load_dword v34, v12, s[14:15]
	s_add_u32 s14, s14, 0x1a000
	s_addc_u32 s15, s15, 0
	global_load_dword v35, v12, s[14:15]
	s_add_u32 s14, s14, 0x1a000
	s_addc_u32 s15, s15, 0
	global_load_dword v36, v12, s[14:15]
	s_add_u32 s14, s14, 0x1a000
	s_addc_u32 s15, s15, 0
	global_load_dword v37, v12, s[14:15]
	s_add_u32 s14, s14, 0x1a000
	s_addc_u32 s15, s15, 0
	global_load_dword v38, v12, s[14:15]
	s_add_u32 s14, s14, 0x1a000
	s_addc_u32 s15, s15, 0
	global_load_dword v39, v12, s[14:15]
	s_add_u32 s14, s14, 0x1a000
	s_addc_u32 s15, s15, 0
	global_load_dword v40, v12, s[14:15]
	s_add_u32 s14, s14, 0x1a000
	s_addc_u32 s15, s15, 0
	global_load_dword v41, v12, s[14:15]
	s_add_u32 s14, s14, 0x1a000
	s_addc_u32 s15, s15, 0
	global_load_dword v42, v12, s[14:15]
	s_add_u32 s14, s14, 0x1a000
	s_addc_u32 s15, s15, 0
	global_load_dword v43, v12, s[14:15]
	s_add_u32 s14, s14, 0x1a000
	s_addc_u32 s15, s15, 0
	global_load_dword v44, v12, s[14:15]
	s_add_u32 s14, s14, 0x1a000
	s_addc_u32 s15, s15, 0
	global_load_dword v45, v12, s[14:15]
	s_add_u32 s14, s14, 0x1a000
	s_addc_u32 s15, s15, 0
	global_load_dword v46, v12, s[14:15]
	s_add_u32 s14, s14, 0x1a000
	s_addc_u32 s15, s15, 0
	global_load_dword v47, v12, s[14:15]
	s_lshl_b32 s14, s11, 8
	s_add_u32 s14, s20, s14
	s_addc_u32 s15, s21, 0
	global_load_dwordx4 v[80:83], v14, s[14:15]
	global_load_dwordx4 v[84:87], v14, s[14:15] offset:16
	s_sub_u32 s13, s12, 0x60
	s_cmp_lt_u32 s13, 0x40
	s_cselect_b32 s28, 1, 0
	s_cmp_lt_u32 s12, 0x40
	s_cselect_b32 s13, 1, 0
	s_or_b32 s28, s28, s13
	s_lshr_b32 s16, s12, 2
	s_lshl_b32 s16, s16, 5
	s_add_u32 s16, s16, s11
	s_lshl_b32 s16, s16, 14
	s_and_b32 s13, s12, 1
	s_lshl_b32 s13, s13, 13
	s_bfe_u32 s14, s12, 0x10001
	s_lshl_b32 s14, s14, 11
	s_add_u32 s13, s13, s14
	s_and_b32 s14, s12, 3
	s_lshl_b32 s14, s14, 12
	s_cmp_lg_u32 s28, 0
	s_cselect_b32 s13, s13, s14
	s_add_u32 s16, s16, s13
	s_add_u32 s16, s6, s16
	s_addc_u32 s17, s7, 0
	s_add_u32 s22, s16, 0x1000
	s_addc_u32 s23, s17, 0
; #define LAS __attribute__((address_space(3)))
; __device__ __forceinline__ unsigned pk2(float lo, float hi) { f32x2 f = {lo, hi}; bf16x2_t b = __builtin_convertvector(f, bf16x2_t); return __builtin_bit_cast(unsigned, b); }
; template <int MAP> __device__ __forceinline__ int rowmap(int n) {
;     if (MAP == 1) return (n >> 7) * 256 + (n & 127);
;     if (MAP == 2) return (n >> 7) * 256 + 128 + (n & 127);
;     if (MAP == 3) {
;         const bool rot = (n < 2048) || (n >= 3072 && n < 5120);
;         if (!rot) return n;
;         const int c = n & 127, i = c & 63, half = c >> 6;
;         return (n & ~127) + 32 * (i >> 4) + 8 * ((i >> 2) & 3) + 4 * half + (i & 3);
;     }
;     return n;
; }
; __device__ __forceinline__ void tr_load(const float* W, int N, int item, int lane, float (&wv)[32]) {
;     const int nblk = N / 32, kb = item / nblk, nb = item % nblk, k0 = 64 * kb, n0 = 32 * nb;
; #pragma unroll
;     for (int i = 0; i < 32; ++i) { const int kk = 2 * i + (lane >> 5); wv[i] = __builtin_nontemporal_load(W + (size_t)(k0 + kk) * N + n0 + (lane & 31)); }
; }
; template <int MAP, bool HASG, bool PERMW>
; __device__ __forceinline__ void tr_store(int K, int N, bf16_t* WT, LAS float* scr, int item, int lane, const float* gk) {
;     const int nblk = N / 32, kb = item / nblk, nb = item % nblk, k0 = 64 * kb, n0 = 32 * nb;
;     asm volatile("s_waitcnt lgkmcnt(0)" ::: "memory");
;     const int c = lane & 7;
;     f32x4 g0 = {1.f, 1.f, 1.f, 1.f}, g1 = {1.f, 1.f, 1.f, 1.f};
;     if (HASG) { g0 = *(const f32x4*)(gk + k0 + 8 * c); g1 = *(const f32x4*)(gk + k0 + 8 * c + 4); }
; #pragma unroll
;     for (int j = 0; j < 4; ++j) { const int n = (lane >> 3) + 8 * j; const LAS float* s = scr + (8 * c) * 33 + n;
;         u32x4 o; o.x = pk2(s[0 * 33] * g0[0], s[1 * 33] * g0[1]); o.y = pk2(s[2 * 33] * g0[2], s[3 * 33] * g0[3]); o.z = pk2(s[4 * 33] * g1[0], s[5 * 33] * g1[1]); o.w = pk2(s[6 * 33] * g1[2], s[7 * 33] * g1[3]);
;         const int wr_ = rowmap<MAP>(n0 + n), slot_ = PERMW ? ((wr_ & ~31) + invperm32(wr_ & 31)) : wr_;
;         *(u32x4*)((char*)WT + tiled_off(slot_, k0 + 8 * c, K / 64)) = o; }
.Ltc1c_loop:
	s_add_u32 s9, s9, s19
	s_cmpk_ge_u32 s9, 0x3400
	s_cbranch_scc1 .Ltc1c_lastA
	s_mul_hi_u32 s11, s9, 0x4ec4ec4f
	s_lshr_b32 s11, s11, 7
	s_mul_i32 s12, s11, 0x1a0
	s_sub_u32 s12, s9, s12
	s_mul_i32 s13, s11, 0x340000
	s_lshl_b32 s14, s12, 7
	s_add_u32 s13, s13, s14
	s_add_u32 s14, s4, s13
	s_addc_u32 s15, s5, 0
	global_load_dword v88, v12, s[14:15]
	s_add_u32 s14, s14, 0x1a000
	s_addc_u32 s15, s15, 0
	global_load_dword v89, v12, s[14:15]
	s_add_u32 s14, s14, 0x1a000
	s_addc_u32 s15, s15, 0
	global_load_dword v90, v12, s[14:15]
	s_add_u32 s14, s14, 0x1a000
	s_addc_u32 s15, s15, 0
	global_load_dword v91, v12, s[14:15]
	s_add_u32 s14, s14, 0x1a000
	s_addc_u32 s15, s15, 0
	global_load_dword v92, v12, s[14:15]
	s_add_u32 s14, s14, 0x1a000
	s_addc_u32 s15, s15, 0
	global_load_dword v93, v12, s[14:15]
	s_add_u32 s14, s14, 0x1a000
	s_addc_u32 s15, s15, 0
	global_load_dword v94, v12, s[14:15]
	s_add_u32 s14, s14, 0x1a000
	s_addc_u32 s15, s15, 0
	global_load_dword v95, v12, s[14:15]
	s_add_u32 s14, s14, 0x1a000
	s_addc_u32 s15, s15, 0
	global_load_dword v96, v12, s[14:15]
	s_add_u32 s14, s14, 0x1a000
	s_addc_u32 s15, s15, 0
	global_load_dword v97, v12, s[14:15]
	s_add_u32 s14, s14, 0x1a000
	s_addc_u32 s15, s15, 0
	global_load_dword v98, v12, s[14:15]
	s_add_u32 s14, s14, 0x1a000
	s_addc_u32 s15, s15, 0
	global_load_dword v99, v12, s[14:15]
	s_add_u32 s14, s14, 0x1a000
	s_addc_u32 s15, s15, 0
	global_load_dword v100, v12, s[14:15]
	s_add_u32 s14, s14, 0x1a000
	s_addc_u32 s15, s15, 0
	global_load_dword v101, v12, s[14:15]
	s_add_u32 s14, s14, 0x1a000
	s_addc_u32 s15, s15, 0
	global_load_dword v102, v12, s[14:15]
	s_add_u32 s14, s14, 0x1a000
	s_addc_u32 s15, s15, 0
	global_load_dword v103, v12, s[14:15]
	s_add_u32 s14, s14, 0x1a000
	s_addc_u32 s15, s15, 0
	global_load_dword v104, v12, s[14:15]
	s_add_u32 s14, s14, 0x1a000
	s_addc_u32 s15, s15, 0
	global_load_dword v105, v12, s[14:15]
	s_add_u32 s14, s14, 0x1a000
	s_addc_u32 s15, s15, 0
	global_load_dword v106, v12, s[14:15]
	s_add_u32 s14, s14, 0x1a000
	s_addc_u32 s15, s15, 0
	global_load_dword v107, v12, s[14:15]
	s_add_u32 s14, s14, 0x1a000
	s_addc_u32 s15, s15, 0
	global_load_dword v108, v12, s[14:15]
	s_add_u32 s14, s14, 0x1a000
	s_addc_u32 s15, s15, 0
	global_load_dword v109, v12, s[14:15]
	s_add_u32 s14, s14, 0x1a000
	s_addc_u32 s15, s15, 0
	global_load_dword v110, v12, s[14:15]
	s_add_u32 s14, s14, 0x1a000
	s_addc_u32 s15, s15, 0
	global_load_dword v111, v12, s[14:15]
	s_add_u32 s14, s14, 0x1a000
	s_addc_u32 s15, s15, 0
	global_load_dword v112, v12, s[14:15]
	s_add_u32 s14, s14, 0x1a000
	s_addc_u32 s15, s15, 0
	global_load_dword v113, v12, s[14:15]
	s_add_u32 s14, s14, 0x1a000
	s_addc_u32 s15, s15, 0
	global_load_dword v114, v12, s[14:15]
	s_add_u32 s14, s14, 0x1a000
	s_addc_u32 s15, s15, 0
	global_load_dword v115, v12, s[14:15]
	s_add_u32 s14, s14, 0x1a000
	s_addc_u32 s15, s15, 0
	global_load_dword v116, v12, s[14:15]
	s_add_u32 s14, s14, 0x1a000
	s_addc_u32 s15, s15, 0
	global_load_dword v117, v12, s[14:15]
	s_add_u32 s14, s14, 0x1a000
	s_addc_u32 s15, s15, 0
	global_load_dword v118, v12, s[14:15]
	s_add_u32 s14, s14, 0x1a000
	s_addc_u32 s15, s15, 0
	global_load_dword v119, v12, s[14:15]
	s_lshl_b32 s14, s11, 8
	s_add_u32 s14, s20, s14
	s_addc_u32 s15, s21, 0
	global_load_dwordx4 v[120:123], v14, s[14:15]
	global_load_dwordx4 v[124:127], v14, s[14:15] offset:16
	s_sub_u32 s13, s12, 0x60
	s_cmp_lt_u32 s13, 0x40
	s_cselect_b32 s29, 1, 0
	s_cmp_lt_u32 s12, 0x40
	s_cselect_b32 s13, 1, 0
	s_or_b32 s29, s29, s13
	s_lshr_b32 s24, s12, 2
	s_lshl_b32 s24, s24, 5
	s_add_u32 s24, s24, s11
	s_lshl_b32 s24, s24, 14
	s_and_b32 s13, s12, 1
	s_lshl_b32 s13, s13, 13
	s_bfe_u32 s14, s12, 0x10001
	s_lshl_b32 s14, s14, 11
	s_add_u32 s13, s13, s14
	s_and_b32 s14, s12, 3
	s_lshl_b32 s14, s14, 12
	s_cmp_lg_u32 s29, 0
	s_cselect_b32 s13, s13, s14
	s_add_u32 s24, s24, s13
	s_add_u32 s24, s6, s24
	s_addc_u32 s25, s7, 0
	s_add_u32 s26, s24, 0x1000
	s_addc_u32 s27, s25, 0
	s_waitcnt vmcnt(34)
; #define LAS __attribute__((address_space(3)))
; __device__ __forceinline__ unsigned pk2(float lo, float hi) { f32x2 f = {lo, hi}; bf16x2_t b = __builtin_convertvector(f, bf16x2_t); return __builtin_bit_cast(unsigned, b); }
; template <int MAP, bool HASG, bool PERMW>
; __device__ __forceinline__ void tr_store(int K, int N, bf16_t* WT, LAS float* scr, int item, int lane, const float* gk) {
;     const int nblk = N / 32, kb = item / nblk, nb = item % nblk, k0 = 64 * kb, n0 = 32 * nb;
;     asm volatile("s_waitcnt lgkmcnt(0)" ::: "memory");
;     const int c = lane & 7;
;     f32x4 g0 = {1.f, 1.f, 1.f, 1.f}, g1 = {1.f, 1.f, 1.f, 1.f};
;     if (HASG) { g0 = *(const f32x4*)(gk + k0 + 8 * c); g1 = *(const f32x4*)(gk + k0 + 8 * c + 4); }
; #pragma unroll
;     for (int j = 0; j < 4; ++j) { const int n = (lane >> 3) + 8 * j; const LAS float* s = scr + (8 * c) * 33 + n;
;         u32x4 o; o.x = pk2(s[0 * 33] * g0[0], s[1 * 33] * g0[1]); o.y = pk2(s[2 * 33] * g0[2], s[3 * 33] * g0[3]); o.z = pk2(s[4 * 33] * g1[0], s[5 * 33] * g1[1]); o.w = pk2(s[6 * 33] * g1[2], s[7 * 33] * g1[3]);
;         const int wr_ = rowmap<MAP>(n0 + n), slot_ = PERMW ? ((wr_ & ~31) + invperm32(wr_ & 31)) : wr_;
;         *(u32x4*)((char*)WT + tiled_off(slot_, k0 + 8 * c, K / 64)) = o; }
;     asm volatile("s_waitcnt lgkmcnt(0)" ::: "memory");
; }
; template <int MAP, bool HASG = false, bool PERMW = false>
; __device__ __forceinline__ void transpose_mat(const float* W, int K, int N, bf16_t* WT, LAS float* scr, int gw, int ngw, int lane, const float* gk = nullptr) {
;     ...
;         for (int i = 0; i < 32; ++i) { const int kk = 2 * i + (lane >> 5); scr[kk * 33 + (lane & 31)] = wv[i]; }
	ds_write_b32 v4, v16
	ds_write_b32 v4, v17 offset:264
	ds_write_b32 v4, v18 offset:528
	ds_write_b32 v4, v19 offset:792
	ds_write_b32 v4, v20 offset:1056
	ds_write_b32 v4, v21 offset:1320
	ds_write_b32 v4, v22 offset:1584
	ds_write_b32 v4, v23 offset:1848
	ds_write_b32 v4, v24 offset:2112
	ds_write_b32 v4, v25 offset:2376
	ds_write_b32 v4, v26 offset:2640
	ds_write_b32 v4, v27 offset:2904
	ds_write_b32 v4, v28 offset:3168
	ds_write_b32 v4, v29 offset:3432
	ds_write_b32 v4, v30 offset:3696
	ds_write_b32 v4, v31 offset:3960
	ds_write_b32 v4, v32 offset:4224
	ds_write_b32 v4, v33 offset:4488
	ds_write_b32 v4, v34 offset:4752
	ds_write_b32 v4, v35 offset:5016
	ds_write_b32 v4, v36 offset:5280
	ds_write_b32 v4, v37 offset:5544
	ds_write_b32 v4, v38 offset:5808
	ds_write_b32 v4, v39 offset:6072
	ds_write_b32 v4, v40 offset:6336
	ds_write_b32 v4, v41 offset:6600
	ds_write_b32 v4, v42 offset:6864
	ds_write_b32 v4, v43 offset:7128
	ds_write_b32 v4, v44 offset:7392
	ds_write_b32 v4, v45 offset:7656
	ds_write_b32 v4, v46 offset:7920
	ds_write_b32 v4, v47 offset:8184
	s_waitcnt lgkmcnt(0)
	ds_read_b32 v48, v7
	ds_read_b32 v49, v7 offset:132
	ds_read_b32 v50, v7 offset:264
	ds_read_b32 v51, v7 offset:396
	ds_read_b32 v52, v7 offset:528
	ds_read_b32 v53, v7 offset:660
	ds_read_b32 v54, v7 offset:792
	ds_read_b32 v55, v7 offset:924
	ds_read_b32 v56, v7 offset:32
	ds_read_b32 v57, v7 offset:164
	ds_read_b32 v58, v7 offset:296
	ds_read_b32 v59, v7 offset:428
	ds_read_b32 v60, v7 offset:560
	ds_read_b32 v61, v7 offset:692
	ds_read_b32 v62, v7 offset:824
	ds_read_b32 v63, v7 offset:956
	ds_read_b32 v64, v7 offset:64
	ds_read_b32 v65, v7 offset:196
	ds_read_b32 v66, v7 offset:328
	ds_read_b32 v67, v7 offset:460
	ds_read_b32 v68, v7 offset:592
	ds_read_b32 v69, v7 offset:724
	ds_read_b32 v70, v7 offset:856
	ds_read_b32 v71, v7 offset:988
	ds_read_b32 v72, v7 offset:96
	ds_read_b32 v73, v7 offset:228
	ds_read_b32 v74, v7 offset:360
	ds_read_b32 v75, v7 offset:492
	ds_read_b32 v76, v7 offset:624
	ds_read_b32 v77, v7 offset:756
	ds_read_b32 v78, v7 offset:888
	ds_read_b32 v79, v7 offset:1020
	s_waitcnt lgkmcnt(0)
	v_mul_f32_e32 v48, v48, v80
	v_mul_f32_e32 v49, v49, v81
	v_mul_f32_e32 v50, v50, v82
	v_mul_f32_e32 v51, v51, v83
	v_mul_f32_e32 v52, v52, v84
	v_mul_f32_e32 v53, v53, v85
	v_mul_f32_e32 v54, v54, v86
	v_mul_f32_e32 v55, v55, v87
	v_cvt_pk_bf16_f32 v48, v48, v49
	v_cvt_pk_bf16_f32 v49, v50, v51
	v_cvt_pk_bf16_f32 v50, v52, v53
	v_cvt_pk_bf16_f32 v51, v54, v55
	v_mul_f32_e32 v56, v56, v80
	v_mul_f32_e32 v57, v57, v81
	v_mul_f32_e32 v58, v58, v82
	v_mul_f32_e32 v59, v59, v83
	v_mul_f32_e32 v60, v60, v84
	v_mul_f32_e32 v61, v61, v85
	v_mul_f32_e32 v62, v62, v86
	v_mul_f32_e32 v63, v63, v87
	v_cvt_pk_bf16_f32 v56, v56, v57
	v_cvt_pk_bf16_f32 v57, v58, v59
	v_cvt_pk_bf16_f32 v58, v60, v61
	v_cvt_pk_bf16_f32 v59, v62, v63
	v_mul_f32_e32 v64, v64, v80
	v_mul_f32_e32 v65, v65, v81
	v_mul_f32_e32 v66, v66, v82
	v_mul_f32_e32 v67, v67, v83
	v_mul_f32_e32 v68, v68, v84
	v_mul_f32_e32 v69, v69, v85
	v_mul_f32_e32 v70, v70, v86
	v_mul_f32_e32 v71, v71, v87
	v_cvt_pk_bf16_f32 v64, v64, v65
	v_cvt_pk_bf16_f32 v65, v66, v67
	v_cvt_pk_bf16_f32 v66, v68, v69
	v_cvt_pk_bf16_f32 v67, v70, v71
	v_mul_f32_e32 v72, v72, v80
	v_mul_f32_e32 v73, v73, v81
	v_mul_f32_e32 v74, v74, v82
	v_mul_f32_e32 v75, v75, v83
	v_mul_f32_e32 v76, v76, v84
	v_mul_f32_e32 v77, v77, v85
	v_mul_f32_e32 v78, v78, v86
	v_mul_f32_e32 v79, v79, v87
	v_cvt_pk_bf16_f32 v72, v72, v73
	v_cvt_pk_bf16_f32 v73, v74, v75
	v_cvt_pk_bf16_f32 v74, v76, v77
	v_cvt_pk_bf16_f32 v75, v78, v79
	s_cmp_lg_u32 s28, 0
	s_cbranch_scc1 .Ltcw1_rot
	global_store_dwordx4 v10, v[48:51], s[16:17]
	global_store_dwordx4 v10, v[56:59], s[16:17] offset:256
	global_store_dwordx4 v11, v[64:67], s[16:17] offset:512
	global_store_dwordx4 v11, v[72:75], s[16:17] offset:768
	s_branch .Ltcw1_done

; #define LAS __attribute__((address_space(3)))
; __device__ __forceinline__ unsigned pk2(float lo, float hi) { f32x2 f = {lo, hi}; bf16x2_t b = __builtin_convertvector(f, bf16x2_t); return __builtin_bit_cast(unsigned, b); }
; template <int MAP> __device__ __forceinline__ int rowmap(int n) {
;     if (MAP == 1) return (n >> 7) * 256 + (n & 127);
;     if (MAP == 2) return (n >> 7) * 256 + 128 + (n & 127);
;     if (MAP == 3) {
;         const bool rot = (n < 2048) || (n >= 3072 && n < 5120);
;         if (!rot) return n;
;         const int c = n & 127, i = c & 63, half = c >> 6;
;         return (n & ~127) + 32 * (i >> 4) + 8 * ((i >> 2) & 3) + 4 * half + (i & 3);
;     }
;     return n;
; }
; __device__ __forceinline__ void tr_load(const float* W, int N, int item, int lane, float (&wv)[32]) {
;     const int nblk = N / 32, kb = item / nblk, nb = item % nblk, k0 = 64 * kb, n0 = 32 * nb;
; #pragma unroll
;     for (int i = 0; i < 32; ++i) { const int kk = 2 * i + (lane >> 5); wv[i] = __builtin_nontemporal_load(W + (size_t)(k0 + kk) * N + n0 + (lane & 31)); }
; }
; template <int MAP, bool HASG, bool PERMW>
; __device__ __forceinline__ void tr_store(int K, int N, bf16_t* WT, LAS float* scr, int item, int lane, const float* gk) {
;     const int nblk = N / 32, kb = item / nblk, nb = item % nblk, k0 = 64 * kb, n0 = 32 * nb;
;     asm volatile("s_waitcnt lgkmcnt(0)" ::: "memory");
;     const int c = lane & 7;
;     f32x4 g0 = {1.f, 1.f, 1.f, 1.f}, g1 = {1.f, 1.f, 1.f, 1.f};
;     if (HASG) { g0 = *(const f32x4*)(gk + k0 + 8 * c); g1 = *(const f32x4*)(gk + k0 + 8 * c + 4); }
; #pragma unroll
;     for (int j = 0; j < 4; ++j) { const int n = (lane >> 3) + 8 * j; const LAS float* s = scr + (8 * c) * 33 + n;
;         u32x4 o; o.x = pk2(s[0 * 33] * g0[0], s[1 * 33] * g0[1]); o.y = pk2(s[2 * 33] * g0[2], s[3 * 33] * g0[3]); o.z = pk2(s[4 * 33] * g1[0], s[5 * 33] * g1[1]); o.w = pk2(s[6 * 33] * g1[2], s[7 * 33] * g1[3]);
;         const int wr_ = rowmap<MAP>(n0 + n), slot_ = PERMW ? ((wr_ & ~31) + invperm32(wr_ & 31)) : wr_;
;         *(u32x4*)((char*)WT + tiled_off(slot_, k0 + 8 * c, K / 64)) = o; }
.Ltcw1_done:
	s_add_u32 s9, s9, s19
	s_cmpk_ge_u32 s9, 0x3400
	s_cbranch_scc1 .Ltc1c_lastB
	s_mul_hi_u32 s11, s9, 0x4ec4ec4f
	s_lshr_b32 s11, s11, 7
	s_mul_i32 s12, s11, 0x1a0
	s_sub_u32 s12, s9, s12
	s_mul_i32 s13, s11, 0x340000
	s_lshl_b32 s14, s12, 7
	s_add_u32 s13, s13, s14
	s_add_u32 s14, s4, s13
	s_addc_u32 s15, s5, 0
	global_load_dword v16, v12, s[14:15]
	s_add_u32 s14, s14, 0x1a000
	s_addc_u32 s15, s15, 0
	global_load_dword v17, v12, s[14:15]
	s_add_u32 s14, s14, 0x1a000
	s_addc_u32 s15, s15, 0
	global_load_dword v18, v12, s[14:15]
	s_add_u32 s14, s14, 0x1a000
	s_addc_u32 s15, s15, 0
	global_load_dword v19, v12, s[14:15]
	s_add_u32 s14, s14, 0x1a000
	s_addc_u32 s15, s15, 0
	global_load_dword v20, v12, s[14:15]
	s_add_u32 s14, s14, 0x1a000
	s_addc_u32 s15, s15, 0
	global_load_dword v21, v12, s[14:15]
	s_add_u32 s14, s14, 0x1a000
	s_addc_u32 s15, s15, 0
	global_load_dword v22, v12, s[14:15]
	s_add_u32 s14, s14, 0x1a000
	s_addc_u32 s15, s15, 0
	global_load_dword v23, v12, s[14:15]
	s_add_u32 s14, s14, 0x1a000
	s_addc_u32 s15, s15, 0
	global_load_dword v24, v12, s[14:15]
	s_add_u32 s14, s14, 0x1a000
	s_addc_u32 s15, s15, 0
	global_load_dword v25, v12, s[14:15]
	s_add_u32 s14, s14, 0x1a000
	s_addc_u32 s15, s15, 0
	global_load_dword v26, v12, s[14:15]
	s_add_u32 s14, s14, 0x1a000
	s_addc_u32 s15, s15, 0
	global_load_dword v27, v12, s[14:15]
	s_add_u32 s14, s14, 0x1a000
	s_addc_u32 s15, s15, 0
	global_load_dword v28, v12, s[14:15]
	s_add_u32 s14, s14, 0x1a000
	s_addc_u32 s15, s15, 0
	global_load_dword v29, v12, s[14:15]
	s_add_u32 s14, s14, 0x1a000
	s_addc_u32 s15, s15, 0
	global_load_dword v30, v12, s[14:15]
	s_add_u32 s14, s14, 0x1a000
	s_addc_u32 s15, s15, 0
	global_load_dword v31, v12, s[14:15]
	s_add_u32 s14, s14, 0x1a000
	s_addc_u32 s15, s15, 0
	global_load_dword v32, v12, s[14:15]
	s_add_u32 s14, s14, 0x1a000
	s_addc_u32 s15, s15, 0
	global_load_dword v33, v12, s[14:15]
	s_add_u32 s14, s14, 0x1a000
	s_addc_u32 s15, s15, 0
	global_load_dword v34, v12, s[14:15]
	s_add_u32 s14, s14, 0x1a000
	s_addc_u32 s15, s15, 0
	global_load_dword v35, v12, s[14:15]
	s_add_u32 s14, s14, 0x1a000
	s_addc_u32 s15, s15, 0
	global_load_dword v36, v12, s[14:15]
	s_add_u32 s14, s14, 0x1a000
	s_addc_u32 s15, s15, 0
	global_load_dword v37, v12, s[14:15]
	s_add_u32 s14, s14, 0x1a000
	s_addc_u32 s15, s15, 0
	global_load_dword v38, v12, s[14:15]
	s_add_u32 s14, s14, 0x1a000
	s_addc_u32 s15, s15, 0
	global_load_dword v39, v12, s[14:15]
	s_add_u32 s14, s14, 0x1a000
	s_addc_u32 s15, s15, 0
	global_load_dword v40, v12, s[14:15]
	s_add_u32 s14, s14, 0x1a000
	s_addc_u32 s15, s15, 0
	global_load_dword v41, v12, s[14:15]
	s_add_u32 s14, s14, 0x1a000
	s_addc_u32 s15, s15, 0
	global_load_dword v42, v12, s[14:15]
	s_add_u32 s14, s14, 0x1a000
	s_addc_u32 s15, s15, 0
	global_load_dword v43, v12, s[14:15]
	s_add_u32 s14, s14, 0x1a000
	s_addc_u32 s15, s15, 0
	global_load_dword v44, v12, s[14:15]
	s_add_u32 s14, s14, 0x1a000
	s_addc_u32 s15, s15, 0
	global_load_dword v45, v12, s[14:15]
	s_add_u32 s14, s14, 0x1a000
	s_addc_u32 s15, s15, 0
	global_load_dword v46, v12, s[14:15]
	s_add_u32 s14, s14, 0x1a000
	s_addc_u32 s15, s15, 0
	global_load_dword v47, v12, s[14:15]
	s_lshl_b32 s14, s11, 8
	s_add_u32 s14, s20, s14
	s_addc_u32 s15, s21, 0
	global_load_dwordx4 v[80:83], v14, s[14:15]
	global_load_dwordx4 v[84:87], v14, s[14:15] offset:16
	s_sub_u32 s13, s12, 0x60
	s_cmp_lt_u32 s13, 0x40
	s_cselect_b32 s28, 1, 0
	s_cmp_lt_u32 s12, 0x40
	s_cselect_b32 s13, 1, 0
	s_or_b32 s28, s28, s13
	s_lshr_b32 s16, s12, 2
	s_lshl_b32 s16, s16, 5
	s_add_u32 s16, s16, s11
	s_lshl_b32 s16, s16, 14
	s_and_b32 s13, s12, 1
	s_lshl_b32 s13, s13, 13
	s_bfe_u32 s14, s12, 0x10001
	s_lshl_b32 s14, s14, 11
	s_add_u32 s13, s13, s14
	s_and_b32 s14, s12, 3
	s_lshl_b32 s14, s14, 12
	s_cmp_lg_u32 s28, 0
	s_cselect_b32 s13, s13, s14
	s_add_u32 s16, s16, s13
	s_add_u32 s16, s6, s16
	s_addc_u32 s17, s7, 0
	s_add_u32 s22, s16, 0x1000
	s_addc_u32 s23, s17, 0
	s_waitcnt vmcnt(34)
; #define LAS __attribute__((address_space(3)))
; __device__ __forceinline__ unsigned pk2(float lo, float hi) { f32x2 f = {lo, hi}; bf16x2_t b = __builtin_convertvector(f, bf16x2_t); return __builtin_bit_cast(unsigned, b); }
; template <int MAP, bool HASG, bool PERMW>
; __device__ __forceinline__ void tr_store(int K, int N, bf16_t* WT, LAS float* scr, int item, int lane, const float* gk) {
;     const int nblk = N / 32, kb = item / nblk, nb = item % nblk, k0 = 64 * kb, n0 = 32 * nb;
;     asm volatile("s_waitcnt lgkmcnt(0)" ::: "memory");
;     const int c = lane & 7;
;     f32x4 g0 = {1.f, 1.f, 1.f, 1.f}, g1 = {1.f, 1.f, 1.f, 1.f};
;     if (HASG) { g0 = *(const f32x4*)(gk + k0 + 8 * c); g1 = *(const f32x4*)(gk + k0 + 8 * c + 4); }
; #pragma unroll
;     for (int j = 0; j < 4; ++j) { const int n = (lane >> 3) + 8 * j; const LAS float* s = scr + (8 * c) * 33 + n;
;         u32x4 o; o.x = pk2(s[0 * 33] * g0[0], s[1 * 33] * g0[1]); o.y = pk2(s[2 * 33] * g0[2], s[3 * 33] * g0[3]); o.z = pk2(s[4 * 33] * g1[0], s[5 * 33] * g1[1]); o.w = pk2(s[6 * 33] * g1[2], s[7 * 33] * g1[3]);
;         const int wr_ = rowmap<MAP>(n0 + n), slot_ = PERMW ? ((wr_ & ~31) + invperm32(wr_ & 31)) : wr_;
;         *(u32x4*)((char*)WT + tiled_off(slot_, k0 + 8 * c, K / 64)) = o; }
;     asm volatile("s_waitcnt lgkmcnt(0)" ::: "memory");
; }
; template <int MAP, bool HASG = false, bool PERMW = false>
; __device__ __forceinline__ void transpose_mat(const float* W, int K, int N, bf16_t* WT, LAS float* scr, int gw, int ngw, int lane, const float* gk = nullptr) {
;     ...
;         for (int i = 0; i < 32; ++i) { const int kk = 2 * i + (lane >> 5); scr[kk * 33 + (lane & 31)] = wv[i]; }
	ds_write_b32 v4, v88
	ds_write_b32 v4, v89 offset:264
	ds_write_b32 v4, v90 offset:528
	ds_write_b32 v4, v91 offset:792
	ds_write_b32 v4, v92 offset:1056
	ds_write_b32 v4, v93 offset:1320
	ds_write_b32 v4, v94 offset:1584
	ds_write_b32 v4, v95 offset:1848
	ds_write_b32 v4, v96 offset:2112
	ds_write_b32 v4, v97 offset:2376
	ds_write_b32 v4, v98 offset:2640
	ds_write_b32 v4, v99 offset:2904
	ds_write_b32 v4, v100 offset:3168
	ds_write_b32 v4, v101 offset:3432
	ds_write_b32 v4, v102 offset:3696
	ds_write_b32 v4, v103 offset:3960
	ds_write_b32 v4, v104 offset:4224
	ds_write_b32 v4, v105 offset:4488
	ds_write_b32 v4, v106 offset:4752
	ds_write_b32 v4, v107 offset:5016
	ds_write_b32 v4, v108 offset:5280
	ds_write_b32 v4, v109 offset:5544
	ds_write_b32 v4, v110 offset:5808
	ds_write_b32 v4, v111 offset:6072
	ds_write_b32 v4, v112 offset:6336
	ds_write_b32 v4, v113 offset:6600
	ds_write_b32 v4, v114 offset:6864
	ds_write_b32 v4, v115 offset:7128
	ds_write_b32 v4, v116 offset:7392
	ds_write_b32 v4, v117 offset:7656
	ds_write_b32 v4, v118 offset:7920
	ds_write_b32 v4, v119 offset:8184
	s_waitcnt lgkmcnt(0)
	ds_read_b32 v48, v7
	ds_read_b32 v49, v7 offset:132
	ds_read_b32 v50, v7 offset:264
	ds_read_b32 v51, v7 offset:396
	ds_read_b32 v52, v7 offset:528
	ds_read_b32 v53, v7 offset:660
	ds_read_b32 v54, v7 offset:792
	ds_read_b32 v55, v7 offset:924
	ds_read_b32 v56, v7 offset:32
	ds_read_b32 v57, v7 offset:164
	ds_read_b32 v58, v7 offset:296
	ds_read_b32 v59, v7 offset:428
	ds_read_b32 v60, v7 offset:560
	ds_read_b32 v61, v7 offset:692
	ds_read_b32 v62, v7 offset:824
	ds_read_b32 v63, v7 offset:956
	ds_read_b32 v64, v7 offset:64
	ds_read_b32 v65, v7 offset:196
	ds_read_b32 v66, v7 offset:328
	ds_read_b32 v67, v7 offset:460
	ds_read_b32 v68, v7 offset:592
	ds_read_b32 v69, v7 offset:724
	ds_read_b32 v70, v7 offset:856
	ds_read_b32 v71, v7 offset:988
	ds_read_b32 v72, v7 offset:96
	ds_read_b32 v73, v7 offset:228
	ds_read_b32 v74, v7 offset:360
	ds_read_b32 v75, v7 offset:492
	ds_read_b32 v76, v7 offset:624
	ds_read_b32 v77, v7 offset:756
	ds_read_b32 v78, v7 offset:888
	ds_read_b32 v79, v7 offset:1020
	s_waitcnt lgkmcnt(0)
	v_mul_f32_e32 v48, v48, v120
	v_mul_f32_e32 v49, v49, v121
	v_mul_f32_e32 v50, v50, v122
	v_mul_f32_e32 v51, v51, v123
	v_mul_f32_e32 v52, v52, v124
	v_mul_f32_e32 v53, v53, v125
	v_mul_f32_e32 v54, v54, v126
	v_mul_f32_e32 v55, v55, v127
	v_cvt_pk_bf16_f32 v48, v48, v49
	v_cvt_pk_bf16_f32 v49, v50, v51
	v_cvt_pk_bf16_f32 v50, v52, v53
	v_cvt_pk_bf16_f32 v51, v54, v55
	v_mul_f32_e32 v56, v56, v120
	v_mul_f32_e32 v57, v57, v121
	v_mul_f32_e32 v58, v58, v122
	v_mul_f32_e32 v59, v59, v123
	v_mul_f32_e32 v60, v60, v124
	v_mul_f32_e32 v61, v61, v125
	v_mul_f32_e32 v62, v62, v126
	v_mul_f32_e32 v63, v63, v127
	v_cvt_pk_bf16_f32 v56, v56, v57
	v_cvt_pk_bf16_f32 v57, v58, v59
	v_cvt_pk_bf16_f32 v58, v60, v61
	v_cvt_pk_bf16_f32 v59, v62, v63
	v_mul_f32_e32 v64, v64, v120
	v_mul_f32_e32 v65, v65, v121
	v_mul_f32_e32 v66, v66, v122
	v_mul_f32_e32 v67, v67, v123
	v_mul_f32_e32 v68, v68, v124
	v_mul_f32_e32 v69, v69, v125
	v_mul_f32_e32 v70, v70, v126
	v_mul_f32_e32 v71, v71, v127
	v_cvt_pk_bf16_f32 v64, v64, v65
	v_cvt_pk_bf16_f32 v65, v66, v67
	v_cvt_pk_bf16_f32 v66, v68, v69
	v_cvt_pk_bf16_f32 v67, v70, v71
	v_mul_f32_e32 v72, v72, v120
	v_mul_f32_e32 v73, v73, v121
	v_mul_f32_e32 v74, v74, v122
	v_mul_f32_e32 v75, v75, v123
	v_mul_f32_e32 v76, v76, v124
	v_mul_f32_e32 v77, v77, v125
	v_mul_f32_e32 v78, v78, v126
	v_mul_f32_e32 v79, v79, v127
	v_cvt_pk_bf16_f32 v72, v72, v73
	v_cvt_pk_bf16_f32 v73, v74, v75
	v_cvt_pk_bf16_f32 v74, v76, v77
	v_cvt_pk_bf16_f32 v75, v78, v79
	s_cmp_lg_u32 s29, 0
	s_cbranch_scc1 .Ltcw2_rot
	global_store_dwordx4 v10, v[48:51], s[24:25]
	global_store_dwordx4 v10, v[56:59], s[24:25] offset:256
	global_store_dwordx4 v11, v[64:67], s[24:25] offset:512
	global_store_dwordx4 v11, v[72:75], s[24:25] offset:768
	s_branch .Ltcw2_done

; #define LAS __attribute__((address_space(3)))
; __device__ __forceinline__ unsigned pk2(float lo, float hi) { f32x2 f = {lo, hi}; bf16x2_t b = __builtin_convertvector(f, bf16x2_t); return __builtin_bit_cast(unsigned, b); }
; __device__ __forceinline__ void tr_load(const float* W, int N, int item, int lane, float (&wv)[32]) {
;     const int nblk = N / 32, kb = item / nblk, nb = item % nblk, k0 = 64 * kb, n0 = 32 * nb;
; #pragma unroll
;     for (int i = 0; i < 32; ++i) { const int kk = 2 * i + (lane >> 5); wv[i] = __builtin_nontemporal_load(W + (size_t)(k0 + kk) * N + n0 + (lane & 31)); }
; }
; template <int MAP, bool HASG, bool PERMW>
; __device__ __forceinline__ void tr_store(int K, int N, bf16_t* WT, LAS float* scr, int item, int lane, const float* gk) {
;     const int nblk = N / 32, kb = item / nblk, nb = item % nblk, k0 = 64 * kb, n0 = 32 * nb;
;     asm volatile("s_waitcnt lgkmcnt(0)" ::: "memory");
;     const int c = lane & 7;
;     f32x4 g0 = {1.f, 1.f, 1.f, 1.f}, g1 = {1.f, 1.f, 1.f, 1.f};
;     if (HASG) { g0 = *(const f32x4*)(gk + k0 + 8 * c); g1 = *(const f32x4*)(gk + k0 + 8 * c + 4); }
; #pragma unroll
;     for (int j = 0; j < 4; ++j) { const int n = (lane >> 3) + 8 * j; const LAS float* s = scr + (8 * c) * 33 + n;
;         u32x4 o; o.x = pk2(s[0 * 33] * g0[0], s[1 * 33] * g0[1]); o.y = pk2(s[2 * 33] * g0[2], s[3 * 33] * g0[3]); o.z = pk2(s[4 * 33] * g1[0], s[5 * 33] * g1[1]); o.w = pk2(s[6 * 33] * g1[2], s[7 * 33] * g1[3]);
;         const int wr_ = rowmap<MAP>(n0 + n), slot_ = PERMW ? ((wr_ & ~31) + invperm32(wr_ & 31)) : wr_;
;         *(u32x4*)((char*)WT + tiled_off(slot_, k0 + 8 * c, K / 64)) = o; }
;     asm volatile("s_waitcnt lgkmcnt(0)" ::: "memory");
; }
; template <int MAP, bool HASG = false, bool PERMW = false>
; __device__ __forceinline__ void transpose_mat(const float* W, int K, int N, bf16_t* WT, LAS float* scr, int gw, int ngw, int lane, const float* gk = nullptr) {
;     const int nitems = (K / 64) * (N / 32);
;     int it = gw;
;     if (it >= nitems) return;
;     float wv[32];
;     tr_load(W, N, it, lane, wv);
; __global__ void __launch_bounds__(512, 2) mega_fwd(Params p) {
;     ...
;             transpose_mat<0, false, true>(p.in[7] + (size_t)l * 1024 * D, 1024, D, P_W(WS_WA), scr, gw, ngw, lane);
.LBB0_378:
	s_lshr_b32 vcc_lo, s78, 1
	s_cmp_lt_u32 s2, vcc_lo
	s_cbranch_scc1 .Ltc3_done
	v_writelane_b32 v255, s4, 24
	v_writelane_b32 v255, s5, 25
	v_writelane_b32 v255, s6, 26
	v_writelane_b32 v255, s7, 27
	v_writelane_b32 v255, s8, 28
	v_writelane_b32 v255, s9, 29
	v_writelane_b32 v255, s10, 30
	v_writelane_b32 v255, s11, 31
	v_writelane_b32 v255, s12, 32
	v_writelane_b32 v255, s13, 33
	v_writelane_b32 v255, s14, 34
	v_writelane_b32 v255, s15, 35
	v_writelane_b32 v255, s16, 36
	v_writelane_b32 v255, s17, 37
	v_writelane_b32 v255, s18, 38
	v_writelane_b32 v255, s19, 39
	v_writelane_b32 v255, s20, 40
	v_writelane_b32 v255, s21, 41
	v_writelane_b32 v255, s22, 42
	v_writelane_b32 v255, s23, 43
	v_writelane_b32 v255, s24, 44
	v_writelane_b32 v255, s25, 45
	v_writelane_b32 v255, s26, 46
	v_writelane_b32 v255, s27, 47
	v_writelane_b32 v255, s28, 48
	v_writelane_b32 v255, s29, 49
	v_readfirstlane_b32 s8, v234
	s_nop 3
	s_lshr_b32 s8, s8, 6
	s_lshr_b32 s19, s78, 1
	s_sub_u32 s18, s2, s19
	s_lshl_b32 s18, s18, 3
	s_add_u32 s18, s18, s8
	s_sub_u32 s19, s78, s19
	s_lshl_b32 s19, s19, 3
	s_mul_i32 s10, s8, 0x2100
	v_and_b32_e32 v0, 63, v234
	v_and_b32_e32 v1, 31, v0
	v_lshrrev_b32_e32 v2, 5, v0
	v_lshlrev_b32_e32 v3, 13, v2
	v_lshl_add_u32 v3, v1, 2, v3
	v_mul_u32_u24_e32 v4, 33, v2
	v_add_u32_e32 v4, v4, v1
	v_lshl_add_u32 v4, v4, 2, s10
	v_and_b32_e32 v5, 7, v0
	v_lshrrev_b32_e32 v6, 3, v0
	v_mul_u32_u24_e32 v7, 0x108, v5
	v_add_u32_e32 v7, v7, v6
	v_lshl_add_u32 v7, v7, 2, s10
	v_lshrrev_b32_e32 v12, 2, v5
	v_lshlrev_b32_e32 v12, 10, v12
	v_and_b32_e32 v13, 3, v5
	v_lshl_add_u32 v12, v13, 4, v12
	v_lshl_add_u32 v8, v6, 6, v12
	v_xor_b32_e32 v9, 32, v8
	v_add_u32_e32 v9, 0x200, v9
	v_and_b32_e32 v13, 3, v6
	v_lshl_add_u32 v10, v13, 6, v12
	v_bfe_u32 v13, v6, 2, 1
	v_lshl_add_u32 v10, v13, 11, v10
	v_xor_b32_e32 v11, 32, v10
	v_lshlrev_b32_e32 v14, 5, v5
	v_mul_u32_u24_e32 v15, 0x5800, v2
	v_lshl_add_u32 v15, v1, 2, v15
	v_mul_u32_u24_e32 v12, 0xd000, v2
	v_lshl_add_u32 v12, v1, 2, v12
	v_readlane_b32 s4, v255, 10
	v_readlane_b32 s5, v255, 11
	s_nop 3
	s_and_b32 s6, s60, 0x800000
	s_add_u32 s4, s4, s6
	s_addc_u32 s5, s5, 0
	s_add_u32 s6, s76, 0x7600000
	s_addc_u32 s7, s77, 0
	s_mov_b32 s9, s18
	s_cmpk_ge_u32 s9, 0x400
	s_cbranch_scc1 .Ltc3a_exit
	s_lshr_b32 s11, s9, 6
	s_and_b32 s12, s9, 63
	s_lshl_b32 s13, s11, 19
	s_lshl_b32 s14, s12, 7
	s_add_u32 s13, s13, s14
	s_add_u32 s14, s4, s13
	s_addc_u32 s15, s5, 0
	global_load_dword v16, v3, s[14:15]
	s_add_u32 s14, s14, 0x4000
	s_addc_u32 s15, s15, 0
	global_load_dword v17, v3, s[14:15]
	s_add_u32 s14, s14, 0x4000
	s_addc_u32 s15, s15, 0
	global_load_dword v18, v3, s[14:15]
	s_add_u32 s14, s14, 0x4000
	s_addc_u32 s15, s15, 0
	global_load_dword v19, v3, s[14:15]
	s_add_u32 s14, s14, 0x4000
	s_addc_u32 s15, s15, 0
	global_load_dword v20, v3, s[14:15]
	s_add_u32 s14, s14, 0x4000
	s_addc_u32 s15, s15, 0
	global_load_dword v21, v3, s[14:15]
	s_add_u32 s14, s14, 0x4000
	s_addc_u32 s15, s15, 0
	global_load_dword v22, v3, s[14:15]
	s_add_u32 s14, s14, 0x4000
	s_addc_u32 s15, s15, 0
	global_load_dword v23, v3, s[14:15]
	s_add_u32 s14, s14, 0x4000
	s_addc_u32 s15, s15, 0
	global_load_dword v24, v3, s[14:15]
	s_add_u32 s14, s14, 0x4000
	s_addc_u32 s15, s15, 0
	global_load_dword v25, v3, s[14:15]
	s_add_u32 s14, s14, 0x4000
	s_addc_u32 s15, s15, 0
	global_load_dword v26, v3, s[14:15]
	s_add_u32 s14, s14, 0x4000
	s_addc_u32 s15, s15, 0
	global_load_dword v27, v3, s[14:15]
	s_add_u32 s14, s14, 0x4000
	s_addc_u32 s15, s15, 0
	global_load_dword v28, v3, s[14:15]
	s_add_u32 s14, s14, 0x4000
	s_addc_u32 s15, s15, 0
	global_load_dword v29, v3, s[14:15]
	s_add_u32 s14, s14, 0x4000
	s_addc_u32 s15, s15, 0
	global_load_dword v30, v3, s[14:15]
	s_add_u32 s14, s14, 0x4000
	s_addc_u32 s15, s15, 0
	global_load_dword v31, v3, s[14:15]
	s_add_u32 s14, s14, 0x4000
	s_addc_u32 s15, s15, 0
	global_load_dword v32, v3, s[14:15]
	s_add_u32 s14, s14, 0x4000
	s_addc_u32 s15, s15, 0
	global_load_dword v33, v3, s[14:15]
	s_add_u32 s14, s14, 0x4000
	s_addc_u32 s15, s15, 0
	global_load_dword v34, v3, s[14:15]
	s_add_u32 s14, s14, 0x4000
	s_addc_u32 s15, s15, 0
	global_load_dword v35, v3, s[14:15]
	s_add_u32 s14, s14, 0x4000
	s_addc_u32 s15, s15, 0
	global_load_dword v36, v3, s[14:15]
	s_add_u32 s14, s14, 0x4000
	s_addc_u32 s15, s15, 0
	global_load_dword v37, v3, s[14:15]
	s_add_u32 s14, s14, 0x4000
	s_addc_u32 s15, s15, 0
	global_load_dword v38, v3, s[14:15]
	s_add_u32 s14, s14, 0x4000
	s_addc_u32 s15, s15, 0
	global_load_dword v39, v3, s[14:15]
	s_add_u32 s14, s14, 0x4000
	s_addc_u32 s15, s15, 0
	global_load_dword v40, v3, s[14:15]
	s_add_u32 s14, s14, 0x4000
	s_addc_u32 s15, s15, 0
	global_load_dword v41, v3, s[14:15]
	s_add_u32 s14, s14, 0x4000
	s_addc_u32 s15, s15, 0
	global_load_dword v42, v3, s[14:15]
	s_add_u32 s14, s14, 0x4000
	s_addc_u32 s15, s15, 0
	global_load_dword v43, v3, s[14:15]
	s_add_u32 s14, s14, 0x4000
	s_addc_u32 s15, s15, 0
	global_load_dword v44, v3, s[14:15]
	s_add_u32 s14, s14, 0x4000
	s_addc_u32 s15, s15, 0
	global_load_dword v45, v3, s[14:15]
	s_add_u32 s14, s14, 0x4000
	s_addc_u32 s15, s15, 0
	global_load_dword v46, v3, s[14:15]
	s_add_u32 s14, s14, 0x4000
	s_addc_u32 s15, s15, 0
	global_load_dword v47, v3, s[14:15]
	s_lshr_b32 s16, s12, 2
	s_mul_i32 s16, s16, 0x10
	s_add_u32 s16, s16, s11
	s_lshl_b32 s16, s16, 14
	s_and_b32 s17, s12, 3
	s_lshl_b32 s17, s17, 12
	s_add_u32 s16, s16, s17
	s_add_u32 s16, s6, s16
	s_addc_u32 s17, s7, 0
; __device__ __forceinline__ void tr_load(const float* W, int N, int item, int lane, float (&wv)[32]) {
;     const int nblk = N / 32, kb = item / nblk, nb = item % nblk, k0 = 64 * kb, n0 = 32 * nb;
; #pragma unroll
;     for (int i = 0; i < 32; ++i) { const int kk = 2 * i + (lane >> 5); wv[i] = __builtin_nontemporal_load(W + (size_t)(k0 + kk) * N + n0 + (lane & 31)); }
; }
; template <int MAP, bool HASG, bool PERMW>
; __device__ __forceinline__ void tr_store(int K, int N, bf16_t* WT, LAS float* scr, int item, int lane, const float* gk) {
;     const int nblk = N / 32, kb = item / nblk, nb = item % nblk, k0 = 64 * kb, n0 = 32 * nb;
;     asm volatile("s_waitcnt lgkmcnt(0)" ::: "memory");
;     const int c = lane & 7;
;     f32x4 g0 = {1.f, 1.f, 1.f, 1.f}, g1 = {1.f, 1.f, 1.f, 1.f};
;     if (HASG) { g0 = *(const f32x4*)(gk + k0 + 8 * c); g1 = *(const f32x4*)(gk + k0 + 8 * c + 4); }
; #pragma unroll
;     for (int j = 0; j < 4; ++j) { const int n = (lane >> 3) + 8 * j; const LAS float* s = scr + (8 * c) * 33 + n;
;         u32x4 o; o.x = pk2(s[0 * 33] * g0[0], s[1 * 33] * g0[1]); o.y = pk2(s[2 * 33] * g0[2], s[3 * 33] * g0[3]); o.z = pk2(s[4 * 33] * g1[0], s[5 * 33] * g1[1]); o.w = pk2(s[6 * 33] * g1[2], s[7 * 33] * g1[3]);
;         const int wr_ = rowmap<MAP>(n0 + n), slot_ = PERMW ? ((wr_ & ~31) + invperm32(wr_ & 31)) : wr_;
;         *(u32x4*)((char*)WT + tiled_off(slot_, k0 + 8 * c, K / 64)) = o; }
;     asm volatile("s_waitcnt lgkmcnt(0)" ::: "memory");
; }
; template <int MAP, bool HASG = false, bool PERMW = false>
; __device__ __forceinline__ void transpose_mat(const float* W, int K, int N, bf16_t* WT, LAS float* scr, int gw, int ngw, int lane, const float* gk = nullptr) {
;     const int nitems = (K / 64) * (N / 32);
;     int it = gw;
;     if (it >= nitems) return;
;     float wv[32];
;     tr_load(W, N, it, lane, wv);
;     for (;;) {
;         __builtin_amdgcn_sched_barrier(0);
; #pragma unroll
;         for (int i = 0; i < 32; ++i) { const int kk = 2 * i + (lane >> 5); scr[kk * 33 + (lane & 31)] = wv[i]; }
;         __builtin_amdgcn_sched_barrier(0);
;         const int nx = it + ngw;
;         if (nx < nitems) tr_load(W, N, nx, lane, wv);
;         __builtin_amdgcn_sched_barrier(0);
;         tr_store<MAP, HASG, PERMW>(K, N, WT, scr, it, lane, gk);
;         if (nx >= nitems) break;
;         it = nx;
.Ltc3a_loop:
	s_add_u32 s9, s9, s19
	s_cmpk_ge_u32 s9, 0x400
	s_cbranch_scc1 .Ltc3a_lastA
	s_lshr_b32 s11, s9, 6
	s_and_b32 s12, s9, 63
	s_lshl_b32 s13, s11, 19
	s_lshl_b32 s14, s12, 7
	s_add_u32 s13, s13, s14
	s_add_u32 s14, s4, s13
	s_addc_u32 s15, s5, 0
	global_load_dword v88, v3, s[14:15]
	s_add_u32 s14, s14, 0x4000
	s_addc_u32 s15, s15, 0
	global_load_dword v89, v3, s[14:15]
	s_add_u32 s14, s14, 0x4000
	s_addc_u32 s15, s15, 0
	global_load_dword v90, v3, s[14:15]
	s_add_u32 s14, s14, 0x4000
	s_addc_u32 s15, s15, 0
	global_load_dword v91, v3, s[14:15]
	s_add_u32 s14, s14, 0x4000
	s_addc_u32 s15, s15, 0
	global_load_dword v92, v3, s[14:15]
	s_add_u32 s14, s14, 0x4000
	s_addc_u32 s15, s15, 0
	global_load_dword v93, v3, s[14:15]
	s_add_u32 s14, s14, 0x4000
	s_addc_u32 s15, s15, 0
	global_load_dword v94, v3, s[14:15]
	s_add_u32 s14, s14, 0x4000
	s_addc_u32 s15, s15, 0
	global_load_dword v95, v3, s[14:15]
	s_add_u32 s14, s14, 0x4000
	s_addc_u32 s15, s15, 0
	global_load_dword v96, v3, s[14:15]
	s_add_u32 s14, s14, 0x4000
	s_addc_u32 s15, s15, 0
	global_load_dword v97, v3, s[14:15]
	s_add_u32 s14, s14, 0x4000
	s_addc_u32 s15, s15, 0
	global_load_dword v98, v3, s[14:15]
	s_add_u32 s14, s14, 0x4000
	s_addc_u32 s15, s15, 0
	global_load_dword v99, v3, s[14:15]
	s_add_u32 s14, s14, 0x4000
	s_addc_u32 s15, s15, 0
	global_load_dword v100, v3, s[14:15]
	s_add_u32 s14, s14, 0x4000
	s_addc_u32 s15, s15, 0
	global_load_dword v101, v3, s[14:15]
	s_add_u32 s14, s14, 0x4000
	s_addc_u32 s15, s15, 0
	global_load_dword v102, v3, s[14:15]
	s_add_u32 s14, s14, 0x4000
	s_addc_u32 s15, s15, 0
	global_load_dword v103, v3, s[14:15]
	s_add_u32 s14, s14, 0x4000
	s_addc_u32 s15, s15, 0
	global_load_dword v104, v3, s[14:15]
	s_add_u32 s14, s14, 0x4000
	s_addc_u32 s15, s15, 0
	global_load_dword v105, v3, s[14:15]
	s_add_u32 s14, s14, 0x4000
	s_addc_u32 s15, s15, 0
	global_load_dword v106, v3, s[14:15]
	s_add_u32 s14, s14, 0x4000
	s_addc_u32 s15, s15, 0
	global_load_dword v107, v3, s[14:15]
	s_add_u32 s14, s14, 0x4000
	s_addc_u32 s15, s15, 0
	global_load_dword v108, v3, s[14:15]
	s_add_u32 s14, s14, 0x4000
	s_addc_u32 s15, s15, 0
	global_load_dword v109, v3, s[14:15]
	s_add_u32 s14, s14, 0x4000
	s_addc_u32 s15, s15, 0
	global_load_dword v110, v3, s[14:15]
	s_add_u32 s14, s14, 0x4000
	s_addc_u32 s15, s15, 0
	global_load_dword v111, v3, s[14:15]
	s_add_u32 s14, s14, 0x4000
	s_addc_u32 s15, s15, 0
	global_load_dword v112, v3, s[14:15]
	s_add_u32 s14, s14, 0x4000
	s_addc_u32 s15, s15, 0
	global_load_dword v113, v3, s[14:15]
	s_add_u32 s14, s14, 0x4000
	s_addc_u32 s15, s15, 0
	global_load_dword v114, v3, s[14:15]
	s_add_u32 s14, s14, 0x4000
	s_addc_u32 s15, s15, 0
	global_load_dword v115, v3, s[14:15]
	s_add_u32 s14, s14, 0x4000
	s_addc_u32 s15, s15, 0
	global_load_dword v116, v3, s[14:15]
	s_add_u32 s14, s14, 0x4000
	s_addc_u32 s15, s15, 0
	global_load_dword v117, v3, s[14:15]
	s_add_u32 s14, s14, 0x4000
	s_addc_u32 s15, s15, 0
	global_load_dword v118, v3, s[14:15]
	s_add_u32 s14, s14, 0x4000
	s_addc_u32 s15, s15, 0
	global_load_dword v119, v3, s[14:15]
	s_lshr_b32 s24, s12, 2
	s_mul_i32 s24, s24, 0x10
	s_add_u32 s24, s24, s11
	s_lshl_b32 s24, s24, 14
	s_and_b32 s25, s12, 3
	s_lshl_b32 s25, s25, 12
	s_add_u32 s24, s24, s25
	s_add_u32 s24, s6, s24
	s_addc_u32 s25, s7, 0
	s_waitcnt vmcnt(32)
	ds_write_b32 v4, v16
	ds_write_b32 v4, v17 offset:264
	ds_write_b32 v4, v18 offset:528
	ds_write_b32 v4, v19 offset:792
	ds_write_b32 v4, v20 offset:1056
	ds_write_b32 v4, v21 offset:1320
	ds_write_b32 v4, v22 offset:1584
	ds_write_b32 v4, v23 offset:1848
	ds_write_b32 v4, v24 offset:2112
	ds_write_b32 v4, v25 offset:2376
	ds_write_b32 v4, v26 offset:2640
	ds_write_b32 v4, v27 offset:2904
	ds_write_b32 v4, v28 offset:3168
	ds_write_b32 v4, v29 offset:3432
	ds_write_b32 v4, v30 offset:3696
	ds_write_b32 v4, v31 offset:3960
	ds_write_b32 v4, v32 offset:4224
	ds_write_b32 v4, v33 offset:4488
	ds_write_b32 v4, v34 offset:4752
	ds_write_b32 v4, v35 offset:5016
	ds_write_b32 v4, v36 offset:5280
	ds_write_b32 v4, v37 offset:5544
	ds_write_b32 v4, v38 offset:5808
	ds_write_b32 v4, v39 offset:6072
	ds_write_b32 v4, v40 offset:6336
	ds_write_b32 v4, v41 offset:6600
	ds_write_b32 v4, v42 offset:6864
	ds_write_b32 v4, v43 offset:7128
	ds_write_b32 v4, v44 offset:7392
	ds_write_b32 v4, v45 offset:7656
	ds_write_b32 v4, v46 offset:7920
	ds_write_b32 v4, v47 offset:8184
	s_waitcnt lgkmcnt(0)
	ds_read_b32 v48, v7
	ds_read_b32 v49, v7 offset:132
	ds_read_b32 v50, v7 offset:264
	ds_read_b32 v51, v7 offset:396
	ds_read_b32 v52, v7 offset:528
	ds_read_b32 v53, v7 offset:660
	ds_read_b32 v54, v7 offset:792
	ds_read_b32 v55, v7 offset:924
	ds_read_b32 v56, v7 offset:32
	ds_read_b32 v57, v7 offset:164
	ds_read_b32 v58, v7 offset:296
	ds_read_b32 v59, v7 offset:428
	ds_read_b32 v60, v7 offset:560
	ds_read_b32 v61, v7 offset:692
	ds_read_b32 v62, v7 offset:824
	ds_read_b32 v63, v7 offset:956
	ds_read_b32 v64, v7 offset:64
	ds_read_b32 v65, v7 offset:196
	ds_read_b32 v66, v7 offset:328
	ds_read_b32 v67, v7 offset:460
	ds_read_b32 v68, v7 offset:592
	ds_read_b32 v69, v7 offset:724
	ds_read_b32 v70, v7 offset:856
	ds_read_b32 v71, v7 offset:988
	ds_read_b32 v72, v7 offset:96
	ds_read_b32 v73, v7 offset:228
	ds_read_b32 v74, v7 offset:360
	ds_read_b32 v75, v7 offset:492
	ds_read_b32 v76, v7 offset:624
	ds_read_b32 v77, v7 offset:756
	ds_read_b32 v78, v7 offset:888
	ds_read_b32 v79, v7 offset:1020
	s_waitcnt lgkmcnt(0)
	v_cvt_pk_bf16_f32 v48, v48, v49
	v_cvt_pk_bf16_f32 v49, v50, v51
	v_cvt_pk_bf16_f32 v50, v52, v53
	v_cvt_pk_bf16_f32 v51, v54, v55
	global_store_dwordx4 v10, v[48:51], s[16:17]
	v_cvt_pk_bf16_f32 v56, v56, v57
	v_cvt_pk_bf16_f32 v57, v58, v59
	v_cvt_pk_bf16_f32 v58, v60, v61
	v_cvt_pk_bf16_f32 v59, v62, v63
	global_store_dwordx4 v10, v[56:59], s[16:17] offset:256
	v_cvt_pk_bf16_f32 v64, v64, v65
	v_cvt_pk_bf16_f32 v65, v66, v67
	v_cvt_pk_bf16_f32 v66, v68, v69
	v_cvt_pk_bf16_f32 v67, v70, v71
	global_store_dwordx4 v11, v[64:67], s[16:17] offset:512
	v_cvt_pk_bf16_f32 v72, v72, v73
	v_cvt_pk_bf16_f32 v73, v74, v75
	v_cvt_pk_bf16_f32 v74, v76, v77
	v_cvt_pk_bf16_f32 v75, v78, v79
	global_store_dwordx4 v11, v[72:75], s[16:17] offset:768
	s_add_u32 s9, s9, s19
	s_cmpk_ge_u32 s9, 0x400
	s_cbranch_scc1 .Ltc3a_lastB
; __device__ __forceinline__ void tr_load(const float* W, int N, int item, int lane, float (&wv)[32]) {
;     const int nblk = N / 32, kb = item / nblk, nb = item % nblk, k0 = 64 * kb, n0 = 32 * nb;
; #pragma unroll
;     for (int i = 0; i < 32; ++i) { const int kk = 2 * i + (lane >> 5); wv[i] = __builtin_nontemporal_load(W + (size_t)(k0 + kk) * N + n0 + (lane & 31)); }
; }
; template <int MAP, bool HASG, bool PERMW>
; __device__ __forceinline__ void tr_store(int K, int N, bf16_t* WT, LAS float* scr, int item, int lane, const float* gk) {
;     const int nblk = N / 32, kb = item / nblk, nb = item % nblk, k0 = 64 * kb, n0 = 32 * nb;
;     asm volatile("s_waitcnt lgkmcnt(0)" ::: "memory");
;     const int c = lane & 7;
;     f32x4 g0 = {1.f, 1.f, 1.f, 1.f}, g1 = {1.f, 1.f, 1.f, 1.f};
;     if (HASG) { g0 = *(const f32x4*)(gk + k0 + 8 * c); g1 = *(const f32x4*)(gk + k0 + 8 * c + 4); }
; #pragma unroll
;     for (int j = 0; j < 4; ++j) { const int n = (lane >> 3) + 8 * j; const LAS float* s = scr + (8 * c) * 33 + n;
;         u32x4 o; o.x = pk2(s[0 * 33] * g0[0], s[1 * 33] * g0[1]); o.y = pk2(s[2 * 33] * g0[2], s[3 * 33] * g0[3]); o.z = pk2(s[4 * 33] * g1[0], s[5 * 33] * g1[1]); o.w = pk2(s[6 * 33] * g1[2], s[7 * 33] * g1[3]);
;         const int wr_ = rowmap<MAP>(n0 + n), slot_ = PERMW ? ((wr_ & ~31) + invperm32(wr_ & 31)) : wr_;
;         *(u32x4*)((char*)WT + tiled_off(slot_, k0 + 8 * c, K / 64)) = o; }
;     asm volatile("s_waitcnt lgkmcnt(0)" ::: "memory");
; }
; template <int MAP, bool HASG = false, bool PERMW = false>
; __device__ __forceinline__ void transpose_mat(const float* W, int K, int N, bf16_t* WT, LAS float* scr, int gw, int ngw, int lane, const float* gk = nullptr) {
;     const int nitems = (K / 64) * (N / 32);
;     int it = gw;
;     if (it >= nitems) return;
;     float wv[32];
;     tr_load(W, N, it, lane, wv);
;     for (;;) {
;         __builtin_amdgcn_sched_barrier(0);
; #pragma unroll
;         for (int i = 0; i < 32; ++i) { const int kk = 2 * i + (lane >> 5); scr[kk * 33 + (lane & 31)] = wv[i]; }
;         __builtin_amdgcn_sched_barrier(0);
;         const int nx = it + ngw;
;         if (nx < nitems) tr_load(W, N, nx, lane, wv);
;         __builtin_amdgcn_sched_barrier(0);
;         tr_store<MAP, HASG, PERMW>(K, N, WT, scr, it, lane, gk);
;         if (nx >= nitems) break;
;         it = nx;
	s_lshr_b32 s11, s9, 6
	s_and_b32 s12, s9, 63
	s_lshl_b32 s13, s11, 19
	s_lshl_b32 s14, s12, 7
	s_add_u32 s13, s13, s14
	s_add_u32 s14, s4, s13
	s_addc_u32 s15, s5, 0
	global_load_dword v16, v3, s[14:15]
	s_add_u32 s14, s14, 0x4000
	s_addc_u32 s15, s15, 0
	global_load_dword v17, v3, s[14:15]
	s_add_u32 s14, s14, 0x4000
	s_addc_u32 s15, s15, 0
	global_load_dword v18, v3, s[14:15]
	s_add_u32 s14, s14, 0x4000
	s_addc_u32 s15, s15, 0
	global_load_dword v19, v3, s[14:15]
	s_add_u32 s14, s14, 0x4000
	s_addc_u32 s15, s15, 0
	global_load_dword v20, v3, s[14:15]
	s_add_u32 s14, s14, 0x4000
	s_addc_u32 s15, s15, 0
	global_load_dword v21, v3, s[14:15]
	s_add_u32 s14, s14, 0x4000
	s_addc_u32 s15, s15, 0
	global_load_dword v22, v3, s[14:15]
	s_add_u32 s14, s14, 0x4000
	s_addc_u32 s15, s15, 0
	global_load_dword v23, v3, s[14:15]
	s_add_u32 s14, s14, 0x4000
	s_addc_u32 s15, s15, 0
	global_load_dword v24, v3, s[14:15]
	s_add_u32 s14, s14, 0x4000
	s_addc_u32 s15, s15, 0
	global_load_dword v25, v3, s[14:15]
	s_add_u32 s14, s14, 0x4000
	s_addc_u32 s15, s15, 0
	global_load_dword v26, v3, s[14:15]
	s_add_u32 s14, s14, 0x4000
	s_addc_u32 s15, s15, 0
	global_load_dword v27, v3, s[14:15]
	s_add_u32 s14, s14, 0x4000
	s_addc_u32 s15, s15, 0
	global_load_dword v28, v3, s[14:15]
	s_add_u32 s14, s14, 0x4000
	s_addc_u32 s15, s15, 0
	global_load_dword v29, v3, s[14:15]
	s_add_u32 s14, s14, 0x4000
	s_addc_u32 s15, s15, 0
	global_load_dword v30, v3, s[14:15]
	s_add_u32 s14, s14, 0x4000
	s_addc_u32 s15, s15, 0
	global_load_dword v31, v3, s[14:15]
	s_add_u32 s14, s14, 0x4000
	s_addc_u32 s15, s15, 0
	global_load_dword v32, v3, s[14:15]
	s_add_u32 s14, s14, 0x4000
	s_addc_u32 s15, s15, 0
	global_load_dword v33, v3, s[14:15]
	s_add_u32 s14, s14, 0x4000
	s_addc_u32 s15, s15, 0
	global_load_dword v34, v3, s[14:15]
	s_add_u32 s14, s14, 0x4000
	s_addc_u32 s15, s15, 0
	global_load_dword v35, v3, s[14:15]
	s_add_u32 s14, s14, 0x4000
	s_addc_u32 s15, s15, 0
	global_load_dword v36, v3, s[14:15]
	s_add_u32 s14, s14, 0x4000
	s_addc_u32 s15, s15, 0
	global_load_dword v37, v3, s[14:15]
	s_add_u32 s14, s14, 0x4000
	s_addc_u32 s15, s15, 0
	global_load_dword v38, v3, s[14:15]
	s_add_u32 s14, s14, 0x4000
	s_addc_u32 s15, s15, 0
	global_load_dword v39, v3, s[14:15]
	s_add_u32 s14, s14, 0x4000
	s_addc_u32 s15, s15, 0
	global_load_dword v40, v3, s[14:15]
	s_add_u32 s14, s14, 0x4000
	s_addc_u32 s15, s15, 0
	global_load_dword v41, v3, s[14:15]
	s_add_u32 s14, s14, 0x4000
	s_addc_u32 s15, s15, 0
	global_load_dword v42, v3, s[14:15]
	s_add_u32 s14, s14, 0x4000
	s_addc_u32 s15, s15, 0
	global_load_dword v43, v3, s[14:15]
	s_add_u32 s14, s14, 0x4000
	s_addc_u32 s15, s15, 0
	global_load_dword v44, v3, s[14:15]
	s_add_u32 s14, s14, 0x4000
	s_addc_u32 s15, s15, 0
	global_load_dword v45, v3, s[14:15]
	s_add_u32 s14, s14, 0x4000
	s_addc_u32 s15, s15, 0
	global_load_dword v46, v3, s[14:15]
	s_add_u32 s14, s14, 0x4000
	s_addc_u32 s15, s15, 0
	global_load_dword v47, v3, s[14:15]
	s_lshr_b32 s16, s12, 2
	s_mul_i32 s16, s16, 0x10
	s_add_u32 s16, s16, s11
	s_lshl_b32 s16, s16, 14
	s_and_b32 s17, s12, 3
	s_lshl_b32 s17, s17, 12
	s_add_u32 s16, s16, s17
	s_add_u32 s16, s6, s16
	s_addc_u32 s17, s7, 0
	s_waitcnt vmcnt(32)
	ds_write_b32 v4, v88
	ds_write_b32 v4, v89 offset:264
	ds_write_b32 v4, v90 offset:528
	ds_write_b32 v4, v91 offset:792
	ds_write_b32 v4, v92 offset:1056
	ds_write_b32 v4, v93 offset:1320
	ds_write_b32 v4, v94 offset:1584
	ds_write_b32 v4, v95 offset:1848
	ds_write_b32 v4, v96 offset:2112
	ds_write_b32 v4, v97 offset:2376
	ds_write_b32 v4, v98 offset:2640
	ds_write_b32 v4, v99 offset:2904
	ds_write_b32 v4, v100 offset:3168
	ds_write_b32 v4, v101 offset:3432
	ds_write_b32 v4, v102 offset:3696
	ds_write_b32 v4, v103 offset:3960
	ds_write_b32 v4, v104 offset:4224
	ds_write_b32 v4, v105 offset:4488
	ds_write_b32 v4, v106 offset:4752
	ds_write_b32 v4, v107 offset:5016
	ds_write_b32 v4, v108 offset:5280
	ds_write_b32 v4, v109 offset:5544
	ds_write_b32 v4, v110 offset:5808
	ds_write_b32 v4, v111 offset:6072
	ds_write_b32 v4, v112 offset:6336
	ds_write_b32 v4, v113 offset:6600
	ds_write_b32 v4, v114 offset:6864
	ds_write_b32 v4, v115 offset:7128
	ds_write_b32 v4, v116 offset:7392
	ds_write_b32 v4, v117 offset:7656
	ds_write_b32 v4, v118 offset:7920
	ds_write_b32 v4, v119 offset:8184
	s_waitcnt lgkmcnt(0)
	ds_read_b32 v48, v7
	ds_read_b32 v49, v7 offset:132
	ds_read_b32 v50, v7 offset:264
	ds_read_b32 v51, v7 offset:396
	ds_read_b32 v52, v7 offset:528
	ds_read_b32 v53, v7 offset:660
	ds_read_b32 v54, v7 offset:792
	ds_read_b32 v55, v7 offset:924
	ds_read_b32 v56, v7 offset:32
	ds_read_b32 v57, v7 offset:164
	ds_read_b32 v58, v7 offset:296
	ds_read_b32 v59, v7 offset:428
	ds_read_b32 v60, v7 offset:560
	ds_read_b32 v61, v7 offset:692
	ds_read_b32 v62, v7 offset:824
	ds_read_b32 v63, v7 offset:956
	ds_read_b32 v64, v7 offset:64
	ds_read_b32 v65, v7 offset:196
	ds_read_b32 v66, v7 offset:328
	ds_read_b32 v67, v7 offset:460
	ds_read_b32 v68, v7 offset:592
	ds_read_b32 v69, v7 offset:724
	ds_read_b32 v70, v7 offset:856
	ds_read_b32 v71, v7 offset:988
	ds_read_b32 v72, v7 offset:96
	ds_read_b32 v73, v7 offset:228
	ds_read_b32 v74, v7 offset:360
	ds_read_b32 v75, v7 offset:492
	ds_read_b32 v76, v7 offset:624
	ds_read_b32 v77, v7 offset:756
	ds_read_b32 v78, v7 offset:888
	ds_read_b32 v79, v7 offset:1020
	s_waitcnt lgkmcnt(0)
	v_cvt_pk_bf16_f32 v48, v48, v49
	v_cvt_pk_bf16_f32 v49, v50, v51
	v_cvt_pk_bf16_f32 v50, v52, v53
	v_cvt_pk_bf16_f32 v51, v54, v55
	global_store_dwordx4 v10, v[48:51], s[24:25]
	v_cvt_pk_bf16_f32 v56, v56, v57
	v_cvt_pk_bf16_f32 v57, v58, v59
	v_cvt_pk_bf16_f32 v58, v60, v61
	v_cvt_pk_bf16_f32 v59, v62, v63
	global_store_dwordx4 v10, v[56:59], s[24:25] offset:256
	v_cvt_pk_bf16_f32 v64, v64, v65
	v_cvt_pk_bf16_f32 v65, v66, v67
	v_cvt_pk_bf16_f32 v66, v68, v69
	v_cvt_pk_bf16_f32 v67, v70, v71
	global_store_dwordx4 v11, v[64:67], s[24:25] offset:512
	v_cvt_pk_bf16_f32 v72, v72, v73
	v_cvt_pk_bf16_f32 v73, v74, v75
	v_cvt_pk_bf16_f32 v74, v76, v77
	v_cvt_pk_bf16_f32 v75, v78, v79
	global_store_dwordx4 v11, v[72:75], s[24:25] offset:768
	s_branch .Ltc3a_loop

; __device__ __forceinline__ void tr_load(const float* W, int N, int item, int lane, float (&wv)[32]) {
;     const int nblk = N / 32, kb = item / nblk, nb = item % nblk, k0 = 64 * kb, n0 = 32 * nb;
; #pragma unroll
;     for (int i = 0; i < 32; ++i) { const int kk = 2 * i + (lane >> 5); wv[i] = __builtin_nontemporal_load(W + (size_t)(k0 + kk) * N + n0 + (lane & 31)); }
; }
; template <int MAP, bool HASG, bool PERMW>
; __device__ __forceinline__ void tr_store(int K, int N, bf16_t* WT, LAS float* scr, int item, int lane, const float* gk) {
;     const int nblk = N / 32, kb = item / nblk, nb = item % nblk, k0 = 64 * kb, n0 = 32 * nb;
;     asm volatile("s_waitcnt lgkmcnt(0)" ::: "memory");
;     const int c = lane & 7;
;     f32x4 g0 = {1.f, 1.f, 1.f, 1.f}, g1 = {1.f, 1.f, 1.f, 1.f};
;     if (HASG) { g0 = *(const f32x4*)(gk + k0 + 8 * c); g1 = *(const f32x4*)(gk + k0 + 8 * c + 4); }
; #pragma unroll
;     for (int j = 0; j < 4; ++j) { const int n = (lane >> 3) + 8 * j; const LAS float* s = scr + (8 * c) * 33 + n;
;         u32x4 o; o.x = pk2(s[0 * 33] * g0[0], s[1 * 33] * g0[1]); o.y = pk2(s[2 * 33] * g0[2], s[3 * 33] * g0[3]); o.z = pk2(s[4 * 33] * g1[0], s[5 * 33] * g1[1]); o.w = pk2(s[6 * 33] * g1[2], s[7 * 33] * g1[3]);
;         const int wr_ = rowmap<MAP>(n0 + n), slot_ = PERMW ? ((wr_ & ~31) + invperm32(wr_ & 31)) : wr_;
;         *(u32x4*)((char*)WT + tiled_off(slot_, k0 + 8 * c, K / 64)) = o; }
;     asm volatile("s_waitcnt lgkmcnt(0)" ::: "memory");
; }
; template <int MAP, bool HASG = false, bool PERMW = false>
; __device__ __forceinline__ void transpose_mat(const float* W, int K, int N, bf16_t* WT, LAS float* scr, int gw, int ngw, int lane, const float* gk = nullptr) {
;     const int nitems = (K / 64) * (N / 32);
;     int it = gw;
;     if (it >= nitems) return;
;     float wv[32];
;     tr_load(W, N, it, lane, wv);
;     for (;;) {
;         __builtin_amdgcn_sched_barrier(0);
; #pragma unroll
;         for (int i = 0; i < 32; ++i) { const int kk = 2 * i + (lane >> 5); scr[kk * 33 + (lane & 31)] = wv[i]; }
;         __builtin_amdgcn_sched_barrier(0);
;         const int nx = it + ngw;
;         if (nx < nitems) tr_load(W, N, nx, lane, wv);
;         __builtin_amdgcn_sched_barrier(0);
;         tr_store<MAP, HASG, PERMW>(K, N, WT, scr, it, lane, gk);
;         if (nx >= nitems) break;
;         it = nx;
.Ltc3a_exit:
	v_readlane_b32 s4, v254, 0
	v_readlane_b32 s5, v254, 1
	s_nop 3
	s_and_b32 s6, s60, 0x1000000
	s_add_u32 s4, s4, s6
	s_addc_u32 s5, s5, 0
	s_add_u32 s6, s76, 0x7a00000
	s_addc_u32 s7, s77, 0
	s_mov_b32 s9, s18
	s_cmpk_ge_u32 s9, 0x800
	s_cbranch_scc1 .Ltc3b_exit
	s_lshr_b32 s11, s9, 6
	s_and_b32 s12, s9, 63
	s_lshl_b32 s13, s11, 19
	s_lshl_b32 s14, s12, 7
	s_add_u32 s13, s13, s14
	s_add_u32 s14, s4, s13
	s_addc_u32 s15, s5, 0
	global_load_dword v16, v3, s[14:15]
	s_add_u32 s14, s14, 0x4000
	s_addc_u32 s15, s15, 0
	global_load_dword v17, v3, s[14:15]
	s_add_u32 s14, s14, 0x4000
	s_addc_u32 s15, s15, 0
	global_load_dword v18, v3, s[14:15]
	s_add_u32 s14, s14, 0x4000
	s_addc_u32 s15, s15, 0
	global_load_dword v19, v3, s[14:15]
	s_add_u32 s14, s14, 0x4000
	s_addc_u32 s15, s15, 0
	global_load_dword v20, v3, s[14:15]
	s_add_u32 s14, s14, 0x4000
	s_addc_u32 s15, s15, 0
	global_load_dword v21, v3, s[14:15]
	s_add_u32 s14, s14, 0x4000
	s_addc_u32 s15, s15, 0
	global_load_dword v22, v3, s[14:15]
	s_add_u32 s14, s14, 0x4000
	s_addc_u32 s15, s15, 0
	global_load_dword v23, v3, s[14:15]
	s_add_u32 s14, s14, 0x4000
	s_addc_u32 s15, s15, 0
	global_load_dword v24, v3, s[14:15]
	s_add_u32 s14, s14, 0x4000
	s_addc_u32 s15, s15, 0
	global_load_dword v25, v3, s[14:15]
	s_add_u32 s14, s14, 0x4000
	s_addc_u32 s15, s15, 0
	global_load_dword v26, v3, s[14:15]
	s_add_u32 s14, s14, 0x4000
	s_addc_u32 s15, s15, 0
	global_load_dword v27, v3, s[14:15]
	s_add_u32 s14, s14, 0x4000
	s_addc_u32 s15, s15, 0
	global_load_dword v28, v3, s[14:15]
	s_add_u32 s14, s14, 0x4000
	s_addc_u32 s15, s15, 0
	global_load_dword v29, v3, s[14:15]
	s_add_u32 s14, s14, 0x4000
	s_addc_u32 s15, s15, 0
	global_load_dword v30, v3, s[14:15]
	s_add_u32 s14, s14, 0x4000
	s_addc_u32 s15, s15, 0
	global_load_dword v31, v3, s[14:15]
	s_add_u32 s14, s14, 0x4000
	s_addc_u32 s15, s15, 0
	global_load_dword v32, v3, s[14:15]
	s_add_u32 s14, s14, 0x4000
	s_addc_u32 s15, s15, 0
	global_load_dword v33, v3, s[14:15]
	s_add_u32 s14, s14, 0x4000
	s_addc_u32 s15, s15, 0
	global_load_dword v34, v3, s[14:15]
	s_add_u32 s14, s14, 0x4000
	s_addc_u32 s15, s15, 0
	global_load_dword v35, v3, s[14:15]
	s_add_u32 s14, s14, 0x4000
	s_addc_u32 s15, s15, 0
	global_load_dword v36, v3, s[14:15]
	s_add_u32 s14, s14, 0x4000
	s_addc_u32 s15, s15, 0
	global_load_dword v37, v3, s[14:15]
	s_add_u32 s14, s14, 0x4000
	s_addc_u32 s15, s15, 0
	global_load_dword v38, v3, s[14:15]
	s_add_u32 s14, s14, 0x4000
	s_addc_u32 s15, s15, 0
	global_load_dword v39, v3, s[14:15]
	s_add_u32 s14, s14, 0x4000
	s_addc_u32 s15, s15, 0
	global_load_dword v40, v3, s[14:15]
	s_add_u32 s14, s14, 0x4000
	s_addc_u32 s15, s15, 0
	global_load_dword v41, v3, s[14:15]
	s_add_u32 s14, s14, 0x4000
	s_addc_u32 s15, s15, 0
	global_load_dword v42, v3, s[14:15]
	s_add_u32 s14, s14, 0x4000
	s_addc_u32 s15, s15, 0
	global_load_dword v43, v3, s[14:15]
	s_add_u32 s14, s14, 0x4000
	s_addc_u32 s15, s15, 0
	global_load_dword v44, v3, s[14:15]
	s_add_u32 s14, s14, 0x4000
	s_addc_u32 s15, s15, 0
	global_load_dword v45, v3, s[14:15]
	s_add_u32 s14, s14, 0x4000
	s_addc_u32 s15, s15, 0
	global_load_dword v46, v3, s[14:15]
	s_add_u32 s14, s14, 0x4000
	s_addc_u32 s15, s15, 0
	global_load_dword v47, v3, s[14:15]
	s_lshr_b32 s16, s12, 2
	s_mul_i32 s16, s16, 0x20
	s_add_u32 s16, s16, s11
	s_lshl_b32 s16, s16, 14
	s_and_b32 s17, s12, 3
	s_lshl_b32 s17, s17, 12
	s_add_u32 s16, s16, s17
	s_add_u32 s16, s6, s16
	s_addc_u32 s17, s7, 0
.Ltc3b_loop:
	s_add_u32 s9, s9, s19
	s_cmpk_ge_u32 s9, 0x800
	s_cbranch_scc1 .Ltc3b_lastA
	s_lshr_b32 s11, s9, 6
	s_and_b32 s12, s9, 63
	s_lshl_b32 s13, s11, 19
	s_lshl_b32 s14, s12, 7
	s_add_u32 s13, s13, s14
	s_add_u32 s14, s4, s13
	s_addc_u32 s15, s5, 0
	global_load_dword v88, v3, s[14:15]
	s_add_u32 s14, s14, 0x4000
	s_addc_u32 s15, s15, 0
	global_load_dword v89, v3, s[14:15]
	s_add_u32 s14, s14, 0x4000
	s_addc_u32 s15, s15, 0
	global_load_dword v90, v3, s[14:15]
	s_add_u32 s14, s14, 0x4000
	s_addc_u32 s15, s15, 0
	global_load_dword v91, v3, s[14:15]
	s_add_u32 s14, s14, 0x4000
	s_addc_u32 s15, s15, 0
	global_load_dword v92, v3, s[14:15]
	s_add_u32 s14, s14, 0x4000
	s_addc_u32 s15, s15, 0
	global_load_dword v93, v3, s[14:15]
	s_add_u32 s14, s14, 0x4000
	s_addc_u32 s15, s15, 0
	global_load_dword v94, v3, s[14:15]
	s_add_u32 s14, s14, 0x4000
	s_addc_u32 s15, s15, 0
	global_load_dword v95, v3, s[14:15]
	s_add_u32 s14, s14, 0x4000
	s_addc_u32 s15, s15, 0
	global_load_dword v96, v3, s[14:15]
	s_add_u32 s14, s14, 0x4000
	s_addc_u32 s15, s15, 0
	global_load_dword v97, v3, s[14:15]
	s_add_u32 s14, s14, 0x4000
	s_addc_u32 s15, s15, 0
	global_load_dword v98, v3, s[14:15]
	s_add_u32 s14, s14, 0x4000
	s_addc_u32 s15, s15, 0
	global_load_dword v99, v3, s[14:15]
	s_add_u32 s14, s14, 0x4000
	s_addc_u32 s15, s15, 0
	global_load_dword v100, v3, s[14:15]
	s_add_u32 s14, s14, 0x4000
	s_addc_u32 s15, s15, 0
	global_load_dword v101, v3, s[14:15]
	s_add_u32 s14, s14, 0x4000
	s_addc_u32 s15, s15, 0
	global_load_dword v102, v3, s[14:15]
	s_add_u32 s14, s14, 0x4000
	s_addc_u32 s15, s15, 0
	global_load_dword v103, v3, s[14:15]
	s_add_u32 s14, s14, 0x4000
	s_addc_u32 s15, s15, 0
	global_load_dword v104, v3, s[14:15]
	s_add_u32 s14, s14, 0x4000
	s_addc_u32 s15, s15, 0
	global_load_dword v105, v3, s[14:15]
	s_add_u32 s14, s14, 0x4000
	s_addc_u32 s15, s15, 0
	global_load_dword v106, v3, s[14:15]
	s_add_u32 s14, s14, 0x4000
	s_addc_u32 s15, s15, 0
	global_load_dword v107, v3, s[14:15]
	s_add_u32 s14, s14, 0x4000
	s_addc_u32 s15, s15, 0
	global_load_dword v108, v3, s[14:15]
	s_add_u32 s14, s14, 0x4000
	s_addc_u32 s15, s15, 0
	global_load_dword v109, v3, s[14:15]
	s_add_u32 s14, s14, 0x4000
	s_addc_u32 s15, s15, 0
	global_load_dword v110, v3, s[14:15]
	s_add_u32 s14, s14, 0x4000
	s_addc_u32 s15, s15, 0
	global_load_dword v111, v3, s[14:15]
	s_add_u32 s14, s14, 0x4000
	s_addc_u32 s15, s15, 0
	global_load_dword v112, v3, s[14:15]
	s_add_u32 s14, s14, 0x4000
	s_addc_u32 s15, s15, 0
	global_load_dword v113, v3, s[14:15]
	s_add_u32 s14, s14, 0x4000
	s_addc_u32 s15, s15, 0
	global_load_dword v114, v3, s[14:15]
	s_add_u32 s14, s14, 0x4000
	s_addc_u32 s15, s15, 0
	global_load_dword v115, v3, s[14:15]
	s_add_u32 s14, s14, 0x4000
	s_addc_u32 s15, s15, 0
	global_load_dword v116, v3, s[14:15]
	s_add_u32 s14, s14, 0x4000
	s_addc_u32 s15, s15, 0
	global_load_dword v117, v3, s[14:15]
	s_add_u32 s14, s14, 0x4000
	s_addc_u32 s15, s15, 0
	global_load_dword v118, v3, s[14:15]
	s_add_u32 s14, s14, 0x4000
	s_addc_u32 s15, s15, 0
	global_load_dword v119, v3, s[14:15]
	s_lshr_b32 s24, s12, 2
	s_mul_i32 s24, s24, 0x20
	s_add_u32 s24, s24, s11
	s_lshl_b32 s24, s24, 14
	s_and_b32 s25, s12, 3
	s_lshl_b32 s25, s25, 12
	s_add_u32 s24, s24, s25
	s_add_u32 s24, s6, s24
	s_addc_u32 s25, s7, 0
	s_waitcnt vmcnt(32)
; #define LAS __attribute__((address_space(3)))
; __device__ __forceinline__ unsigned pk2(float lo, float hi) { f32x2 f = {lo, hi}; bf16x2_t b = __builtin_convertvector(f, bf16x2_t); return __builtin_bit_cast(unsigned, b); }
; template <int MAP, bool HASG, bool PERMW>
; __device__ __forceinline__ void tr_store(int K, int N, bf16_t* WT, LAS float* scr, int item, int lane, const float* gk) {
;     const int nblk = N / 32, kb = item / nblk, nb = item % nblk, k0 = 64 * kb, n0 = 32 * nb;
;     asm volatile("s_waitcnt lgkmcnt(0)" ::: "memory");
;     const int c = lane & 7;
;     f32x4 g0 = {1.f, 1.f, 1.f, 1.f}, g1 = {1.f, 1.f, 1.f, 1.f};
;     if (HASG) { g0 = *(const f32x4*)(gk + k0 + 8 * c); g1 = *(const f32x4*)(gk + k0 + 8 * c + 4); }
; #pragma unroll
;     for (int j = 0; j < 4; ++j) { const int n = (lane >> 3) + 8 * j; const LAS float* s = scr + (8 * c) * 33 + n;
;         u32x4 o; o.x = pk2(s[0 * 33] * g0[0], s[1 * 33] * g0[1]); o.y = pk2(s[2 * 33] * g0[2], s[3 * 33] * g0[3]); o.z = pk2(s[4 * 33] * g1[0], s[5 * 33] * g1[1]); o.w = pk2(s[6 * 33] * g1[2], s[7 * 33] * g1[3]);
;         const int wr_ = rowmap<MAP>(n0 + n), slot_ = PERMW ? ((wr_ & ~31) + invperm32(wr_ & 31)) : wr_;
;         *(u32x4*)((char*)WT + tiled_off(slot_, k0 + 8 * c, K / 64)) = o; }
;     asm volatile("s_waitcnt lgkmcnt(0)" ::: "memory");
; }
; template <int MAP, bool HASG = false, bool PERMW = false>
; __device__ __forceinline__ void transpose_mat(const float* W, int K, int N, bf16_t* WT, LAS float* scr, int gw, int ngw, int lane, const float* gk = nullptr) {
;     ...
;         for (int i = 0; i < 32; ++i) { const int kk = 2 * i + (lane >> 5); scr[kk * 33 + (lane & 31)] = wv[i]; }
	ds_write_b32 v4, v16
	ds_write_b32 v4, v17 offset:264
	ds_write_b32 v4, v18 offset:528
	ds_write_b32 v4, v19 offset:792
	ds_write_b32 v4, v20 offset:1056
	ds_write_b32 v4, v21 offset:1320
	ds_write_b32 v4, v22 offset:1584
	ds_write_b32 v4, v23 offset:1848
	ds_write_b32 v4, v24 offset:2112
	ds_write_b32 v4, v25 offset:2376
	ds_write_b32 v4, v26 offset:2640
	ds_write_b32 v4, v27 offset:2904
	ds_write_b32 v4, v28 offset:3168
	ds_write_b32 v4, v29 offset:3432
	ds_write_b32 v4, v30 offset:3696
	ds_write_b32 v4, v31 offset:3960
	ds_write_b32 v4, v32 offset:4224
	ds_write_b32 v4, v33 offset:4488
	ds_write_b32 v4, v34 offset:4752
	ds_write_b32 v4, v35 offset:5016
	ds_write_b32 v4, v36 offset:5280
	ds_write_b32 v4, v37 offset:5544
	ds_write_b32 v4, v38 offset:5808
	ds_write_b32 v4, v39 offset:6072
	ds_write_b32 v4, v40 offset:6336
	ds_write_b32 v4, v41 offset:6600
	ds_write_b32 v4, v42 offset:6864
	ds_write_b32 v4, v43 offset:7128
	ds_write_b32 v4, v44 offset:7392
	ds_write_b32 v4, v45 offset:7656
	ds_write_b32 v4, v46 offset:7920
	ds_write_b32 v4, v47 offset:8184
	s_waitcnt lgkmcnt(0)
	ds_read_b32 v48, v7
	ds_read_b32 v49, v7 offset:132
	ds_read_b32 v50, v7 offset:264
	ds_read_b32 v51, v7 offset:396
	ds_read_b32 v52, v7 offset:528
	ds_read_b32 v53, v7 offset:660
	ds_read_b32 v54, v7 offset:792
	ds_read_b32 v55, v7 offset:924
	ds_read_b32 v56, v7 offset:32
	ds_read_b32 v57, v7 offset:164
	ds_read_b32 v58, v7 offset:296
	ds_read_b32 v59, v7 offset:428
	ds_read_b32 v60, v7 offset:560
	ds_read_b32 v61, v7 offset:692
	ds_read_b32 v62, v7 offset:824
	ds_read_b32 v63, v7 offset:956
	ds_read_b32 v64, v7 offset:64
	ds_read_b32 v65, v7 offset:196
	ds_read_b32 v66, v7 offset:328
	ds_read_b32 v67, v7 offset:460
	ds_read_b32 v68, v7 offset:592
	ds_read_b32 v69, v7 offset:724
	ds_read_b32 v70, v7 offset:856
	ds_read_b32 v71, v7 offset:988
	ds_read_b32 v72, v7 offset:96
	ds_read_b32 v73, v7 offset:228
	ds_read_b32 v74, v7 offset:360
	ds_read_b32 v75, v7 offset:492
	ds_read_b32 v76, v7 offset:624
	ds_read_b32 v77, v7 offset:756
	ds_read_b32 v78, v7 offset:888
	ds_read_b32 v79, v7 offset:1020
	s_waitcnt lgkmcnt(0)
	v_cvt_pk_bf16_f32 v48, v48, v49
	v_cvt_pk_bf16_f32 v49, v50, v51
	v_cvt_pk_bf16_f32 v50, v52, v53
	v_cvt_pk_bf16_f32 v51, v54, v55
	global_store_dwordx4 v10, v[48:51], s[16:17]
	v_cvt_pk_bf16_f32 v56, v56, v57
	v_cvt_pk_bf16_f32 v57, v58, v59
	v_cvt_pk_bf16_f32 v58, v60, v61
	v_cvt_pk_bf16_f32 v59, v62, v63
	global_store_dwordx4 v10, v[56:59], s[16:17] offset:256
	v_cvt_pk_bf16_f32 v64, v64, v65
	v_cvt_pk_bf16_f32 v65, v66, v67
	v_cvt_pk_bf16_f32 v66, v68, v69
	v_cvt_pk_bf16_f32 v67, v70, v71
	global_store_dwordx4 v11, v[64:67], s[16:17] offset:512
	v_cvt_pk_bf16_f32 v72, v72, v73
	v_cvt_pk_bf16_f32 v73, v74, v75
	v_cvt_pk_bf16_f32 v74, v76, v77
	v_cvt_pk_bf16_f32 v75, v78, v79
	global_store_dwordx4 v11, v[72:75], s[16:17] offset:768
	s_add_u32 s9, s9, s19
	s_cmpk_ge_u32 s9, 0x800
	s_cbranch_scc1 .Ltc3b_lastB
; __device__ __forceinline__ void tr_load(const float* W, int N, int item, int lane, float (&wv)[32]) {
;     const int nblk = N / 32, kb = item / nblk, nb = item % nblk, k0 = 64 * kb, n0 = 32 * nb;
; #pragma unroll
;     for (int i = 0; i < 32; ++i) { const int kk = 2 * i + (lane >> 5); wv[i] = __builtin_nontemporal_load(W + (size_t)(k0 + kk) * N + n0 + (lane & 31)); }
; }
; template <int MAP, bool HASG, bool PERMW>
; __device__ __forceinline__ void tr_store(int K, int N, bf16_t* WT, LAS float* scr, int item, int lane, const float* gk) {
;     const int nblk = N / 32, kb = item / nblk, nb = item % nblk, k0 = 64 * kb, n0 = 32 * nb;
;     asm volatile("s_waitcnt lgkmcnt(0)" ::: "memory");
;     const int c = lane & 7;
;     f32x4 g0 = {1.f, 1.f, 1.f, 1.f}, g1 = {1.f, 1.f, 1.f, 1.f};
;     if (HASG) { g0 = *(const f32x4*)(gk + k0 + 8 * c); g1 = *(const f32x4*)(gk + k0 + 8 * c + 4); }
; #pragma unroll
;     for (int j = 0; j < 4; ++j) { const int n = (lane >> 3) + 8 * j; const LAS float* s = scr + (8 * c) * 33 + n;
;         u32x4 o; o.x = pk2(s[0 * 33] * g0[0], s[1 * 33] * g0[1]); o.y = pk2(s[2 * 33] * g0[2], s[3 * 33] * g0[3]); o.z = pk2(s[4 * 33] * g1[0], s[5 * 33] * g1[1]); o.w = pk2(s[6 * 33] * g1[2], s[7 * 33] * g1[3]);
;         const int wr_ = rowmap<MAP>(n0 + n), slot_ = PERMW ? ((wr_ & ~31) + invperm32(wr_ & 31)) : wr_;
;         *(u32x4*)((char*)WT + tiled_off(slot_, k0 + 8 * c, K / 64)) = o; }
;     asm volatile("s_waitcnt lgkmcnt(0)" ::: "memory");
; }
; template <int MAP, bool HASG = false, bool PERMW = false>
; __device__ __forceinline__ void transpose_mat(const float* W, int K, int N, bf16_t* WT, LAS float* scr, int gw, int ngw, int lane, const float* gk = nullptr) {
;     const int nitems = (K / 64) * (N / 32);
;     int it = gw;
;     if (it >= nitems) return;
;     float wv[32];
;     tr_load(W, N, it, lane, wv);
;     for (;;) {
;         __builtin_amdgcn_sched_barrier(0);
; #pragma unroll
;         for (int i = 0; i < 32; ++i) { const int kk = 2 * i + (lane >> 5); scr[kk * 33 + (lane & 31)] = wv[i]; }
;         __builtin_amdgcn_sched_barrier(0);
;         const int nx = it + ngw;
;         if (nx < nitems) tr_load(W, N, nx, lane, wv);
;         __builtin_amdgcn_sched_barrier(0);
;         tr_store<MAP, HASG, PERMW>(K, N, WT, scr, it, lane, gk);
;         if (nx >= nitems) break;
;         it = nx;
	s_lshr_b32 s11, s9, 6
	s_and_b32 s12, s9, 63
	s_lshl_b32 s13, s11, 19
	s_lshl_b32 s14, s12, 7
	s_add_u32 s13, s13, s14
	s_add_u32 s14, s4, s13
	s_addc_u32 s15, s5, 0
	global_load_dword v16, v3, s[14:15]
	s_add_u32 s14, s14, 0x4000
	s_addc_u32 s15, s15, 0
	global_load_dword v17, v3, s[14:15]
	s_add_u32 s14, s14, 0x4000
	s_addc_u32 s15, s15, 0
	global_load_dword v18, v3, s[14:15]
	s_add_u32 s14, s14, 0x4000
	s_addc_u32 s15, s15, 0
	global_load_dword v19, v3, s[14:15]
	s_add_u32 s14, s14, 0x4000
	s_addc_u32 s15, s15, 0
	global_load_dword v20, v3, s[14:15]
	s_add_u32 s14, s14, 0x4000
	s_addc_u32 s15, s15, 0
	global_load_dword v21, v3, s[14:15]
	s_add_u32 s14, s14, 0x4000
	s_addc_u32 s15, s15, 0
	global_load_dword v22, v3, s[14:15]
	s_add_u32 s14, s14, 0x4000
	s_addc_u32 s15, s15, 0
	global_load_dword v23, v3, s[14:15]
	s_add_u32 s14, s14, 0x4000
	s_addc_u32 s15, s15, 0
	global_load_dword v24, v3, s[14:15]
	s_add_u32 s14, s14, 0x4000
	s_addc_u32 s15, s15, 0
	global_load_dword v25, v3, s[14:15]
	s_add_u32 s14, s14, 0x4000
	s_addc_u32 s15, s15, 0
	global_load_dword v26, v3, s[14:15]
	s_add_u32 s14, s14, 0x4000
	s_addc_u32 s15, s15, 0
	global_load_dword v27, v3, s[14:15]
	s_add_u32 s14, s14, 0x4000
	s_addc_u32 s15, s15, 0
	global_load_dword v28, v3, s[14:15]
	s_add_u32 s14, s14, 0x4000
	s_addc_u32 s15, s15, 0
	global_load_dword v29, v3, s[14:15]
	s_add_u32 s14, s14, 0x4000
	s_addc_u32 s15, s15, 0
	global_load_dword v30, v3, s[14:15]
	s_add_u32 s14, s14, 0x4000
	s_addc_u32 s15, s15, 0
	global_load_dword v31, v3, s[14:15]
	s_add_u32 s14, s14, 0x4000
	s_addc_u32 s15, s15, 0
	global_load_dword v32, v3, s[14:15]
	s_add_u32 s14, s14, 0x4000
	s_addc_u32 s15, s15, 0
	global_load_dword v33, v3, s[14:15]
	s_add_u32 s14, s14, 0x4000
	s_addc_u32 s15, s15, 0
	global_load_dword v34, v3, s[14:15]
	s_add_u32 s14, s14, 0x4000
	s_addc_u32 s15, s15, 0
	global_load_dword v35, v3, s[14:15]
	s_add_u32 s14, s14, 0x4000
	s_addc_u32 s15, s15, 0
	global_load_dword v36, v3, s[14:15]
	s_add_u32 s14, s14, 0x4000
	s_addc_u32 s15, s15, 0
	global_load_dword v37, v3, s[14:15]
	s_add_u32 s14, s14, 0x4000
	s_addc_u32 s15, s15, 0
	global_load_dword v38, v3, s[14:15]
	s_add_u32 s14, s14, 0x4000
	s_addc_u32 s15, s15, 0
	global_load_dword v39, v3, s[14:15]
	s_add_u32 s14, s14, 0x4000
	s_addc_u32 s15, s15, 0
	global_load_dword v40, v3, s[14:15]
	s_add_u32 s14, s14, 0x4000
	s_addc_u32 s15, s15, 0
	global_load_dword v41, v3, s[14:15]
	s_add_u32 s14, s14, 0x4000
	s_addc_u32 s15, s15, 0
	global_load_dword v42, v3, s[14:15]
	s_add_u32 s14, s14, 0x4000
	s_addc_u32 s15, s15, 0
	global_load_dword v43, v3, s[14:15]
	s_add_u32 s14, s14, 0x4000
	s_addc_u32 s15, s15, 0
	global_load_dword v44, v3, s[14:15]
	s_add_u32 s14, s14, 0x4000
	s_addc_u32 s15, s15, 0
	global_load_dword v45, v3, s[14:15]
	s_add_u32 s14, s14, 0x4000
	s_addc_u32 s15, s15, 0
	global_load_dword v46, v3, s[14:15]
	s_add_u32 s14, s14, 0x4000
	s_addc_u32 s15, s15, 0
	global_load_dword v47, v3, s[14:15]
	s_lshr_b32 s16, s12, 2
	s_mul_i32 s16, s16, 0x20
	s_add_u32 s16, s16, s11
	s_lshl_b32 s16, s16, 14
	s_and_b32 s17, s12, 3
	s_lshl_b32 s17, s17, 12
	s_add_u32 s16, s16, s17
	s_add_u32 s16, s6, s16
	s_addc_u32 s17, s7, 0
	s_waitcnt vmcnt(32)
	ds_write_b32 v4, v88
	ds_write_b32 v4, v89 offset:264
	ds_write_b32 v4, v90 offset:528
	ds_write_b32 v4, v91 offset:792
	ds_write_b32 v4, v92 offset:1056
	ds_write_b32 v4, v93 offset:1320
	ds_write_b32 v4, v94 offset:1584
	ds_write_b32 v4, v95 offset:1848
	ds_write_b32 v4, v96 offset:2112
	ds_write_b32 v4, v97 offset:2376
	ds_write_b32 v4, v98 offset:2640
	ds_write_b32 v4, v99 offset:2904
	ds_write_b32 v4, v100 offset:3168
	ds_write_b32 v4, v101 offset:3432
	ds_write_b32 v4, v102 offset:3696
	ds_write_b32 v4, v103 offset:3960
	ds_write_b32 v4, v104 offset:4224
	ds_write_b32 v4, v105 offset:4488
	ds_write_b32 v4, v106 offset:4752
	ds_write_b32 v4, v107 offset:5016
	ds_write_b32 v4, v108 offset:5280
	ds_write_b32 v4, v109 offset:5544
	ds_write_b32 v4, v110 offset:5808
	ds_write_b32 v4, v111 offset:6072
	ds_write_b32 v4, v112 offset:6336
	ds_write_b32 v4, v113 offset:6600
	ds_write_b32 v4, v114 offset:6864
	ds_write_b32 v4, v115 offset:7128
	ds_write_b32 v4, v116 offset:7392
	ds_write_b32 v4, v117 offset:7656
	ds_write_b32 v4, v118 offset:7920
	ds_write_b32 v4, v119 offset:8184
	s_waitcnt lgkmcnt(0)
	ds_read_b32 v48, v7
	ds_read_b32 v49, v7 offset:132
	ds_read_b32 v50, v7 offset:264
	ds_read_b32 v51, v7 offset:396
	ds_read_b32 v52, v7 offset:528
	ds_read_b32 v53, v7 offset:660
	ds_read_b32 v54, v7 offset:792
	ds_read_b32 v55, v7 offset:924
	ds_read_b32 v56, v7 offset:32
	ds_read_b32 v57, v7 offset:164
	ds_read_b32 v58, v7 offset:296
	ds_read_b32 v59, v7 offset:428
	ds_read_b32 v60, v7 offset:560
	ds_read_b32 v61, v7 offset:692
	ds_read_b32 v62, v7 offset:824
	ds_read_b32 v63, v7 offset:956
	ds_read_b32 v64, v7 offset:64
	ds_read_b32 v65, v7 offset:196
	ds_read_b32 v66, v7 offset:328
	ds_read_b32 v67, v7 offset:460
	ds_read_b32 v68, v7 offset:592
	ds_read_b32 v69, v7 offset:724
	ds_read_b32 v70, v7 offset:856
	ds_read_b32 v71, v7 offset:988
	ds_read_b32 v72, v7 offset:96
	ds_read_b32 v73, v7 offset:228
	ds_read_b32 v74, v7 offset:360
	ds_read_b32 v75, v7 offset:492
	ds_read_b32 v76, v7 offset:624
	ds_read_b32 v77, v7 offset:756
	ds_read_b32 v78, v7 offset:888
	ds_read_b32 v79, v7 offset:1020
	s_waitcnt lgkmcnt(0)
	v_cvt_pk_bf16_f32 v48, v48, v49
	v_cvt_pk_bf16_f32 v49, v50, v51
	v_cvt_pk_bf16_f32 v50, v52, v53
	v_cvt_pk_bf16_f32 v51, v54, v55
	global_store_dwordx4 v10, v[48:51], s[24:25]
	v_cvt_pk_bf16_f32 v56, v56, v57
	v_cvt_pk_bf16_f32 v57, v58, v59
	v_cvt_pk_bf16_f32 v58, v60, v61
	v_cvt_pk_bf16_f32 v59, v62, v63
	global_store_dwordx4 v10, v[56:59], s[24:25] offset:256
	v_cvt_pk_bf16_f32 v64, v64, v65
	v_cvt_pk_bf16_f32 v65, v66, v67
	v_cvt_pk_bf16_f32 v66, v68, v69
	v_cvt_pk_bf16_f32 v67, v70, v71
	global_store_dwordx4 v11, v[64:67], s[24:25] offset:512
	v_cvt_pk_bf16_f32 v72, v72, v73
	v_cvt_pk_bf16_f32 v73, v74, v75
	v_cvt_pk_bf16_f32 v74, v76, v77
	v_cvt_pk_bf16_f32 v75, v78, v79
	global_store_dwordx4 v11, v[72:75], s[24:25] offset:768
	s_branch .Ltc3b_loop

; __device__ __forceinline__ void tr_load(const float* W, int N, int item, int lane, float (&wv)[32]) {
;     const int nblk = N / 32, kb = item / nblk, nb = item % nblk, k0 = 64 * kb, n0 = 32 * nb;
; #pragma unroll
;     for (int i = 0; i < 32; ++i) { const int kk = 2 * i + (lane >> 5); wv[i] = __builtin_nontemporal_load(W + (size_t)(k0 + kk) * N + n0 + (lane & 31)); }
; }
; template <int MAP, bool HASG, bool PERMW>
; __device__ __forceinline__ void tr_store(int K, int N, bf16_t* WT, LAS float* scr, int item, int lane, const float* gk) {
;     const int nblk = N / 32, kb = item / nblk, nb = item % nblk, k0 = 64 * kb, n0 = 32 * nb;
;     asm volatile("s_waitcnt lgkmcnt(0)" ::: "memory");
;     const int c = lane & 7;
;     f32x4 g0 = {1.f, 1.f, 1.f, 1.f}, g1 = {1.f, 1.f, 1.f, 1.f};
;     if (HASG) { g0 = *(const f32x4*)(gk + k0 + 8 * c); g1 = *(const f32x4*)(gk + k0 + 8 * c + 4); }
; #pragma unroll
;     for (int j = 0; j < 4; ++j) { const int n = (lane >> 3) + 8 * j; const LAS float* s = scr + (8 * c) * 33 + n;
;         u32x4 o; o.x = pk2(s[0 * 33] * g0[0], s[1 * 33] * g0[1]); o.y = pk2(s[2 * 33] * g0[2], s[3 * 33] * g0[3]); o.z = pk2(s[4 * 33] * g1[0], s[5 * 33] * g1[1]); o.w = pk2(s[6 * 33] * g1[2], s[7 * 33] * g1[3]);
;         const int wr_ = rowmap<MAP>(n0 + n), slot_ = PERMW ? ((wr_ & ~31) + invperm32(wr_ & 31)) : wr_;
;         *(u32x4*)((char*)WT + tiled_off(slot_, k0 + 8 * c, K / 64)) = o; }
;     asm volatile("s_waitcnt lgkmcnt(0)" ::: "memory");
; }
; template <int MAP, bool HASG = false, bool PERMW = false>
; __device__ __forceinline__ void transpose_mat(const float* W, int K, int N, bf16_t* WT, LAS float* scr, int gw, int ngw, int lane, const float* gk = nullptr) {
;     const int nitems = (K / 64) * (N / 32);
;     int it = gw;
;     if (it >= nitems) return;
;     float wv[32];
;     tr_load(W, N, it, lane, wv);
;     for (;;) {
;         __builtin_amdgcn_sched_barrier(0);
; #pragma unroll
;         for (int i = 0; i < 32; ++i) { const int kk = 2 * i + (lane >> 5); scr[kk * 33 + (lane & 31)] = wv[i]; }
;         __builtin_amdgcn_sched_barrier(0);
;         const int nx = it + ngw;
;         if (nx < nitems) tr_load(W, N, nx, lane, wv);
;         __builtin_amdgcn_sched_barrier(0);
;         tr_store<MAP, HASG, PERMW>(K, N, WT, scr, it, lane, gk);
;         if (nx >= nitems) break;
;         it = nx;
.Ltc3b_exit:
	v_readlane_b32 s4, v254, 2
	v_readlane_b32 s5, v254, 3
	s_nop 3
	s_and_b32 s6, s60, 0x1000000
	s_add_u32 s4, s4, s6
	s_addc_u32 s5, s5, 0
	s_add_u32 s6, s76, 0x8200000
	s_addc_u32 s7, s77, 0
	s_mov_b32 s9, s18
	s_cmpk_ge_u32 s9, 0x800
	s_cbranch_scc1 .Ltc3c_exit
	s_lshr_b32 s11, s9, 6
	s_and_b32 s12, s9, 63
	s_lshl_b32 s13, s11, 19
	s_lshl_b32 s14, s12, 7
	s_add_u32 s13, s13, s14
	s_add_u32 s14, s4, s13
	s_addc_u32 s15, s5, 0
	global_load_dword v16, v3, s[14:15]
	s_add_u32 s14, s14, 0x4000
	s_addc_u32 s15, s15, 0
	global_load_dword v17, v3, s[14:15]
	s_add_u32 s14, s14, 0x4000
	s_addc_u32 s15, s15, 0
	global_load_dword v18, v3, s[14:15]
	s_add_u32 s14, s14, 0x4000
	s_addc_u32 s15, s15, 0
	global_load_dword v19, v3, s[14:15]
	s_add_u32 s14, s14, 0x4000
	s_addc_u32 s15, s15, 0
	global_load_dword v20, v3, s[14:15]
	s_add_u32 s14, s14, 0x4000
	s_addc_u32 s15, s15, 0
	global_load_dword v21, v3, s[14:15]
	s_add_u32 s14, s14, 0x4000
	s_addc_u32 s15, s15, 0
	global_load_dword v22, v3, s[14:15]
	s_add_u32 s14, s14, 0x4000
	s_addc_u32 s15, s15, 0
	global_load_dword v23, v3, s[14:15]
	s_add_u32 s14, s14, 0x4000
	s_addc_u32 s15, s15, 0
	global_load_dword v24, v3, s[14:15]
	s_add_u32 s14, s14, 0x4000
	s_addc_u32 s15, s15, 0
	global_load_dword v25, v3, s[14:15]
	s_add_u32 s14, s14, 0x4000
	s_addc_u32 s15, s15, 0
	global_load_dword v26, v3, s[14:15]
	s_add_u32 s14, s14, 0x4000
	s_addc_u32 s15, s15, 0
	global_load_dword v27, v3, s[14:15]
	s_add_u32 s14, s14, 0x4000
	s_addc_u32 s15, s15, 0
	global_load_dword v28, v3, s[14:15]
	s_add_u32 s14, s14, 0x4000
	s_addc_u32 s15, s15, 0
	global_load_dword v29, v3, s[14:15]
	s_add_u32 s14, s14, 0x4000
	s_addc_u32 s15, s15, 0
	global_load_dword v30, v3, s[14:15]
	s_add_u32 s14, s14, 0x4000
	s_addc_u32 s15, s15, 0
	global_load_dword v31, v3, s[14:15]
	s_add_u32 s14, s14, 0x4000
	s_addc_u32 s15, s15, 0
	global_load_dword v32, v3, s[14:15]
	s_add_u32 s14, s14, 0x4000
	s_addc_u32 s15, s15, 0
	global_load_dword v33, v3, s[14:15]
	s_add_u32 s14, s14, 0x4000
	s_addc_u32 s15, s15, 0
	global_load_dword v34, v3, s[14:15]
	s_add_u32 s14, s14, 0x4000
	s_addc_u32 s15, s15, 0
	global_load_dword v35, v3, s[14:15]
	s_add_u32 s14, s14, 0x4000
	s_addc_u32 s15, s15, 0
	global_load_dword v36, v3, s[14:15]
	s_add_u32 s14, s14, 0x4000
	s_addc_u32 s15, s15, 0
	global_load_dword v37, v3, s[14:15]
	s_add_u32 s14, s14, 0x4000
	s_addc_u32 s15, s15, 0
	global_load_dword v38, v3, s[14:15]
	s_add_u32 s14, s14, 0x4000
	s_addc_u32 s15, s15, 0
	global_load_dword v39, v3, s[14:15]
	s_add_u32 s14, s14, 0x4000
	s_addc_u32 s15, s15, 0
	global_load_dword v40, v3, s[14:15]
	s_add_u32 s14, s14, 0x4000
	s_addc_u32 s15, s15, 0
	global_load_dword v41, v3, s[14:15]
	s_add_u32 s14, s14, 0x4000
	s_addc_u32 s15, s15, 0
	global_load_dword v42, v3, s[14:15]
	s_add_u32 s14, s14, 0x4000
	s_addc_u32 s15, s15, 0
	global_load_dword v43, v3, s[14:15]
	s_add_u32 s14, s14, 0x4000
	s_addc_u32 s15, s15, 0
	global_load_dword v44, v3, s[14:15]
	s_add_u32 s14, s14, 0x4000
	s_addc_u32 s15, s15, 0
	global_load_dword v45, v3, s[14:15]
	s_add_u32 s14, s14, 0x4000
	s_addc_u32 s15, s15, 0
	global_load_dword v46, v3, s[14:15]
	s_add_u32 s14, s14, 0x4000
	s_addc_u32 s15, s15, 0
	global_load_dword v47, v3, s[14:15]
	s_lshr_b32 s16, s12, 2
	s_mul_i32 s16, s16, 0x20
	s_add_u32 s16, s16, s11
	s_lshl_b32 s16, s16, 14
	s_and_b32 s17, s12, 3
	s_lshl_b32 s17, s17, 12
	s_add_u32 s16, s16, s17
	s_add_u32 s16, s6, s16
	s_addc_u32 s17, s7, 0
.Ltc3c_loop:
	s_add_u32 s9, s9, s19
	s_cmpk_ge_u32 s9, 0x800
	s_cbranch_scc1 .Ltc3c_lastA
	s_lshr_b32 s11, s9, 6
	s_and_b32 s12, s9, 63
	s_lshl_b32 s13, s11, 19
	s_lshl_b32 s14, s12, 7
	s_add_u32 s13, s13, s14
	s_add_u32 s14, s4, s13
	s_addc_u32 s15, s5, 0
	global_load_dword v88, v3, s[14:15]
	s_add_u32 s14, s14, 0x4000
	s_addc_u32 s15, s15, 0
	global_load_dword v89, v3, s[14:15]
	s_add_u32 s14, s14, 0x4000
	s_addc_u32 s15, s15, 0
	global_load_dword v90, v3, s[14:15]
	s_add_u32 s14, s14, 0x4000
	s_addc_u32 s15, s15, 0
	global_load_dword v91, v3, s[14:15]
	s_add_u32 s14, s14, 0x4000
	s_addc_u32 s15, s15, 0
	global_load_dword v92, v3, s[14:15]
	s_add_u32 s14, s14, 0x4000
	s_addc_u32 s15, s15, 0
	global_load_dword v93, v3, s[14:15]
	s_add_u32 s14, s14, 0x4000
	s_addc_u32 s15, s15, 0
	global_load_dword v94, v3, s[14:15]
	s_add_u32 s14, s14, 0x4000
	s_addc_u32 s15, s15, 0
	global_load_dword v95, v3, s[14:15]
	s_add_u32 s14, s14, 0x4000
	s_addc_u32 s15, s15, 0
	global_load_dword v96, v3, s[14:15]
	s_add_u32 s14, s14, 0x4000
	s_addc_u32 s15, s15, 0
	global_load_dword v97, v3, s[14:15]
	s_add_u32 s14, s14, 0x4000
	s_addc_u32 s15, s15, 0
	global_load_dword v98, v3, s[14:15]
	s_add_u32 s14, s14, 0x4000
	s_addc_u32 s15, s15, 0
	global_load_dword v99, v3, s[14:15]
	s_add_u32 s14, s14, 0x4000
	s_addc_u32 s15, s15, 0
	global_load_dword v100, v3, s[14:15]
	s_add_u32 s14, s14, 0x4000
	s_addc_u32 s15, s15, 0
	global_load_dword v101, v3, s[14:15]
	s_add_u32 s14, s14, 0x4000
	s_addc_u32 s15, s15, 0
	global_load_dword v102, v3, s[14:15]
	s_add_u32 s14, s14, 0x4000
	s_addc_u32 s15, s15, 0
	global_load_dword v103, v3, s[14:15]
	s_add_u32 s14, s14, 0x4000
	s_addc_u32 s15, s15, 0
	global_load_dword v104, v3, s[14:15]
	s_add_u32 s14, s14, 0x4000
	s_addc_u32 s15, s15, 0
	global_load_dword v105, v3, s[14:15]
	s_add_u32 s14, s14, 0x4000
	s_addc_u32 s15, s15, 0
	global_load_dword v106, v3, s[14:15]
	s_add_u32 s14, s14, 0x4000
	s_addc_u32 s15, s15, 0
	global_load_dword v107, v3, s[14:15]
	s_add_u32 s14, s14, 0x4000
	s_addc_u32 s15, s15, 0
	global_load_dword v108, v3, s[14:15]
	s_add_u32 s14, s14, 0x4000
	s_addc_u32 s15, s15, 0
	global_load_dword v109, v3, s[14:15]
	s_add_u32 s14, s14, 0x4000
	s_addc_u32 s15, s15, 0
	global_load_dword v110, v3, s[14:15]
	s_add_u32 s14, s14, 0x4000
	s_addc_u32 s15, s15, 0
	global_load_dword v111, v3, s[14:15]
	s_add_u32 s14, s14, 0x4000
	s_addc_u32 s15, s15, 0
	global_load_dword v112, v3, s[14:15]
	s_add_u32 s14, s14, 0x4000
	s_addc_u32 s15, s15, 0
	global_load_dword v113, v3, s[14:15]
	s_add_u32 s14, s14, 0x4000
	s_addc_u32 s15, s15, 0
	global_load_dword v114, v3, s[14:15]
	s_add_u32 s14, s14, 0x4000
	s_addc_u32 s15, s15, 0
	global_load_dword v115, v3, s[14:15]
	s_add_u32 s14, s14, 0x4000
	s_addc_u32 s15, s15, 0
	global_load_dword v116, v3, s[14:15]
	s_add_u32 s14, s14, 0x4000
	s_addc_u32 s15, s15, 0
	global_load_dword v117, v3, s[14:15]
	s_add_u32 s14, s14, 0x4000
	s_addc_u32 s15, s15, 0
	global_load_dword v118, v3, s[14:15]
	s_add_u32 s14, s14, 0x4000
	s_addc_u32 s15, s15, 0
	global_load_dword v119, v3, s[14:15]
	s_lshr_b32 s24, s12, 2
	s_mul_i32 s24, s24, 0x20
	s_add_u32 s24, s24, s11
	s_lshl_b32 s24, s24, 14
	s_and_b32 s25, s12, 3
	s_lshl_b32 s25, s25, 12
	s_add_u32 s24, s24, s25
	s_add_u32 s24, s6, s24
	s_addc_u32 s25, s7, 0
	s_waitcnt vmcnt(32)
; #define LAS __attribute__((address_space(3)))
; __device__ __forceinline__ unsigned pk2(float lo, float hi) { f32x2 f = {lo, hi}; bf16x2_t b = __builtin_convertvector(f, bf16x2_t); return __builtin_bit_cast(unsigned, b); }
; template <int MAP, bool HASG, bool PERMW>
; __device__ __forceinline__ void tr_store(int K, int N, bf16_t* WT, LAS float* scr, int item, int lane, const float* gk) {
;     const int nblk = N / 32, kb = item / nblk, nb = item % nblk, k0 = 64 * kb, n0 = 32 * nb;
;     asm volatile("s_waitcnt lgkmcnt(0)" ::: "memory");
;     const int c = lane & 7;
;     f32x4 g0 = {1.f, 1.f, 1.f, 1.f}, g1 = {1.f, 1.f, 1.f, 1.f};
;     if (HASG) { g0 = *(const f32x4*)(gk + k0 + 8 * c); g1 = *(const f32x4*)(gk + k0 + 8 * c + 4); }
; #pragma unroll
;     for (int j = 0; j < 4; ++j) { const int n = (lane >> 3) + 8 * j; const LAS float* s = scr + (8 * c) * 33 + n;
;         u32x4 o; o.x = pk2(s[0 * 33] * g0[0], s[1 * 33] * g0[1]); o.y = pk2(s[2 * 33] * g0[2], s[3 * 33] * g0[3]); o.z = pk2(s[4 * 33] * g1[0], s[5 * 33] * g1[1]); o.w = pk2(s[6 * 33] * g1[2], s[7 * 33] * g1[3]);
;         const int wr_ = rowmap<MAP>(n0 + n), slot_ = PERMW ? ((wr_ & ~31) + invperm32(wr_ & 31)) : wr_;
;         *(u32x4*)((char*)WT + tiled_off(slot_, k0 + 8 * c, K / 64)) = o; }
;     asm volatile("s_waitcnt lgkmcnt(0)" ::: "memory");
; }
; template <int MAP, bool HASG = false, bool PERMW = false>
; __device__ __forceinline__ void transpose_mat(const float* W, int K, int N, bf16_t* WT, LAS float* scr, int gw, int ngw, int lane, const float* gk = nullptr) {
;     ...
;         for (int i = 0; i < 32; ++i) { const int kk = 2 * i + (lane >> 5); scr[kk * 33 + (lane & 31)] = wv[i]; }
	ds_write_b32 v4, v16
	ds_write_b32 v4, v17 offset:264
	ds_write_b32 v4, v18 offset:528
	ds_write_b32 v4, v19 offset:792
	ds_write_b32 v4, v20 offset:1056
	ds_write_b32 v4, v21 offset:1320
	ds_write_b32 v4, v22 offset:1584
	ds_write_b32 v4, v23 offset:1848
	ds_write_b32 v4, v24 offset:2112
	ds_write_b32 v4, v25 offset:2376
	ds_write_b32 v4, v26 offset:2640
	ds_write_b32 v4, v27 offset:2904
	ds_write_b32 v4, v28 offset:3168
	ds_write_b32 v4, v29 offset:3432
	ds_write_b32 v4, v30 offset:3696
	ds_write_b32 v4, v31 offset:3960
	ds_write_b32 v4, v32 offset:4224
	ds_write_b32 v4, v33 offset:4488
	ds_write_b32 v4, v34 offset:4752
	ds_write_b32 v4, v35 offset:5016
	ds_write_b32 v4, v36 offset:5280
	ds_write_b32 v4, v37 offset:5544
	ds_write_b32 v4, v38 offset:5808
	ds_write_b32 v4, v39 offset:6072
	ds_write_b32 v4, v40 offset:6336
	ds_write_b32 v4, v41 offset:6600
	ds_write_b32 v4, v42 offset:6864
	ds_write_b32 v4, v43 offset:7128
	ds_write_b32 v4, v44 offset:7392
	ds_write_b32 v4, v45 offset:7656
	ds_write_b32 v4, v46 offset:7920
	ds_write_b32 v4, v47 offset:8184
	s_waitcnt lgkmcnt(0)
	ds_read_b32 v48, v7
	ds_read_b32 v49, v7 offset:132
	ds_read_b32 v50, v7 offset:264
	ds_read_b32 v51, v7 offset:396
	ds_read_b32 v52, v7 offset:528
	ds_read_b32 v53, v7 offset:660
	ds_read_b32 v54, v7 offset:792
	ds_read_b32 v55, v7 offset:924
	ds_read_b32 v56, v7 offset:32
	ds_read_b32 v57, v7 offset:164
	ds_read_b32 v58, v7 offset:296
	ds_read_b32 v59, v7 offset:428
	ds_read_b32 v60, v7 offset:560
	ds_read_b32 v61, v7 offset:692
	ds_read_b32 v62, v7 offset:824
	ds_read_b32 v63, v7 offset:956
	ds_read_b32 v64, v7 offset:64
	ds_read_b32 v65, v7 offset:196
	ds_read_b32 v66, v7 offset:328
	ds_read_b32 v67, v7 offset:460
	ds_read_b32 v68, v7 offset:592
	ds_read_b32 v69, v7 offset:724
	ds_read_b32 v70, v7 offset:856
	ds_read_b32 v71, v7 offset:988
	ds_read_b32 v72, v7 offset:96
	ds_read_b32 v73, v7 offset:228
	ds_read_b32 v74, v7 offset:360
	ds_read_b32 v75, v7 offset:492
	ds_read_b32 v76, v7 offset:624
	ds_read_b32 v77, v7 offset:756
	ds_read_b32 v78, v7 offset:888
	ds_read_b32 v79, v7 offset:1020
	s_waitcnt lgkmcnt(0)
	v_cvt_pk_bf16_f32 v48, v48, v49
	v_cvt_pk_bf16_f32 v49, v50, v51
	v_cvt_pk_bf16_f32 v50, v52, v53
	v_cvt_pk_bf16_f32 v51, v54, v55
	global_store_dwordx4 v8, v[48:51], s[16:17]
	v_cvt_pk_bf16_f32 v56, v56, v57
	v_cvt_pk_bf16_f32 v57, v58, v59
	v_cvt_pk_bf16_f32 v58, v60, v61
	v_cvt_pk_bf16_f32 v59, v62, v63
	global_store_dwordx4 v9, v[56:59], s[16:17]
	v_cvt_pk_bf16_f32 v64, v64, v65
	v_cvt_pk_bf16_f32 v65, v66, v67
	v_cvt_pk_bf16_f32 v66, v68, v69
	v_cvt_pk_bf16_f32 v67, v70, v71
	global_store_dwordx4 v8, v[64:67], s[16:17] offset:2048
	v_cvt_pk_bf16_f32 v72, v72, v73
	v_cvt_pk_bf16_f32 v73, v74, v75
	v_cvt_pk_bf16_f32 v74, v76, v77
	v_cvt_pk_bf16_f32 v75, v78, v79
	global_store_dwordx4 v9, v[72:75], s[16:17] offset:2048
	s_add_u32 s9, s9, s19
	s_cmpk_ge_u32 s9, 0x800
	s_cbranch_scc1 .Ltc3c_lastB
; __device__ __forceinline__ void tr_load(const float* W, int N, int item, int lane, float (&wv)[32]) {
;     const int nblk = N / 32, kb = item / nblk, nb = item % nblk, k0 = 64 * kb, n0 = 32 * nb;
; #pragma unroll
;     for (int i = 0; i < 32; ++i) { const int kk = 2 * i + (lane >> 5); wv[i] = __builtin_nontemporal_load(W + (size_t)(k0 + kk) * N + n0 + (lane & 31)); }
; }
; template <int MAP, bool HASG, bool PERMW>
; __device__ __forceinline__ void tr_store(int K, int N, bf16_t* WT, LAS float* scr, int item, int lane, const float* gk) {
;     const int nblk = N / 32, kb = item / nblk, nb = item % nblk, k0 = 64 * kb, n0 = 32 * nb;
;     asm volatile("s_waitcnt lgkmcnt(0)" ::: "memory");
;     const int c = lane & 7;
;     f32x4 g0 = {1.f, 1.f, 1.f, 1.f}, g1 = {1.f, 1.f, 1.f, 1.f};
;     if (HASG) { g0 = *(const f32x4*)(gk + k0 + 8 * c); g1 = *(const f32x4*)(gk + k0 + 8 * c + 4); }
; #pragma unroll
;     for (int j = 0; j < 4; ++j) { const int n = (lane >> 3) + 8 * j; const LAS float* s = scr + (8 * c) * 33 + n;
;         u32x4 o; o.x = pk2(s[0 * 33] * g0[0], s[1 * 33] * g0[1]); o.y = pk2(s[2 * 33] * g0[2], s[3 * 33] * g0[3]); o.z = pk2(s[4 * 33] * g1[0], s[5 * 33] * g1[1]); o.w = pk2(s[6 * 33] * g1[2], s[7 * 33] * g1[3]);
;         const int wr_ = rowmap<MAP>(n0 + n), slot_ = PERMW ? ((wr_ & ~31) + invperm32(wr_ & 31)) : wr_;
;         *(u32x4*)((char*)WT + tiled_off(slot_, k0 + 8 * c, K / 64)) = o; }
;     asm volatile("s_waitcnt lgkmcnt(0)" ::: "memory");
; }
; template <int MAP, bool HASG = false, bool PERMW = false>
; __device__ __forceinline__ void transpose_mat(const float* W, int K, int N, bf16_t* WT, LAS float* scr, int gw, int ngw, int lane, const float* gk = nullptr) {
;     const int nitems = (K / 64) * (N / 32);
;     int it = gw;
;     if (it >= nitems) return;
;     float wv[32];
;     tr_load(W, N, it, lane, wv);
;     for (;;) {
;         __builtin_amdgcn_sched_barrier(0);
; #pragma unroll
;         for (int i = 0; i < 32; ++i) { const int kk = 2 * i + (lane >> 5); scr[kk * 33 + (lane & 31)] = wv[i]; }
;         __builtin_amdgcn_sched_barrier(0);
;         const int nx = it + ngw;
;         if (nx < nitems) tr_load(W, N, nx, lane, wv);
;         __builtin_amdgcn_sched_barrier(0);
;         tr_store<MAP, HASG, PERMW>(K, N, WT, scr, it, lane, gk);
;         if (nx >= nitems) break;
;         it = nx;
	s_lshr_b32 s11, s9, 6
	s_and_b32 s12, s9, 63
	s_lshl_b32 s13, s11, 19
	s_lshl_b32 s14, s12, 7
	s_add_u32 s13, s13, s14
	s_add_u32 s14, s4, s13
	s_addc_u32 s15, s5, 0
	global_load_dword v16, v3, s[14:15]
	s_add_u32 s14, s14, 0x4000
	s_addc_u32 s15, s15, 0
	global_load_dword v17, v3, s[14:15]
	s_add_u32 s14, s14, 0x4000
	s_addc_u32 s15, s15, 0
	global_load_dword v18, v3, s[14:15]
	s_add_u32 s14, s14, 0x4000
	s_addc_u32 s15, s15, 0
	global_load_dword v19, v3, s[14:15]
	s_add_u32 s14, s14, 0x4000
	s_addc_u32 s15, s15, 0
	global_load_dword v20, v3, s[14:15]
	s_add_u32 s14, s14, 0x4000
	s_addc_u32 s15, s15, 0
	global_load_dword v21, v3, s[14:15]
	s_add_u32 s14, s14, 0x4000
	s_addc_u32 s15, s15, 0
	global_load_dword v22, v3, s[14:15]
	s_add_u32 s14, s14, 0x4000
	s_addc_u32 s15, s15, 0
	global_load_dword v23, v3, s[14:15]
	s_add_u32 s14, s14, 0x4000
	s_addc_u32 s15, s15, 0
	global_load_dword v24, v3, s[14:15]
	s_add_u32 s14, s14, 0x4000
	s_addc_u32 s15, s15, 0
	global_load_dword v25, v3, s[14:15]
	s_add_u32 s14, s14, 0x4000
	s_addc_u32 s15, s15, 0
	global_load_dword v26, v3, s[14:15]
	s_add_u32 s14, s14, 0x4000
	s_addc_u32 s15, s15, 0
	global_load_dword v27, v3, s[14:15]
	s_add_u32 s14, s14, 0x4000
	s_addc_u32 s15, s15, 0
	global_load_dword v28, v3, s[14:15]
	s_add_u32 s14, s14, 0x4000
	s_addc_u32 s15, s15, 0
	global_load_dword v29, v3, s[14:15]
	s_add_u32 s14, s14, 0x4000
	s_addc_u32 s15, s15, 0
	global_load_dword v30, v3, s[14:15]
	s_add_u32 s14, s14, 0x4000
	s_addc_u32 s15, s15, 0
	global_load_dword v31, v3, s[14:15]
	s_add_u32 s14, s14, 0x4000
	s_addc_u32 s15, s15, 0
	global_load_dword v32, v3, s[14:15]
	s_add_u32 s14, s14, 0x4000
	s_addc_u32 s15, s15, 0
	global_load_dword v33, v3, s[14:15]
	s_add_u32 s14, s14, 0x4000
	s_addc_u32 s15, s15, 0
	global_load_dword v34, v3, s[14:15]
	s_add_u32 s14, s14, 0x4000
	s_addc_u32 s15, s15, 0
	global_load_dword v35, v3, s[14:15]
	s_add_u32 s14, s14, 0x4000
	s_addc_u32 s15, s15, 0
	global_load_dword v36, v3, s[14:15]
	s_add_u32 s14, s14, 0x4000
	s_addc_u32 s15, s15, 0
	global_load_dword v37, v3, s[14:15]
	s_add_u32 s14, s14, 0x4000
	s_addc_u32 s15, s15, 0
	global_load_dword v38, v3, s[14:15]
	s_add_u32 s14, s14, 0x4000
	s_addc_u32 s15, s15, 0
	global_load_dword v39, v3, s[14:15]
	s_add_u32 s14, s14, 0x4000
	s_addc_u32 s15, s15, 0
	global_load_dword v40, v3, s[14:15]
	s_add_u32 s14, s14, 0x4000
	s_addc_u32 s15, s15, 0
	global_load_dword v41, v3, s[14:15]
	s_add_u32 s14, s14, 0x4000
	s_addc_u32 s15, s15, 0
	global_load_dword v42, v3, s[14:15]
	s_add_u32 s14, s14, 0x4000
	s_addc_u32 s15, s15, 0
	global_load_dword v43, v3, s[14:15]
	s_add_u32 s14, s14, 0x4000
	s_addc_u32 s15, s15, 0
	global_load_dword v44, v3, s[14:15]
	s_add_u32 s14, s14, 0x4000
	s_addc_u32 s15, s15, 0
	global_load_dword v45, v3, s[14:15]
	s_add_u32 s14, s14, 0x4000
	s_addc_u32 s15, s15, 0
	global_load_dword v46, v3, s[14:15]
	s_add_u32 s14, s14, 0x4000
	s_addc_u32 s15, s15, 0
	global_load_dword v47, v3, s[14:15]
	s_lshr_b32 s16, s12, 2
	s_mul_i32 s16, s16, 0x20
	s_add_u32 s16, s16, s11
	s_lshl_b32 s16, s16, 14
	s_and_b32 s17, s12, 3
	s_lshl_b32 s17, s17, 12
	s_add_u32 s16, s16, s17
	s_add_u32 s16, s6, s16
	s_addc_u32 s17, s7, 0
	s_waitcnt vmcnt(32)
	ds_write_b32 v4, v88
	ds_write_b32 v4, v89 offset:264
	ds_write_b32 v4, v90 offset:528
	ds_write_b32 v4, v91 offset:792
	ds_write_b32 v4, v92 offset:1056
	ds_write_b32 v4, v93 offset:1320
	ds_write_b32 v4, v94 offset:1584
	ds_write_b32 v4, v95 offset:1848
	ds_write_b32 v4, v96 offset:2112
	ds_write_b32 v4, v97 offset:2376
	ds_write_b32 v4, v98 offset:2640
	ds_write_b32 v4, v99 offset:2904
	ds_write_b32 v4, v100 offset:3168
	ds_write_b32 v4, v101 offset:3432
	ds_write_b32 v4, v102 offset:3696
	ds_write_b32 v4, v103 offset:3960
	ds_write_b32 v4, v104 offset:4224
	ds_write_b32 v4, v105 offset:4488
	ds_write_b32 v4, v106 offset:4752
	ds_write_b32 v4, v107 offset:5016
	ds_write_b32 v4, v108 offset:5280
	ds_write_b32 v4, v109 offset:5544
	ds_write_b32 v4, v110 offset:5808
	ds_write_b32 v4, v111 offset:6072
	ds_write_b32 v4, v112 offset:6336
	ds_write_b32 v4, v113 offset:6600
	ds_write_b32 v4, v114 offset:6864
	ds_write_b32 v4, v115 offset:7128
	ds_write_b32 v4, v116 offset:7392
	ds_write_b32 v4, v117 offset:7656
	ds_write_b32 v4, v118 offset:7920
	ds_write_b32 v4, v119 offset:8184
	s_waitcnt lgkmcnt(0)
	ds_read_b32 v48, v7
	ds_read_b32 v49, v7 offset:132
	ds_read_b32 v50, v7 offset:264
	ds_read_b32 v51, v7 offset:396
	ds_read_b32 v52, v7 offset:528
	ds_read_b32 v53, v7 offset:660
	ds_read_b32 v54, v7 offset:792
	ds_read_b32 v55, v7 offset:924
	ds_read_b32 v56, v7 offset:32
	ds_read_b32 v57, v7 offset:164
	ds_read_b32 v58, v7 offset:296
	ds_read_b32 v59, v7 offset:428
	ds_read_b32 v60, v7 offset:560
	ds_read_b32 v61, v7 offset:692
	ds_read_b32 v62, v7 offset:824
	ds_read_b32 v63, v7 offset:956
	ds_read_b32 v64, v7 offset:64
	ds_read_b32 v65, v7 offset:196
	ds_read_b32 v66, v7 offset:328
	ds_read_b32 v67, v7 offset:460
	ds_read_b32 v68, v7 offset:592
	ds_read_b32 v69, v7 offset:724
	ds_read_b32 v70, v7 offset:856
	ds_read_b32 v71, v7 offset:988
	ds_read_b32 v72, v7 offset:96
	ds_read_b32 v73, v7 offset:228
	ds_read_b32 v74, v7 offset:360
	ds_read_b32 v75, v7 offset:492
	ds_read_b32 v76, v7 offset:624
	ds_read_b32 v77, v7 offset:756
	ds_read_b32 v78, v7 offset:888
	ds_read_b32 v79, v7 offset:1020
	s_waitcnt lgkmcnt(0)
	v_cvt_pk_bf16_f32 v48, v48, v49
	v_cvt_pk_bf16_f32 v49, v50, v51
	v_cvt_pk_bf16_f32 v50, v52, v53
	v_cvt_pk_bf16_f32 v51, v54, v55
	global_store_dwordx4 v8, v[48:51], s[24:25]
	v_cvt_pk_bf16_f32 v56, v56, v57
	v_cvt_pk_bf16_f32 v57, v58, v59
	v_cvt_pk_bf16_f32 v58, v60, v61
	v_cvt_pk_bf16_f32 v59, v62, v63
	global_store_dwordx4 v9, v[56:59], s[24:25]
	v_cvt_pk_bf16_f32 v64, v64, v65
	v_cvt_pk_bf16_f32 v65, v66, v67
	v_cvt_pk_bf16_f32 v66, v68, v69
	v_cvt_pk_bf16_f32 v67, v70, v71
	global_store_dwordx4 v8, v[64:67], s[24:25] offset:2048
	v_cvt_pk_bf16_f32 v72, v72, v73
	v_cvt_pk_bf16_f32 v73, v74, v75
	v_cvt_pk_bf16_f32 v74, v76, v77
	v_cvt_pk_bf16_f32 v75, v78, v79
	global_store_dwordx4 v9, v[72:75], s[24:25] offset:2048
	s_branch .Ltc3c_loop

; __device__ __forceinline__ void tr_load(const float* W, int N, int item, int lane, float (&wv)[32]) {
;     const int nblk = N / 32, kb = item / nblk, nb = item % nblk, k0 = 64 * kb, n0 = 32 * nb;
; #pragma unroll
;     for (int i = 0; i < 32; ++i) { const int kk = 2 * i + (lane >> 5); wv[i] = __builtin_nontemporal_load(W + (size_t)(k0 + kk) * N + n0 + (lane & 31)); }
; }
; template <int MAP, bool HASG, bool PERMW>
; __device__ __forceinline__ void tr_store(int K, int N, bf16_t* WT, LAS float* scr, int item, int lane, const float* gk) {
;     const int nblk = N / 32, kb = item / nblk, nb = item % nblk, k0 = 64 * kb, n0 = 32 * nb;
;     asm volatile("s_waitcnt lgkmcnt(0)" ::: "memory");
;     const int c = lane & 7;
;     f32x4 g0 = {1.f, 1.f, 1.f, 1.f}, g1 = {1.f, 1.f, 1.f, 1.f};
;     if (HASG) { g0 = *(const f32x4*)(gk + k0 + 8 * c); g1 = *(const f32x4*)(gk + k0 + 8 * c + 4); }
; #pragma unroll
;     for (int j = 0; j < 4; ++j) { const int n = (lane >> 3) + 8 * j; const LAS float* s = scr + (8 * c) * 33 + n;
;         u32x4 o; o.x = pk2(s[0 * 33] * g0[0], s[1 * 33] * g0[1]); o.y = pk2(s[2 * 33] * g0[2], s[3 * 33] * g0[3]); o.z = pk2(s[4 * 33] * g1[0], s[5 * 33] * g1[1]); o.w = pk2(s[6 * 33] * g1[2], s[7 * 33] * g1[3]);
;         const int wr_ = rowmap<MAP>(n0 + n), slot_ = PERMW ? ((wr_ & ~31) + invperm32(wr_ & 31)) : wr_;
;         *(u32x4*)((char*)WT + tiled_off(slot_, k0 + 8 * c, K / 64)) = o; }
;     asm volatile("s_waitcnt lgkmcnt(0)" ::: "memory");
; }
; template <int MAP, bool HASG = false, bool PERMW = false>
; __device__ __forceinline__ void transpose_mat(const float* W, int K, int N, bf16_t* WT, LAS float* scr, int gw, int ngw, int lane, const float* gk = nullptr) {
;     const int nitems = (K / 64) * (N / 32);
;     int it = gw;
;     if (it >= nitems) return;
;     float wv[32];
;     tr_load(W, N, it, lane, wv);
;     for (;;) {
;         __builtin_amdgcn_sched_barrier(0);
; #pragma unroll
;         for (int i = 0; i < 32; ++i) { const int kk = 2 * i + (lane >> 5); scr[kk * 33 + (lane & 31)] = wv[i]; }
;         __builtin_amdgcn_sched_barrier(0);
;         const int nx = it + ngw;
;         if (nx < nitems) tr_load(W, N, nx, lane, wv);
;         __builtin_amdgcn_sched_barrier(0);
;         tr_store<MAP, HASG, PERMW>(K, N, WT, scr, it, lane, gk);
;         if (nx >= nitems) break;
;         it = nx;
.Ltc3c_exit:
	v_readlane_b32 s4, v254, 6
	v_readlane_b32 s5, v254, 7
	v_readlane_b32 s20, v254, 4
	v_readlane_b32 s21, v254, 5
	s_nop 3
	s_and_b32 s6, s60, 0x2c00000
	s_add_u32 s4, s4, s6
	s_addc_u32 s5, s5, 0
	s_and_b32 s6, s60, 0x2000
	s_add_u32 s20, s20, s6
	s_addc_u32 s21, s21, 0
	s_add_u32 s6, s76, 0x8a00000
	s_addc_u32 s7, s77, 0
	s_mov_b32 s9, s18
	s_cmpk_ge_u32 s9, 0x1600
	s_cbranch_scc1 .Ltc3e_exit
	s_mul_hi_u32 s11, s9, 0x2e8ba2e9
	s_lshr_b32 s11, s11, 5
	s_mul_i32 s12, s11, 0xb0
	s_sub_u32 s12, s9, s12
	s_mul_i32 s13, s11, 0x160000
	s_lshl_b32 s14, s12, 7
	s_add_u32 s13, s13, s14
	s_add_u32 s14, s4, s13
	s_addc_u32 s15, s5, 0
	global_load_dword v16, v15, s[14:15]
	s_add_u32 s14, s14, 0xb000
	s_addc_u32 s15, s15, 0
	global_load_dword v17, v15, s[14:15]
	s_add_u32 s14, s14, 0xb000
	s_addc_u32 s15, s15, 0
	global_load_dword v18, v15, s[14:15]
	s_add_u32 s14, s14, 0xb000
	s_addc_u32 s15, s15, 0
	global_load_dword v19, v15, s[14:15]
	s_add_u32 s14, s14, 0xb000
	s_addc_u32 s15, s15, 0
	global_load_dword v20, v15, s[14:15]
	s_add_u32 s14, s14, 0xb000
	s_addc_u32 s15, s15, 0
	global_load_dword v21, v15, s[14:15]
	s_add_u32 s14, s14, 0xb000
	s_addc_u32 s15, s15, 0
	global_load_dword v22, v15, s[14:15]
	s_add_u32 s14, s14, 0xb000
	s_addc_u32 s15, s15, 0
	global_load_dword v23, v15, s[14:15]
	s_add_u32 s14, s14, 0xb000
	s_addc_u32 s15, s15, 0
	global_load_dword v24, v15, s[14:15]
	s_add_u32 s14, s14, 0xb000
	s_addc_u32 s15, s15, 0
	global_load_dword v25, v15, s[14:15]
	s_add_u32 s14, s14, 0xb000
	s_addc_u32 s15, s15, 0
	global_load_dword v26, v15, s[14:15]
	s_add_u32 s14, s14, 0xb000
	s_addc_u32 s15, s15, 0
	global_load_dword v27, v15, s[14:15]
	s_add_u32 s14, s14, 0xb000
	s_addc_u32 s15, s15, 0
	global_load_dword v28, v15, s[14:15]
	s_add_u32 s14, s14, 0xb000
	s_addc_u32 s15, s15, 0
	global_load_dword v29, v15, s[14:15]
	s_add_u32 s14, s14, 0xb000
	s_addc_u32 s15, s15, 0
	global_load_dword v30, v15, s[14:15]
	s_add_u32 s14, s14, 0xb000
	s_addc_u32 s15, s15, 0
	global_load_dword v31, v15, s[14:15]
	s_add_u32 s14, s14, 0xb000
	s_addc_u32 s15, s15, 0
	global_load_dword v32, v15, s[14:15]
	s_add_u32 s14, s14, 0xb000
	s_addc_u32 s15, s15, 0
	global_load_dword v33, v15, s[14:15]
	s_add_u32 s14, s14, 0xb000
	s_addc_u32 s15, s15, 0
	global_load_dword v34, v15, s[14:15]
	s_add_u32 s14, s14, 0xb000
	s_addc_u32 s15, s15, 0
	global_load_dword v35, v15, s[14:15]
	s_add_u32 s14, s14, 0xb000
	s_addc_u32 s15, s15, 0
	global_load_dword v36, v15, s[14:15]
	s_add_u32 s14, s14, 0xb000
	s_addc_u32 s15, s15, 0
	global_load_dword v37, v15, s[14:15]
	s_add_u32 s14, s14, 0xb000
	s_addc_u32 s15, s15, 0
	global_load_dword v38, v15, s[14:15]
	s_add_u32 s14, s14, 0xb000
	s_addc_u32 s15, s15, 0
	global_load_dword v39, v15, s[14:15]
	s_add_u32 s14, s14, 0xb000
	s_addc_u32 s15, s15, 0
	global_load_dword v40, v15, s[14:15]
	s_add_u32 s14, s14, 0xb000
	s_addc_u32 s15, s15, 0
	global_load_dword v41, v15, s[14:15]
	s_add_u32 s14, s14, 0xb000
	s_addc_u32 s15, s15, 0
	global_load_dword v42, v15, s[14:15]
	s_add_u32 s14, s14, 0xb000
	s_addc_u32 s15, s15, 0
	global_load_dword v43, v15, s[14:15]
	s_add_u32 s14, s14, 0xb000
	s_addc_u32 s15, s15, 0
	global_load_dword v44, v15, s[14:15]
	s_add_u32 s14, s14, 0xb000
	s_addc_u32 s15, s15, 0
	global_load_dword v45, v15, s[14:15]
	s_add_u32 s14, s14, 0xb000
	s_addc_u32 s15, s15, 0
	global_load_dword v46, v15, s[14:15]
	s_add_u32 s14, s14, 0xb000
	s_addc_u32 s15, s15, 0
	global_load_dword v47, v15, s[14:15]
	s_lshl_b32 s14, s11, 8
	s_add_u32 s14, s20, s14
	s_addc_u32 s15, s21, 0
	global_load_dwordx4 v[80:83], v14, s[14:15]
	global_load_dwordx4 v[84:87], v14, s[14:15] offset:16
	s_lshr_b32 s16, s12, 2
	s_lshl_b32 s16, s16, 1
	s_lshl_b32 s16, s16, 5
	s_add_u32 s16, s16, s11
	s_lshl_b32 s16, s16, 14
	s_and_b32 s17, s12, 3
	s_lshl_b32 s17, s17, 12
	s_add_u32 s16, s16, s17
	s_add_u32 s16, s6, s16
	s_addc_u32 s17, s7, 0
.Ltc3e_loop:
	s_add_u32 s9, s9, s19
	s_cmpk_ge_u32 s9, 0x1600
	s_cbranch_scc1 .Ltc3e_lastA
	s_mul_hi_u32 s11, s9, 0x2e8ba2e9
	s_lshr_b32 s11, s11, 5
	s_mul_i32 s12, s11, 0xb0
	s_sub_u32 s12, s9, s12
	s_mul_i32 s13, s11, 0x160000
	s_lshl_b32 s14, s12, 7
	s_add_u32 s13, s13, s14
	s_add_u32 s14, s4, s13
	s_addc_u32 s15, s5, 0
	global_load_dword v88, v15, s[14:15]
	s_add_u32 s14, s14, 0xb000
	s_addc_u32 s15, s15, 0
	global_load_dword v89, v15, s[14:15]
	s_add_u32 s14, s14, 0xb000
	s_addc_u32 s15, s15, 0
	global_load_dword v90, v15, s[14:15]
	s_add_u32 s14, s14, 0xb000
	s_addc_u32 s15, s15, 0
	global_load_dword v91, v15, s[14:15]
	s_add_u32 s14, s14, 0xb000
	s_addc_u32 s15, s15, 0
	global_load_dword v92, v15, s[14:15]
	s_add_u32 s14, s14, 0xb000
	s_addc_u32 s15, s15, 0
	global_load_dword v93, v15, s[14:15]
	s_add_u32 s14, s14, 0xb000
	s_addc_u32 s15, s15, 0
	global_load_dword v94, v15, s[14:15]
	s_add_u32 s14, s14, 0xb000
	s_addc_u32 s15, s15, 0
	global_load_dword v95, v15, s[14:15]
	s_add_u32 s14, s14, 0xb000
	s_addc_u32 s15, s15, 0
	global_load_dword v96, v15, s[14:15]
	s_add_u32 s14, s14, 0xb000
	s_addc_u32 s15, s15, 0
	global_load_dword v97, v15, s[14:15]
	s_add_u32 s14, s14, 0xb000
	s_addc_u32 s15, s15, 0
	global_load_dword v98, v15, s[14:15]
	s_add_u32 s14, s14, 0xb000
	s_addc_u32 s15, s15, 0
	global_load_dword v99, v15, s[14:15]
	s_add_u32 s14, s14, 0xb000
	s_addc_u32 s15, s15, 0
	global_load_dword v100, v15, s[14:15]
	s_add_u32 s14, s14, 0xb000
	s_addc_u32 s15, s15, 0
	global_load_dword v101, v15, s[14:15]
	s_add_u32 s14, s14, 0xb000
	s_addc_u32 s15, s15, 0
	global_load_dword v102, v15, s[14:15]
	s_add_u32 s14, s14, 0xb000
	s_addc_u32 s15, s15, 0
	global_load_dword v103, v15, s[14:15]
	s_add_u32 s14, s14, 0xb000
; __device__ __forceinline__ void tr_load(const float* W, int N, int item, int lane, float (&wv)[32]) {
;     const int nblk = N / 32, kb = item / nblk, nb = item % nblk, k0 = 64 * kb, n0 = 32 * nb;
; #pragma unroll
;     for (int i = 0; i < 32; ++i) { const int kk = 2 * i + (lane >> 5); wv[i] = __builtin_nontemporal_load(W + (size_t)(k0 + kk) * N + n0 + (lane & 31)); }
; }
; template <int MAP, bool HASG, bool PERMW>
; __device__ __forceinline__ void tr_store(int K, int N, bf16_t* WT, LAS float* scr, int item, int lane, const float* gk) {
;     const int nblk = N / 32, kb = item / nblk, nb = item % nblk, k0 = 64 * kb, n0 = 32 * nb;
;     asm volatile("s_waitcnt lgkmcnt(0)" ::: "memory");
;     const int c = lane & 7;
;     f32x4 g0 = {1.f, 1.f, 1.f, 1.f}, g1 = {1.f, 1.f, 1.f, 1.f};
;     if (HASG) { g0 = *(const f32x4*)(gk + k0 + 8 * c); g1 = *(const f32x4*)(gk + k0 + 8 * c + 4); }
; #pragma unroll
;     for (int j = 0; j < 4; ++j) { const int n = (lane >> 3) + 8 * j; const LAS float* s = scr + (8 * c) * 33 + n;
;         u32x4 o; o.x = pk2(s[0 * 33] * g0[0], s[1 * 33] * g0[1]); o.y = pk2(s[2 * 33] * g0[2], s[3 * 33] * g0[3]); o.z = pk2(s[4 * 33] * g1[0], s[5 * 33] * g1[1]); o.w = pk2(s[6 * 33] * g1[2], s[7 * 33] * g1[3]);
;         const int wr_ = rowmap<MAP>(n0 + n), slot_ = PERMW ? ((wr_ & ~31) + invperm32(wr_ & 31)) : wr_;
;         *(u32x4*)((char*)WT + tiled_off(slot_, k0 + 8 * c, K / 64)) = o; }
;     asm volatile("s_waitcnt lgkmcnt(0)" ::: "memory");
; }
; template <int MAP, bool HASG = false, bool PERMW = false>
; __device__ __forceinline__ void transpose_mat(const float* W, int K, int N, bf16_t* WT, LAS float* scr, int gw, int ngw, int lane, const float* gk = nullptr) {
;     const int nitems = (K / 64) * (N / 32);
;     int it = gw;
;     if (it >= nitems) return;
;     float wv[32];
;     tr_load(W, N, it, lane, wv);
;     for (;;) {
;         __builtin_amdgcn_sched_barrier(0);
; #pragma unroll
;         for (int i = 0; i < 32; ++i) { const int kk = 2 * i + (lane >> 5); scr[kk * 33 + (lane & 31)] = wv[i]; }
;         __builtin_amdgcn_sched_barrier(0);
;         const int nx = it + ngw;
;         if (nx < nitems) tr_load(W, N, nx, lane, wv);
;         __builtin_amdgcn_sched_barrier(0);
;         tr_store<MAP, HASG, PERMW>(K, N, WT, scr, it, lane, gk);
;         if (nx >= nitems) break;
;         it = nx;
	s_addc_u32 s15, s15, 0
	global_load_dword v104, v15, s[14:15]
	s_add_u32 s14, s14, 0xb000
	s_addc_u32 s15, s15, 0
	global_load_dword v105, v15, s[14:15]
	s_add_u32 s14, s14, 0xb000
	s_addc_u32 s15, s15, 0
	global_load_dword v106, v15, s[14:15]
	s_add_u32 s14, s14, 0xb000
	s_addc_u32 s15, s15, 0
	global_load_dword v107, v15, s[14:15]
	s_add_u32 s14, s14, 0xb000
	s_addc_u32 s15, s15, 0
	global_load_dword v108, v15, s[14:15]
	s_add_u32 s14, s14, 0xb000
	s_addc_u32 s15, s15, 0
	global_load_dword v109, v15, s[14:15]
	s_add_u32 s14, s14, 0xb000
	s_addc_u32 s15, s15, 0
	global_load_dword v110, v15, s[14:15]
	s_add_u32 s14, s14, 0xb000
	s_addc_u32 s15, s15, 0
	global_load_dword v111, v15, s[14:15]
	s_add_u32 s14, s14, 0xb000
	s_addc_u32 s15, s15, 0
	global_load_dword v112, v15, s[14:15]
	s_add_u32 s14, s14, 0xb000
	s_addc_u32 s15, s15, 0
	global_load_dword v113, v15, s[14:15]
	s_add_u32 s14, s14, 0xb000
	s_addc_u32 s15, s15, 0
	global_load_dword v114, v15, s[14:15]
	s_add_u32 s14, s14, 0xb000
	s_addc_u32 s15, s15, 0
	global_load_dword v115, v15, s[14:15]
	s_add_u32 s14, s14, 0xb000
	s_addc_u32 s15, s15, 0
	global_load_dword v116, v15, s[14:15]
	s_add_u32 s14, s14, 0xb000
	s_addc_u32 s15, s15, 0
	global_load_dword v117, v15, s[14:15]
	s_add_u32 s14, s14, 0xb000
	s_addc_u32 s15, s15, 0
	global_load_dword v118, v15, s[14:15]
	s_add_u32 s14, s14, 0xb000
	s_addc_u32 s15, s15, 0
	global_load_dword v119, v15, s[14:15]
	s_lshl_b32 s14, s11, 8
	s_add_u32 s14, s20, s14
	s_addc_u32 s15, s21, 0
	global_load_dwordx4 v[120:123], v14, s[14:15]
	global_load_dwordx4 v[124:127], v14, s[14:15] offset:16
	s_lshr_b32 s24, s12, 2
	s_lshl_b32 s24, s24, 1
	s_lshl_b32 s24, s24, 5
	s_add_u32 s24, s24, s11
	s_lshl_b32 s24, s24, 14
	s_and_b32 s25, s12, 3
	s_lshl_b32 s25, s25, 12
	s_add_u32 s24, s24, s25
	s_add_u32 s24, s6, s24
	s_addc_u32 s25, s7, 0
	s_waitcnt vmcnt(34)
	ds_write_b32 v4, v16
	ds_write_b32 v4, v17 offset:264
	ds_write_b32 v4, v18 offset:528
	ds_write_b32 v4, v19 offset:792
	ds_write_b32 v4, v20 offset:1056
	ds_write_b32 v4, v21 offset:1320
	ds_write_b32 v4, v22 offset:1584
	ds_write_b32 v4, v23 offset:1848
	ds_write_b32 v4, v24 offset:2112
	ds_write_b32 v4, v25 offset:2376
	ds_write_b32 v4, v26 offset:2640
	ds_write_b32 v4, v27 offset:2904
	ds_write_b32 v4, v28 offset:3168
	ds_write_b32 v4, v29 offset:3432
	ds_write_b32 v4, v30 offset:3696
	ds_write_b32 v4, v31 offset:3960
	ds_write_b32 v4, v32 offset:4224
	ds_write_b32 v4, v33 offset:4488
	ds_write_b32 v4, v34 offset:4752
	ds_write_b32 v4, v35 offset:5016
	ds_write_b32 v4, v36 offset:5280
	ds_write_b32 v4, v37 offset:5544
	ds_write_b32 v4, v38 offset:5808
	ds_write_b32 v4, v39 offset:6072
	ds_write_b32 v4, v40 offset:6336
	ds_write_b32 v4, v41 offset:6600
	ds_write_b32 v4, v42 offset:6864
	ds_write_b32 v4, v43 offset:7128
	ds_write_b32 v4, v44 offset:7392
	ds_write_b32 v4, v45 offset:7656
	ds_write_b32 v4, v46 offset:7920
	ds_write_b32 v4, v47 offset:8184
	s_waitcnt lgkmcnt(0)
	ds_read_b32 v48, v7
	ds_read_b32 v49, v7 offset:132
	ds_read_b32 v50, v7 offset:264
	ds_read_b32 v51, v7 offset:396
	ds_read_b32 v52, v7 offset:528
	ds_read_b32 v53, v7 offset:660
	ds_read_b32 v54, v7 offset:792
	ds_read_b32 v55, v7 offset:924
	ds_read_b32 v56, v7 offset:32
	ds_read_b32 v57, v7 offset:164
	ds_read_b32 v58, v7 offset:296
	ds_read_b32 v59, v7 offset:428
	ds_read_b32 v60, v7 offset:560
	ds_read_b32 v61, v7 offset:692
	ds_read_b32 v62, v7 offset:824
	ds_read_b32 v63, v7 offset:956
	ds_read_b32 v64, v7 offset:64
	ds_read_b32 v65, v7 offset:196
	ds_read_b32 v66, v7 offset:328
	ds_read_b32 v67, v7 offset:460
	ds_read_b32 v68, v7 offset:592
	ds_read_b32 v69, v7 offset:724
	ds_read_b32 v70, v7 offset:856
	ds_read_b32 v71, v7 offset:988
	ds_read_b32 v72, v7 offset:96
	ds_read_b32 v73, v7 offset:228
	ds_read_b32 v74, v7 offset:360
	ds_read_b32 v75, v7 offset:492
	ds_read_b32 v76, v7 offset:624
	ds_read_b32 v77, v7 offset:756
	ds_read_b32 v78, v7 offset:888
	ds_read_b32 v79, v7 offset:1020
	s_waitcnt lgkmcnt(0)
	v_mul_f32_e32 v48, v48, v80
	v_mul_f32_e32 v49, v49, v81
	v_mul_f32_e32 v50, v50, v82
	v_mul_f32_e32 v51, v51, v83
	v_mul_f32_e32 v52, v52, v84
	v_mul_f32_e32 v53, v53, v85
	v_mul_f32_e32 v54, v54, v86
	v_mul_f32_e32 v55, v55, v87
	v_cvt_pk_bf16_f32 v48, v48, v49
	v_cvt_pk_bf16_f32 v49, v50, v51
	v_cvt_pk_bf16_f32 v50, v52, v53
	v_cvt_pk_bf16_f32 v51, v54, v55
	global_store_dwordx4 v10, v[48:51], s[16:17]
	v_mul_f32_e32 v56, v56, v80
	v_mul_f32_e32 v57, v57, v81
	v_mul_f32_e32 v58, v58, v82
	v_mul_f32_e32 v59, v59, v83
	v_mul_f32_e32 v60, v60, v84
	v_mul_f32_e32 v61, v61, v85
	v_mul_f32_e32 v62, v62, v86
	v_mul_f32_e32 v63, v63, v87
	v_cvt_pk_bf16_f32 v56, v56, v57
	v_cvt_pk_bf16_f32 v57, v58, v59
	v_cvt_pk_bf16_f32 v58, v60, v61
	v_cvt_pk_bf16_f32 v59, v62, v63
	global_store_dwordx4 v10, v[56:59], s[16:17] offset:256
	v_mul_f32_e32 v64, v64, v80
	v_mul_f32_e32 v65, v65, v81
	v_mul_f32_e32 v66, v66, v82
	v_mul_f32_e32 v67, v67, v83
	v_mul_f32_e32 v68, v68, v84
	v_mul_f32_e32 v69, v69, v85
	v_mul_f32_e32 v70, v70, v86
	v_mul_f32_e32 v71, v71, v87
	v_cvt_pk_bf16_f32 v64, v64, v65
	v_cvt_pk_bf16_f32 v65, v66, v67
	v_cvt_pk_bf16_f32 v66, v68, v69
	v_cvt_pk_bf16_f32 v67, v70, v71
	global_store_dwordx4 v11, v[64:67], s[16:17] offset:512
	v_mul_f32_e32 v72, v72, v80
	v_mul_f32_e32 v73, v73, v81
	v_mul_f32_e32 v74, v74, v82
	v_mul_f32_e32 v75, v75, v83
	v_mul_f32_e32 v76, v76, v84
	v_mul_f32_e32 v77, v77, v85
	v_mul_f32_e32 v78, v78, v86
	v_mul_f32_e32 v79, v79, v87
	v_cvt_pk_bf16_f32 v72, v72, v73
	v_cvt_pk_bf16_f32 v73, v74, v75
	v_cvt_pk_bf16_f32 v74, v76, v77
	v_cvt_pk_bf16_f32 v75, v78, v79
	global_store_dwordx4 v11, v[72:75], s[16:17] offset:768
	s_add_u32 s9, s9, s19
	s_cmpk_ge_u32 s9, 0x1600
	s_cbranch_scc1 .Ltc3e_lastB
; __device__ __forceinline__ void tr_load(const float* W, int N, int item, int lane, float (&wv)[32]) {
;     const int nblk = N / 32, kb = item / nblk, nb = item % nblk, k0 = 64 * kb, n0 = 32 * nb;
; #pragma unroll
;     for (int i = 0; i < 32; ++i) { const int kk = 2 * i + (lane >> 5); wv[i] = __builtin_nontemporal_load(W + (size_t)(k0 + kk) * N + n0 + (lane & 31)); }
; }
; template <int MAP, bool HASG, bool PERMW>
; __device__ __forceinline__ void tr_store(int K, int N, bf16_t* WT, LAS float* scr, int item, int lane, const float* gk) {
;     const int nblk = N / 32, kb = item / nblk, nb = item % nblk, k0 = 64 * kb, n0 = 32 * nb;
;     asm volatile("s_waitcnt lgkmcnt(0)" ::: "memory");
;     const int c = lane & 7;
;     f32x4 g0 = {1.f, 1.f, 1.f, 1.f}, g1 = {1.f, 1.f, 1.f, 1.f};
;     if (HASG) { g0 = *(const f32x4*)(gk + k0 + 8 * c); g1 = *(const f32x4*)(gk + k0 + 8 * c + 4); }
; #pragma unroll
;     for (int j = 0; j < 4; ++j) { const int n = (lane >> 3) + 8 * j; const LAS float* s = scr + (8 * c) * 33 + n;
;         u32x4 o; o.x = pk2(s[0 * 33] * g0[0], s[1 * 33] * g0[1]); o.y = pk2(s[2 * 33] * g0[2], s[3 * 33] * g0[3]); o.z = pk2(s[4 * 33] * g1[0], s[5 * 33] * g1[1]); o.w = pk2(s[6 * 33] * g1[2], s[7 * 33] * g1[3]);
;         const int wr_ = rowmap<MAP>(n0 + n), slot_ = PERMW ? ((wr_ & ~31) + invperm32(wr_ & 31)) : wr_;
;         *(u32x4*)((char*)WT + tiled_off(slot_, k0 + 8 * c, K / 64)) = o; }
;     asm volatile("s_waitcnt lgkmcnt(0)" ::: "memory");
; }
; template <int MAP, bool HASG = false, bool PERMW = false>
; __device__ __forceinline__ void transpose_mat(const float* W, int K, int N, bf16_t* WT, LAS float* scr, int gw, int ngw, int lane, const float* gk = nullptr) {
;     const int nitems = (K / 64) * (N / 32);
;     int it = gw;
;     if (it >= nitems) return;
;     float wv[32];
;     tr_load(W, N, it, lane, wv);
;     for (;;) {
;         __builtin_amdgcn_sched_barrier(0);
; #pragma unroll
;         for (int i = 0; i < 32; ++i) { const int kk = 2 * i + (lane >> 5); scr[kk * 33 + (lane & 31)] = wv[i]; }
;         __builtin_amdgcn_sched_barrier(0);
;         const int nx = it + ngw;
;         if (nx < nitems) tr_load(W, N, nx, lane, wv);
;         __builtin_amdgcn_sched_barrier(0);
;         tr_store<MAP, HASG, PERMW>(K, N, WT, scr, it, lane, gk);
;         if (nx >= nitems) break;
;         it = nx;
	s_mul_hi_u32 s11, s9, 0x2e8ba2e9
	s_lshr_b32 s11, s11, 5
	s_mul_i32 s12, s11, 0xb0
	s_sub_u32 s12, s9, s12
	s_mul_i32 s13, s11, 0x160000
	s_lshl_b32 s14, s12, 7
	s_add_u32 s13, s13, s14
	s_add_u32 s14, s4, s13
	s_addc_u32 s15, s5, 0
	global_load_dword v16, v15, s[14:15]
	s_add_u32 s14, s14, 0xb000
	s_addc_u32 s15, s15, 0
	global_load_dword v17, v15, s[14:15]
	s_add_u32 s14, s14, 0xb000
	s_addc_u32 s15, s15, 0
	global_load_dword v18, v15, s[14:15]
	s_add_u32 s14, s14, 0xb000
	s_addc_u32 s15, s15, 0
	global_load_dword v19, v15, s[14:15]
	s_add_u32 s14, s14, 0xb000
	s_addc_u32 s15, s15, 0
	global_load_dword v20, v15, s[14:15]
	s_add_u32 s14, s14, 0xb000
	s_addc_u32 s15, s15, 0
	global_load_dword v21, v15, s[14:15]
	s_add_u32 s14, s14, 0xb000
	s_addc_u32 s15, s15, 0
	global_load_dword v22, v15, s[14:15]
	s_add_u32 s14, s14, 0xb000
	s_addc_u32 s15, s15, 0
	global_load_dword v23, v15, s[14:15]
	s_add_u32 s14, s14, 0xb000
	s_addc_u32 s15, s15, 0
	global_load_dword v24, v15, s[14:15]
	s_add_u32 s14, s14, 0xb000
	s_addc_u32 s15, s15, 0
	global_load_dword v25, v15, s[14:15]
	s_add_u32 s14, s14, 0xb000
	s_addc_u32 s15, s15, 0
	global_load_dword v26, v15, s[14:15]
	s_add_u32 s14, s14, 0xb000
	s_addc_u32 s15, s15, 0
	global_load_dword v27, v15, s[14:15]
	s_add_u32 s14, s14, 0xb000
	s_addc_u32 s15, s15, 0
	global_load_dword v28, v15, s[14:15]
	s_add_u32 s14, s14, 0xb000
	s_addc_u32 s15, s15, 0
	global_load_dword v29, v15, s[14:15]
	s_add_u32 s14, s14, 0xb000
	s_addc_u32 s15, s15, 0
	global_load_dword v30, v15, s[14:15]
	s_add_u32 s14, s14, 0xb000
	s_addc_u32 s15, s15, 0
	global_load_dword v31, v15, s[14:15]
	s_add_u32 s14, s14, 0xb000
	s_addc_u32 s15, s15, 0
	global_load_dword v32, v15, s[14:15]
	s_add_u32 s14, s14, 0xb000
	s_addc_u32 s15, s15, 0
	global_load_dword v33, v15, s[14:15]
	s_add_u32 s14, s14, 0xb000
	s_addc_u32 s15, s15, 0
	global_load_dword v34, v15, s[14:15]
	s_add_u32 s14, s14, 0xb000
	s_addc_u32 s15, s15, 0
	global_load_dword v35, v15, s[14:15]
	s_add_u32 s14, s14, 0xb000
	s_addc_u32 s15, s15, 0
	global_load_dword v36, v15, s[14:15]
	s_add_u32 s14, s14, 0xb000
	s_addc_u32 s15, s15, 0
	global_load_dword v37, v15, s[14:15]
	s_add_u32 s14, s14, 0xb000
	s_addc_u32 s15, s15, 0
	global_load_dword v38, v15, s[14:15]
	s_add_u32 s14, s14, 0xb000
	s_addc_u32 s15, s15, 0
	global_load_dword v39, v15, s[14:15]
	s_add_u32 s14, s14, 0xb000
	s_addc_u32 s15, s15, 0
	global_load_dword v40, v15, s[14:15]
	s_add_u32 s14, s14, 0xb000
	s_addc_u32 s15, s15, 0
	global_load_dword v41, v15, s[14:15]
	s_add_u32 s14, s14, 0xb000
	s_addc_u32 s15, s15, 0
	global_load_dword v42, v15, s[14:15]
	s_add_u32 s14, s14, 0xb000
	s_addc_u32 s15, s15, 0
	global_load_dword v43, v15, s[14:15]
	s_add_u32 s14, s14, 0xb000
	s_addc_u32 s15, s15, 0
	global_load_dword v44, v15, s[14:15]
	s_add_u32 s14, s14, 0xb000
	s_addc_u32 s15, s15, 0
	global_load_dword v45, v15, s[14:15]
	s_add_u32 s14, s14, 0xb000
	s_addc_u32 s15, s15, 0
	global_load_dword v46, v15, s[14:15]
	s_add_u32 s14, s14, 0xb000
	s_addc_u32 s15, s15, 0
	global_load_dword v47, v15, s[14:15]
	s_lshl_b32 s14, s11, 8
	s_add_u32 s14, s20, s14
	s_addc_u32 s15, s21, 0
	global_load_dwordx4 v[80:83], v14, s[14:15]
	global_load_dwordx4 v[84:87], v14, s[14:15] offset:16
	s_lshr_b32 s16, s12, 2
	s_lshl_b32 s16, s16, 1
	s_lshl_b32 s16, s16, 5
	s_add_u32 s16, s16, s11
	s_lshl_b32 s16, s16, 14
	s_and_b32 s17, s12, 3
	s_lshl_b32 s17, s17, 12
	s_add_u32 s16, s16, s17
	s_add_u32 s16, s6, s16
	s_addc_u32 s17, s7, 0
	s_waitcnt vmcnt(34)
; #define LAS __attribute__((address_space(3)))
; __device__ __forceinline__ unsigned pk2(float lo, float hi) { f32x2 f = {lo, hi}; bf16x2_t b = __builtin_convertvector(f, bf16x2_t); return __builtin_bit_cast(unsigned, b); }
; template <int MAP, bool HASG, bool PERMW>
; __device__ __forceinline__ void tr_store(int K, int N, bf16_t* WT, LAS float* scr, int item, int lane, const float* gk) {
;     const int nblk = N / 32, kb = item / nblk, nb = item % nblk, k0 = 64 * kb, n0 = 32 * nb;
;     asm volatile("s_waitcnt lgkmcnt(0)" ::: "memory");
;     const int c = lane & 7;
;     f32x4 g0 = {1.f, 1.f, 1.f, 1.f}, g1 = {1.f, 1.f, 1.f, 1.f};
;     if (HASG) { g0 = *(const f32x4*)(gk + k0 + 8 * c); g1 = *(const f32x4*)(gk + k0 + 8 * c + 4); }
; #pragma unroll
;     for (int j = 0; j < 4; ++j) { const int n = (lane >> 3) + 8 * j; const LAS float* s = scr + (8 * c) * 33 + n;
;         u32x4 o; o.x = pk2(s[0 * 33] * g0[0], s[1 * 33] * g0[1]); o.y = pk2(s[2 * 33] * g0[2], s[3 * 33] * g0[3]); o.z = pk2(s[4 * 33] * g1[0], s[5 * 33] * g1[1]); o.w = pk2(s[6 * 33] * g1[2], s[7 * 33] * g1[3]);
;         const int wr_ = rowmap<MAP>(n0 + n), slot_ = PERMW ? ((wr_ & ~31) + invperm32(wr_ & 31)) : wr_;
;         *(u32x4*)((char*)WT + tiled_off(slot_, k0 + 8 * c, K / 64)) = o; }
;     asm volatile("s_waitcnt lgkmcnt(0)" ::: "memory");
; }
; template <int MAP, bool HASG = false, bool PERMW = false>
; __device__ __forceinline__ void transpose_mat(const float* W, int K, int N, bf16_t* WT, LAS float* scr, int gw, int ngw, int lane, const float* gk = nullptr) {
;     ...
;         for (int i = 0; i < 32; ++i) { const int kk = 2 * i + (lane >> 5); scr[kk * 33 + (lane & 31)] = wv[i]; }
	ds_write_b32 v4, v88
	ds_write_b32 v4, v89 offset:264
	ds_write_b32 v4, v90 offset:528
	ds_write_b32 v4, v91 offset:792
	ds_write_b32 v4, v92 offset:1056
	ds_write_b32 v4, v93 offset:1320
	ds_write_b32 v4, v94 offset:1584
	ds_write_b32 v4, v95 offset:1848
	ds_write_b32 v4, v96 offset:2112
	ds_write_b32 v4, v97 offset:2376
	ds_write_b32 v4, v98 offset:2640
	ds_write_b32 v4, v99 offset:2904
	ds_write_b32 v4, v100 offset:3168
	ds_write_b32 v4, v101 offset:3432
	ds_write_b32 v4, v102 offset:3696
	ds_write_b32 v4, v103 offset:3960
	ds_write_b32 v4, v104 offset:4224
	ds_write_b32 v4, v105 offset:4488
	ds_write_b32 v4, v106 offset:4752
	ds_write_b32 v4, v107 offset:5016
	ds_write_b32 v4, v108 offset:5280
	ds_write_b32 v4, v109 offset:5544
	ds_write_b32 v4, v110 offset:5808
	ds_write_b32 v4, v111 offset:6072
	ds_write_b32 v4, v112 offset:6336
	ds_write_b32 v4, v113 offset:6600
	ds_write_b32 v4, v114 offset:6864
	ds_write_b32 v4, v115 offset:7128
	ds_write_b32 v4, v116 offset:7392
	ds_write_b32 v4, v117 offset:7656
	ds_write_b32 v4, v118 offset:7920
	ds_write_b32 v4, v119 offset:8184
	s_waitcnt lgkmcnt(0)
	ds_read_b32 v48, v7
	ds_read_b32 v49, v7 offset:132
	ds_read_b32 v50, v7 offset:264
	ds_read_b32 v51, v7 offset:396
	ds_read_b32 v52, v7 offset:528
	ds_read_b32 v53, v7 offset:660
	ds_read_b32 v54, v7 offset:792
	ds_read_b32 v55, v7 offset:924
	ds_read_b32 v56, v7 offset:32
	ds_read_b32 v57, v7 offset:164
	ds_read_b32 v58, v7 offset:296
	ds_read_b32 v59, v7 offset:428
	ds_read_b32 v60, v7 offset:560
	ds_read_b32 v61, v7 offset:692
	ds_read_b32 v62, v7 offset:824
	ds_read_b32 v63, v7 offset:956
	ds_read_b32 v64, v7 offset:64
	ds_read_b32 v65, v7 offset:196
	ds_read_b32 v66, v7 offset:328
	ds_read_b32 v67, v7 offset:460
	ds_read_b32 v68, v7 offset:592
	ds_read_b32 v69, v7 offset:724
	ds_read_b32 v70, v7 offset:856
	ds_read_b32 v71, v7 offset:988
	ds_read_b32 v72, v7 offset:96
	ds_read_b32 v73, v7 offset:228
	ds_read_b32 v74, v7 offset:360
	ds_read_b32 v75, v7 offset:492
	ds_read_b32 v76, v7 offset:624
	ds_read_b32 v77, v7 offset:756
	ds_read_b32 v78, v7 offset:888
	ds_read_b32 v79, v7 offset:1020
	s_waitcnt lgkmcnt(0)
	v_mul_f32_e32 v48, v48, v120
	v_mul_f32_e32 v49, v49, v121
	v_mul_f32_e32 v50, v50, v122
	v_mul_f32_e32 v51, v51, v123
	v_mul_f32_e32 v52, v52, v124
	v_mul_f32_e32 v53, v53, v125
	v_mul_f32_e32 v54, v54, v126
	v_mul_f32_e32 v55, v55, v127
	v_cvt_pk_bf16_f32 v48, v48, v49
	v_cvt_pk_bf16_f32 v49, v50, v51
	v_cvt_pk_bf16_f32 v50, v52, v53
	v_cvt_pk_bf16_f32 v51, v54, v55
	global_store_dwordx4 v10, v[48:51], s[24:25]
	v_mul_f32_e32 v56, v56, v120
	v_mul_f32_e32 v57, v57, v121
	v_mul_f32_e32 v58, v58, v122
	v_mul_f32_e32 v59, v59, v123
	v_mul_f32_e32 v60, v60, v124
	v_mul_f32_e32 v61, v61, v125
	v_mul_f32_e32 v62, v62, v126
	v_mul_f32_e32 v63, v63, v127
	v_cvt_pk_bf16_f32 v56, v56, v57
	v_cvt_pk_bf16_f32 v57, v58, v59
	v_cvt_pk_bf16_f32 v58, v60, v61
	v_cvt_pk_bf16_f32 v59, v62, v63
	global_store_dwordx4 v10, v[56:59], s[24:25] offset:256
	v_mul_f32_e32 v64, v64, v120
	v_mul_f32_e32 v65, v65, v121
	v_mul_f32_e32 v66, v66, v122
	v_mul_f32_e32 v67, v67, v123
	v_mul_f32_e32 v68, v68, v124
	v_mul_f32_e32 v69, v69, v125
	v_mul_f32_e32 v70, v70, v126
	v_mul_f32_e32 v71, v71, v127
	v_cvt_pk_bf16_f32 v64, v64, v65
	v_cvt_pk_bf16_f32 v65, v66, v67
	v_cvt_pk_bf16_f32 v66, v68, v69
	v_cvt_pk_bf16_f32 v67, v70, v71
	global_store_dwordx4 v11, v[64:67], s[24:25] offset:512
	v_mul_f32_e32 v72, v72, v120
	v_mul_f32_e32 v73, v73, v121
	v_mul_f32_e32 v74, v74, v122
	v_mul_f32_e32 v75, v75, v123
	v_mul_f32_e32 v76, v76, v124
	v_mul_f32_e32 v77, v77, v125
	v_mul_f32_e32 v78, v78, v126
	v_mul_f32_e32 v79, v79, v127
	v_cvt_pk_bf16_f32 v72, v72, v73
	v_cvt_pk_bf16_f32 v73, v74, v75
	v_cvt_pk_bf16_f32 v74, v76, v77
	v_cvt_pk_bf16_f32 v75, v78, v79
	global_store_dwordx4 v11, v[72:75], s[24:25] offset:768
	s_branch .Ltc3e_loop

; __device__ __forceinline__ void tr_load(const float* W, int N, int item, int lane, float (&wv)[32]) {
;     const int nblk = N / 32, kb = item / nblk, nb = item % nblk, k0 = 64 * kb, n0 = 32 * nb;
; #pragma unroll
;     for (int i = 0; i < 32; ++i) { const int kk = 2 * i + (lane >> 5); wv[i] = __builtin_nontemporal_load(W + (size_t)(k0 + kk) * N + n0 + (lane & 31)); }
; }
; template <int MAP, bool HASG, bool PERMW>
; __device__ __forceinline__ void tr_store(int K, int N, bf16_t* WT, LAS float* scr, int item, int lane, const float* gk) {
;     const int nblk = N / 32, kb = item / nblk, nb = item % nblk, k0 = 64 * kb, n0 = 32 * nb;
;     asm volatile("s_waitcnt lgkmcnt(0)" ::: "memory");
;     const int c = lane & 7;
;     f32x4 g0 = {1.f, 1.f, 1.f, 1.f}, g1 = {1.f, 1.f, 1.f, 1.f};
;     if (HASG) { g0 = *(const f32x4*)(gk + k0 + 8 * c); g1 = *(const f32x4*)(gk + k0 + 8 * c + 4); }
; #pragma unroll
;     for (int j = 0; j < 4; ++j) { const int n = (lane >> 3) + 8 * j; const LAS float* s = scr + (8 * c) * 33 + n;
;         u32x4 o; o.x = pk2(s[0 * 33] * g0[0], s[1 * 33] * g0[1]); o.y = pk2(s[2 * 33] * g0[2], s[3 * 33] * g0[3]); o.z = pk2(s[4 * 33] * g1[0], s[5 * 33] * g1[1]); o.w = pk2(s[6 * 33] * g1[2], s[7 * 33] * g1[3]);
;         const int wr_ = rowmap<MAP>(n0 + n), slot_ = PERMW ? ((wr_ & ~31) + invperm32(wr_ & 31)) : wr_;
;         *(u32x4*)((char*)WT + tiled_off(slot_, k0 + 8 * c, K / 64)) = o; }
;     asm volatile("s_waitcnt lgkmcnt(0)" ::: "memory");
; }
; template <int MAP, bool HASG = false, bool PERMW = false>
; __device__ __forceinline__ void transpose_mat(const float* W, int K, int N, bf16_t* WT, LAS float* scr, int gw, int ngw, int lane, const float* gk = nullptr) {
;     const int nitems = (K / 64) * (N / 32);
;     int it = gw;
;     if (it >= nitems) return;
;     float wv[32];
;     tr_load(W, N, it, lane, wv);
;     for (;;) {
;         __builtin_amdgcn_sched_barrier(0);
; #pragma unroll
;         for (int i = 0; i < 32; ++i) { const int kk = 2 * i + (lane >> 5); scr[kk * 33 + (lane & 31)] = wv[i]; }
;         __builtin_amdgcn_sched_barrier(0);
;         const int nx = it + ngw;
;         if (nx < nitems) tr_load(W, N, nx, lane, wv);
;         __builtin_amdgcn_sched_barrier(0);
;         tr_store<MAP, HASG, PERMW>(K, N, WT, scr, it, lane, gk);
;         if (nx >= nitems) break;
;         it = nx;
.Ltc3e_exit:
	v_readlane_b32 s4, v254, 8
	v_readlane_b32 s5, v254, 9
	v_readlane_b32 s20, v254, 4
	v_readlane_b32 s21, v254, 5
	s_nop 3
	s_and_b32 s6, s60, 0x2c00000
	s_add_u32 s4, s4, s6
	s_addc_u32 s5, s5, 0
	s_and_b32 s6, s60, 0x2000
	s_add_u32 s20, s20, s6
	s_addc_u32 s21, s21, 0
	s_add_u32 s6, s76, 0x8a00000
	s_addc_u32 s7, s77, 0
	s_mov_b32 s9, s18
	s_cmpk_ge_u32 s9, 0x1600
	s_cbranch_scc1 .Ltc3d_exit
	s_mul_hi_u32 s11, s9, 0x2e8ba2e9
	s_lshr_b32 s11, s11, 5
	s_mul_i32 s12, s11, 0xb0
	s_sub_u32 s12, s9, s12
	s_mul_i32 s13, s11, 0x160000
	s_lshl_b32 s14, s12, 7
	s_add_u32 s13, s13, s14
	s_add_u32 s14, s4, s13
	s_addc_u32 s15, s5, 0
	global_load_dword v16, v15, s[14:15]
	s_add_u32 s14, s14, 0xb000
	s_addc_u32 s15, s15, 0
	global_load_dword v17, v15, s[14:15]
	s_add_u32 s14, s14, 0xb000
	s_addc_u32 s15, s15, 0
	global_load_dword v18, v15, s[14:15]
	s_add_u32 s14, s14, 0xb000
	s_addc_u32 s15, s15, 0
	global_load_dword v19, v15, s[14:15]
	s_add_u32 s14, s14, 0xb000
	s_addc_u32 s15, s15, 0
	global_load_dword v20, v15, s[14:15]
	s_add_u32 s14, s14, 0xb000
	s_addc_u32 s15, s15, 0
	global_load_dword v21, v15, s[14:15]
	s_add_u32 s14, s14, 0xb000
	s_addc_u32 s15, s15, 0
	global_load_dword v22, v15, s[14:15]
	s_add_u32 s14, s14, 0xb000
	s_addc_u32 s15, s15, 0
	global_load_dword v23, v15, s[14:15]
	s_add_u32 s14, s14, 0xb000
	s_addc_u32 s15, s15, 0
	global_load_dword v24, v15, s[14:15]
	s_add_u32 s14, s14, 0xb000
	s_addc_u32 s15, s15, 0
	global_load_dword v25, v15, s[14:15]
	s_add_u32 s14, s14, 0xb000
	s_addc_u32 s15, s15, 0
	global_load_dword v26, v15, s[14:15]
	s_add_u32 s14, s14, 0xb000
	s_addc_u32 s15, s15, 0
	global_load_dword v27, v15, s[14:15]
	s_add_u32 s14, s14, 0xb000
	s_addc_u32 s15, s15, 0
	global_load_dword v28, v15, s[14:15]
	s_add_u32 s14, s14, 0xb000
	s_addc_u32 s15, s15, 0
	global_load_dword v29, v15, s[14:15]
	s_add_u32 s14, s14, 0xb000
	s_addc_u32 s15, s15, 0
	global_load_dword v30, v15, s[14:15]
	s_add_u32 s14, s14, 0xb000
	s_addc_u32 s15, s15, 0
	global_load_dword v31, v15, s[14:15]
	s_add_u32 s14, s14, 0xb000
	s_addc_u32 s15, s15, 0
	global_load_dword v32, v15, s[14:15]
	s_add_u32 s14, s14, 0xb000
	s_addc_u32 s15, s15, 0
	global_load_dword v33, v15, s[14:15]
	s_add_u32 s14, s14, 0xb000
	s_addc_u32 s15, s15, 0
	global_load_dword v34, v15, s[14:15]
	s_add_u32 s14, s14, 0xb000
	s_addc_u32 s15, s15, 0
	global_load_dword v35, v15, s[14:15]
	s_add_u32 s14, s14, 0xb000
	s_addc_u32 s15, s15, 0
	global_load_dword v36, v15, s[14:15]
	s_add_u32 s14, s14, 0xb000
	s_addc_u32 s15, s15, 0
	global_load_dword v37, v15, s[14:15]
	s_add_u32 s14, s14, 0xb000
	s_addc_u32 s15, s15, 0
	global_load_dword v38, v15, s[14:15]
	s_add_u32 s14, s14, 0xb000
	s_addc_u32 s15, s15, 0
	global_load_dword v39, v15, s[14:15]
	s_add_u32 s14, s14, 0xb000
	s_addc_u32 s15, s15, 0
	global_load_dword v40, v15, s[14:15]
	s_add_u32 s14, s14, 0xb000
	s_addc_u32 s15, s15, 0
	global_load_dword v41, v15, s[14:15]
	s_add_u32 s14, s14, 0xb000
	s_addc_u32 s15, s15, 0
	global_load_dword v42, v15, s[14:15]
	s_add_u32 s14, s14, 0xb000
	s_addc_u32 s15, s15, 0
	global_load_dword v43, v15, s[14:15]
	s_add_u32 s14, s14, 0xb000
	s_addc_u32 s15, s15, 0
	global_load_dword v44, v15, s[14:15]
	s_add_u32 s14, s14, 0xb000
	s_addc_u32 s15, s15, 0
	global_load_dword v45, v15, s[14:15]
	s_add_u32 s14, s14, 0xb000
	s_addc_u32 s15, s15, 0
	global_load_dword v46, v15, s[14:15]
	s_add_u32 s14, s14, 0xb000
	s_addc_u32 s15, s15, 0
	global_load_dword v47, v15, s[14:15]
	s_lshl_b32 s14, s11, 8
	s_add_u32 s14, s20, s14
	s_addc_u32 s15, s21, 0
	global_load_dwordx4 v[80:83], v14, s[14:15]
	global_load_dwordx4 v[84:87], v14, s[14:15] offset:16
	s_lshr_b32 s16, s12, 2
	s_lshl_b32 s16, s16, 1
	s_add_u32 s16, s16, 1
	s_lshl_b32 s16, s16, 5
	s_add_u32 s16, s16, s11
	s_lshl_b32 s16, s16, 14
	s_and_b32 s17, s12, 3
	s_lshl_b32 s17, s17, 12
	s_add_u32 s16, s16, s17
	s_add_u32 s16, s6, s16
	s_addc_u32 s17, s7, 0
.Ltc3d_loop:
	s_add_u32 s9, s9, s19
	s_cmpk_ge_u32 s9, 0x1600
	s_cbranch_scc1 .Ltc3d_lastA
	s_mul_hi_u32 s11, s9, 0x2e8ba2e9
	s_lshr_b32 s11, s11, 5
	s_mul_i32 s12, s11, 0xb0
	s_sub_u32 s12, s9, s12
	s_mul_i32 s13, s11, 0x160000
	s_lshl_b32 s14, s12, 7
	s_add_u32 s13, s13, s14
	s_add_u32 s14, s4, s13
	s_addc_u32 s15, s5, 0
	global_load_dword v88, v15, s[14:15]
	s_add_u32 s14, s14, 0xb000
	s_addc_u32 s15, s15, 0
	global_load_dword v89, v15, s[14:15]
	s_add_u32 s14, s14, 0xb000
	s_addc_u32 s15, s15, 0
	global_load_dword v90, v15, s[14:15]
	s_add_u32 s14, s14, 0xb000
	s_addc_u32 s15, s15, 0
	global_load_dword v91, v15, s[14:15]
	s_add_u32 s14, s14, 0xb000
	s_addc_u32 s15, s15, 0
	global_load_dword v92, v15, s[14:15]
	s_add_u32 s14, s14, 0xb000
	s_addc_u32 s15, s15, 0
	global_load_dword v93, v15, s[14:15]
	s_add_u32 s14, s14, 0xb000
	s_addc_u32 s15, s15, 0
	global_load_dword v94, v15, s[14:15]
	s_add_u32 s14, s14, 0xb000
	s_addc_u32 s15, s15, 0
	global_load_dword v95, v15, s[14:15]
	s_add_u32 s14, s14, 0xb000
	s_addc_u32 s15, s15, 0
	global_load_dword v96, v15, s[14:15]
	s_add_u32 s14, s14, 0xb000
	s_addc_u32 s15, s15, 0
	global_load_dword v97, v15, s[14:15]
	s_add_u32 s14, s14, 0xb000
	s_addc_u32 s15, s15, 0
	global_load_dword v98, v15, s[14:15]
	s_add_u32 s14, s14, 0xb000
	s_addc_u32 s15, s15, 0
	global_load_dword v99, v15, s[14:15]
	s_add_u32 s14, s14, 0xb000
	s_addc_u32 s15, s15, 0
	global_load_dword v100, v15, s[14:15]
	s_add_u32 s14, s14, 0xb000
	s_addc_u32 s15, s15, 0
	global_load_dword v101, v15, s[14:15]
	s_add_u32 s14, s14, 0xb000
	s_addc_u32 s15, s15, 0
	global_load_dword v102, v15, s[14:15]
	s_add_u32 s14, s14, 0xb000
	s_addc_u32 s15, s15, 0
	global_load_dword v103, v15, s[14:15]
; __device__ __forceinline__ void tr_load(const float* W, int N, int item, int lane, float (&wv)[32]) {
;     const int nblk = N / 32, kb = item / nblk, nb = item % nblk, k0 = 64 * kb, n0 = 32 * nb;
; #pragma unroll
;     for (int i = 0; i < 32; ++i) { const int kk = 2 * i + (lane >> 5); wv[i] = __builtin_nontemporal_load(W + (size_t)(k0 + kk) * N + n0 + (lane & 31)); }
; }
; template <int MAP, bool HASG, bool PERMW>
; __device__ __forceinline__ void tr_store(int K, int N, bf16_t* WT, LAS float* scr, int item, int lane, const float* gk) {
;     const int nblk = N / 32, kb = item / nblk, nb = item % nblk, k0 = 64 * kb, n0 = 32 * nb;
;     asm volatile("s_waitcnt lgkmcnt(0)" ::: "memory");
;     const int c = lane & 7;
;     f32x4 g0 = {1.f, 1.f, 1.f, 1.f}, g1 = {1.f, 1.f, 1.f, 1.f};
;     if (HASG) { g0 = *(const f32x4*)(gk + k0 + 8 * c); g1 = *(const f32x4*)(gk + k0 + 8 * c + 4); }
; #pragma unroll
;     for (int j = 0; j < 4; ++j) { const int n = (lane >> 3) + 8 * j; const LAS float* s = scr + (8 * c) * 33 + n;
;         u32x4 o; o.x = pk2(s[0 * 33] * g0[0], s[1 * 33] * g0[1]); o.y = pk2(s[2 * 33] * g0[2], s[3 * 33] * g0[3]); o.z = pk2(s[4 * 33] * g1[0], s[5 * 33] * g1[1]); o.w = pk2(s[6 * 33] * g1[2], s[7 * 33] * g1[3]);
;         const int wr_ = rowmap<MAP>(n0 + n), slot_ = PERMW ? ((wr_ & ~31) + invperm32(wr_ & 31)) : wr_;
;         *(u32x4*)((char*)WT + tiled_off(slot_, k0 + 8 * c, K / 64)) = o; }
;     asm volatile("s_waitcnt lgkmcnt(0)" ::: "memory");
; }
; template <int MAP, bool HASG = false, bool PERMW = false>
; __device__ __forceinline__ void transpose_mat(const float* W, int K, int N, bf16_t* WT, LAS float* scr, int gw, int ngw, int lane, const float* gk = nullptr) {
;     const int nitems = (K / 64) * (N / 32);
;     int it = gw;
;     if (it >= nitems) return;
;     float wv[32];
;     tr_load(W, N, it, lane, wv);
;     for (;;) {
;         __builtin_amdgcn_sched_barrier(0);
; #pragma unroll
;         for (int i = 0; i < 32; ++i) { const int kk = 2 * i + (lane >> 5); scr[kk * 33 + (lane & 31)] = wv[i]; }
;         __builtin_amdgcn_sched_barrier(0);
;         const int nx = it + ngw;
;         if (nx < nitems) tr_load(W, N, nx, lane, wv);
;         __builtin_amdgcn_sched_barrier(0);
;         tr_store<MAP, HASG, PERMW>(K, N, WT, scr, it, lane, gk);
;         if (nx >= nitems) break;
;         it = nx;
;     }
	s_add_u32 s14, s14, 0xb000
	s_addc_u32 s15, s15, 0
	global_load_dword v104, v15, s[14:15]
	s_add_u32 s14, s14, 0xb000
	s_addc_u32 s15, s15, 0
	global_load_dword v105, v15, s[14:15]
	s_add_u32 s14, s14, 0xb000
	s_addc_u32 s15, s15, 0
	global_load_dword v106, v15, s[14:15]
	s_add_u32 s14, s14, 0xb000
	s_addc_u32 s15, s15, 0
	global_load_dword v107, v15, s[14:15]
	s_add_u32 s14, s14, 0xb000
	s_addc_u32 s15, s15, 0
	global_load_dword v108, v15, s[14:15]
	s_add_u32 s14, s14, 0xb000
	s_addc_u32 s15, s15, 0
	global_load_dword v109, v15, s[14:15]
	s_add_u32 s14, s14, 0xb000
	s_addc_u32 s15, s15, 0
	global_load_dword v110, v15, s[14:15]
	s_add_u32 s14, s14, 0xb000
	s_addc_u32 s15, s15, 0
	global_load_dword v111, v15, s[14:15]
	s_add_u32 s14, s14, 0xb000
	s_addc_u32 s15, s15, 0
	global_load_dword v112, v15, s[14:15]
	s_add_u32 s14, s14, 0xb000
	s_addc_u32 s15, s15, 0
	global_load_dword v113, v15, s[14:15]
	s_add_u32 s14, s14, 0xb000
	s_addc_u32 s15, s15, 0
	global_load_dword v114, v15, s[14:15]
	s_add_u32 s14, s14, 0xb000
	s_addc_u32 s15, s15, 0
	global_load_dword v115, v15, s[14:15]
	s_add_u32 s14, s14, 0xb000
	s_addc_u32 s15, s15, 0
	global_load_dword v116, v15, s[14:15]
	s_add_u32 s14, s14, 0xb000
	s_addc_u32 s15, s15, 0
	global_load_dword v117, v15, s[14:15]
	s_add_u32 s14, s14, 0xb000
	s_addc_u32 s15, s15, 0
	global_load_dword v118, v15, s[14:15]
	s_add_u32 s14, s14, 0xb000
	s_addc_u32 s15, s15, 0
	global_load_dword v119, v15, s[14:15]
	s_lshl_b32 s14, s11, 8
	s_add_u32 s14, s20, s14
	s_addc_u32 s15, s21, 0
	global_load_dwordx4 v[120:123], v14, s[14:15]
	global_load_dwordx4 v[124:127], v14, s[14:15] offset:16
	s_lshr_b32 s24, s12, 2
	s_lshl_b32 s24, s24, 1
	s_add_u32 s24, s24, 1
	s_lshl_b32 s24, s24, 5
	s_add_u32 s24, s24, s11
	s_lshl_b32 s24, s24, 14
	s_and_b32 s25, s12, 3
	s_lshl_b32 s25, s25, 12
	s_add_u32 s24, s24, s25
	s_add_u32 s24, s6, s24
	s_addc_u32 s25, s7, 0
	s_waitcnt vmcnt(34)
	ds_write_b32 v4, v16
	ds_write_b32 v4, v17 offset:264
	ds_write_b32 v4, v18 offset:528
	ds_write_b32 v4, v19 offset:792
	ds_write_b32 v4, v20 offset:1056
	ds_write_b32 v4, v21 offset:1320
	ds_write_b32 v4, v22 offset:1584
	ds_write_b32 v4, v23 offset:1848
	ds_write_b32 v4, v24 offset:2112
	ds_write_b32 v4, v25 offset:2376
	ds_write_b32 v4, v26 offset:2640
	ds_write_b32 v4, v27 offset:2904
	ds_write_b32 v4, v28 offset:3168
	ds_write_b32 v4, v29 offset:3432
	ds_write_b32 v4, v30 offset:3696
	ds_write_b32 v4, v31 offset:3960
	ds_write_b32 v4, v32 offset:4224
	ds_write_b32 v4, v33 offset:4488
	ds_write_b32 v4, v34 offset:4752
	ds_write_b32 v4, v35 offset:5016
	ds_write_b32 v4, v36 offset:5280
	ds_write_b32 v4, v37 offset:5544
	ds_write_b32 v4, v38 offset:5808
	ds_write_b32 v4, v39 offset:6072
	ds_write_b32 v4, v40 offset:6336
	ds_write_b32 v4, v41 offset:6600
	ds_write_b32 v4, v42 offset:6864
	ds_write_b32 v4, v43 offset:7128
	ds_write_b32 v4, v44 offset:7392
	ds_write_b32 v4, v45 offset:7656
	ds_write_b32 v4, v46 offset:7920
	ds_write_b32 v4, v47 offset:8184
	s_waitcnt lgkmcnt(0)
	ds_read_b32 v48, v7
	ds_read_b32 v49, v7 offset:132
	ds_read_b32 v50, v7 offset:264
	ds_read_b32 v51, v7 offset:396
	ds_read_b32 v52, v7 offset:528
	ds_read_b32 v53, v7 offset:660
	ds_read_b32 v54, v7 offset:792
	ds_read_b32 v55, v7 offset:924
	ds_read_b32 v56, v7 offset:32
	ds_read_b32 v57, v7 offset:164
	ds_read_b32 v58, v7 offset:296
	ds_read_b32 v59, v7 offset:428
	ds_read_b32 v60, v7 offset:560
	ds_read_b32 v61, v7 offset:692
	ds_read_b32 v62, v7 offset:824
	ds_read_b32 v63, v7 offset:956
	ds_read_b32 v64, v7 offset:64
	ds_read_b32 v65, v7 offset:196
	ds_read_b32 v66, v7 offset:328
	ds_read_b32 v67, v7 offset:460
	ds_read_b32 v68, v7 offset:592
	ds_read_b32 v69, v7 offset:724
	ds_read_b32 v70, v7 offset:856
	ds_read_b32 v71, v7 offset:988
	ds_read_b32 v72, v7 offset:96
	ds_read_b32 v73, v7 offset:228
	ds_read_b32 v74, v7 offset:360
	ds_read_b32 v75, v7 offset:492
	ds_read_b32 v76, v7 offset:624
	ds_read_b32 v77, v7 offset:756
	ds_read_b32 v78, v7 offset:888
	ds_read_b32 v79, v7 offset:1020
	s_waitcnt lgkmcnt(0)
	v_mul_f32_e32 v48, v48, v80
	v_mul_f32_e32 v49, v49, v81
	v_mul_f32_e32 v50, v50, v82
	v_mul_f32_e32 v51, v51, v83
	v_mul_f32_e32 v52, v52, v84
	v_mul_f32_e32 v53, v53, v85
	v_mul_f32_e32 v54, v54, v86
	v_mul_f32_e32 v55, v55, v87
	v_cvt_pk_bf16_f32 v48, v48, v49
	v_cvt_pk_bf16_f32 v49, v50, v51
	v_cvt_pk_bf16_f32 v50, v52, v53
	v_cvt_pk_bf16_f32 v51, v54, v55
	global_store_dwordx4 v10, v[48:51], s[16:17]
	v_mul_f32_e32 v56, v56, v80
	v_mul_f32_e32 v57, v57, v81
	v_mul_f32_e32 v58, v58, v82
	v_mul_f32_e32 v59, v59, v83
	v_mul_f32_e32 v60, v60, v84
	v_mul_f32_e32 v61, v61, v85
	v_mul_f32_e32 v62, v62, v86
	v_mul_f32_e32 v63, v63, v87
	v_cvt_pk_bf16_f32 v56, v56, v57
	v_cvt_pk_bf16_f32 v57, v58, v59
	v_cvt_pk_bf16_f32 v58, v60, v61
	v_cvt_pk_bf16_f32 v59, v62, v63
	global_store_dwordx4 v10, v[56:59], s[16:17] offset:256
	v_mul_f32_e32 v64, v64, v80
	v_mul_f32_e32 v65, v65, v81
	v_mul_f32_e32 v66, v66, v82
	v_mul_f32_e32 v67, v67, v83
	v_mul_f32_e32 v68, v68, v84
	v_mul_f32_e32 v69, v69, v85
	v_mul_f32_e32 v70, v70, v86
	v_mul_f32_e32 v71, v71, v87
	v_cvt_pk_bf16_f32 v64, v64, v65
	v_cvt_pk_bf16_f32 v65, v66, v67
	v_cvt_pk_bf16_f32 v66, v68, v69
	v_cvt_pk_bf16_f32 v67, v70, v71
	global_store_dwordx4 v11, v[64:67], s[16:17] offset:512
	v_mul_f32_e32 v72, v72, v80
	v_mul_f32_e32 v73, v73, v81
	v_mul_f32_e32 v74, v74, v82
	v_mul_f32_e32 v75, v75, v83
	v_mul_f32_e32 v76, v76, v84
	v_mul_f32_e32 v77, v77, v85
	v_mul_f32_e32 v78, v78, v86
	v_mul_f32_e32 v79, v79, v87
	v_cvt_pk_bf16_f32 v72, v72, v73
	v_cvt_pk_bf16_f32 v73, v74, v75
	v_cvt_pk_bf16_f32 v74, v76, v77
	v_cvt_pk_bf16_f32 v75, v78, v79
	global_store_dwordx4 v11, v[72:75], s[16:17] offset:768
	s_add_u32 s9, s9, s19
	s_cmpk_ge_u32 s9, 0x1600
	s_cbranch_scc1 .Ltc3d_lastB
; #define LAS __attribute__((address_space(3)))
; __device__ __forceinline__ unsigned pk2(float lo, float hi) { f32x2 f = {lo, hi}; bf16x2_t b = __builtin_convertvector(f, bf16x2_t); return __builtin_bit_cast(unsigned, b); }
; __device__ __forceinline__ void tr_load(const float* W, int N, int item, int lane, float (&wv)[32]) {
;     const int nblk = N / 32, kb = item / nblk, nb = item % nblk, k0 = 64 * kb, n0 = 32 * nb;
; #pragma unroll
;     for (int i = 0; i < 32; ++i) { const int kk = 2 * i + (lane >> 5); wv[i] = __builtin_nontemporal_load(W + (size_t)(k0 + kk) * N + n0 + (lane & 31)); }
; }
; template <int MAP, bool HASG, bool PERMW>
; __device__ __forceinline__ void tr_store(int K, int N, bf16_t* WT, LAS float* scr, int item, int lane, const float* gk) {
;     const int nblk = N / 32, kb = item / nblk, nb = item % nblk, k0 = 64 * kb, n0 = 32 * nb;
;     asm volatile("s_waitcnt lgkmcnt(0)" ::: "memory");
;     const int c = lane & 7;
;     f32x4 g0 = {1.f, 1.f, 1.f, 1.f}, g1 = {1.f, 1.f, 1.f, 1.f};
;     if (HASG) { g0 = *(const f32x4*)(gk + k0 + 8 * c); g1 = *(const f32x4*)(gk + k0 + 8 * c + 4); }
; #pragma unroll
;     for (int j = 0; j < 4; ++j) { const int n = (lane >> 3) + 8 * j; const LAS float* s = scr + (8 * c) * 33 + n;
;         u32x4 o; o.x = pk2(s[0 * 33] * g0[0], s[1 * 33] * g0[1]); o.y = pk2(s[2 * 33] * g0[2], s[3 * 33] * g0[3]); o.z = pk2(s[4 * 33] * g1[0], s[5 * 33] * g1[1]); o.w = pk2(s[6 * 33] * g1[2], s[7 * 33] * g1[3]);
;         const int wr_ = rowmap<MAP>(n0 + n), slot_ = PERMW ? ((wr_ & ~31) + invperm32(wr_ & 31)) : wr_;
;         *(u32x4*)((char*)WT + tiled_off(slot_, k0 + 8 * c, K / 64)) = o; }
	s_mul_hi_u32 s11, s9, 0x2e8ba2e9
	s_lshr_b32 s11, s11, 5
	s_mul_i32 s12, s11, 0xb0
	s_sub_u32 s12, s9, s12
	s_mul_i32 s13, s11, 0x160000
	s_lshl_b32 s14, s12, 7
	s_add_u32 s13, s13, s14
	s_add_u32 s14, s4, s13
	s_addc_u32 s15, s5, 0
	global_load_dword v16, v15, s[14:15]
	s_add_u32 s14, s14, 0xb000
	s_addc_u32 s15, s15, 0
	global_load_dword v17, v15, s[14:15]
	s_add_u32 s14, s14, 0xb000
	s_addc_u32 s15, s15, 0
	global_load_dword v18, v15, s[14:15]
	s_add_u32 s14, s14, 0xb000
	s_addc_u32 s15, s15, 0
	global_load_dword v19, v15, s[14:15]
	s_add_u32 s14, s14, 0xb000
	s_addc_u32 s15, s15, 0
	global_load_dword v20, v15, s[14:15]
	s_add_u32 s14, s14, 0xb000
	s_addc_u32 s15, s15, 0
	global_load_dword v21, v15, s[14:15]
	s_add_u32 s14, s14, 0xb000
	s_addc_u32 s15, s15, 0
	global_load_dword v22, v15, s[14:15]
	s_add_u32 s14, s14, 0xb000
	s_addc_u32 s15, s15, 0
	global_load_dword v23, v15, s[14:15]
	s_add_u32 s14, s14, 0xb000
	s_addc_u32 s15, s15, 0
	global_load_dword v24, v15, s[14:15]
	s_add_u32 s14, s14, 0xb000
	s_addc_u32 s15, s15, 0
	global_load_dword v25, v15, s[14:15]
	s_add_u32 s14, s14, 0xb000
	s_addc_u32 s15, s15, 0
	global_load_dword v26, v15, s[14:15]
	s_add_u32 s14, s14, 0xb000
	s_addc_u32 s15, s15, 0
	global_load_dword v27, v15, s[14:15]
	s_add_u32 s14, s14, 0xb000
	s_addc_u32 s15, s15, 0
	global_load_dword v28, v15, s[14:15]
	s_add_u32 s14, s14, 0xb000
	s_addc_u32 s15, s15, 0
	global_load_dword v29, v15, s[14:15]
	s_add_u32 s14, s14, 0xb000
	s_addc_u32 s15, s15, 0
	global_load_dword v30, v15, s[14:15]
	s_add_u32 s14, s14, 0xb000
	s_addc_u32 s15, s15, 0
	global_load_dword v31, v15, s[14:15]
	s_add_u32 s14, s14, 0xb000
	s_addc_u32 s15, s15, 0
	global_load_dword v32, v15, s[14:15]
	s_add_u32 s14, s14, 0xb000
	s_addc_u32 s15, s15, 0
	global_load_dword v33, v15, s[14:15]
	s_add_u32 s14, s14, 0xb000
	s_addc_u32 s15, s15, 0
	global_load_dword v34, v15, s[14:15]
	s_add_u32 s14, s14, 0xb000
	s_addc_u32 s15, s15, 0
	global_load_dword v35, v15, s[14:15]
	s_add_u32 s14, s14, 0xb000
	s_addc_u32 s15, s15, 0
	global_load_dword v36, v15, s[14:15]
	s_add_u32 s14, s14, 0xb000
	s_addc_u32 s15, s15, 0
	global_load_dword v37, v15, s[14:15]
	s_add_u32 s14, s14, 0xb000
	s_addc_u32 s15, s15, 0
	global_load_dword v38, v15, s[14:15]
	s_add_u32 s14, s14, 0xb000
	s_addc_u32 s15, s15, 0
	global_load_dword v39, v15, s[14:15]
	s_add_u32 s14, s14, 0xb000
	s_addc_u32 s15, s15, 0
	global_load_dword v40, v15, s[14:15]
	s_add_u32 s14, s14, 0xb000
	s_addc_u32 s15, s15, 0
	global_load_dword v41, v15, s[14:15]
	s_add_u32 s14, s14, 0xb000
	s_addc_u32 s15, s15, 0
	global_load_dword v42, v15, s[14:15]
	s_add_u32 s14, s14, 0xb000
	s_addc_u32 s15, s15, 0
	global_load_dword v43, v15, s[14:15]
	s_add_u32 s14, s14, 0xb000
	s_addc_u32 s15, s15, 0
	global_load_dword v44, v15, s[14:15]
	s_add_u32 s14, s14, 0xb000
	s_addc_u32 s15, s15, 0
	global_load_dword v45, v15, s[14:15]
	s_add_u32 s14, s14, 0xb000
	s_addc_u32 s15, s15, 0
	global_load_dword v46, v15, s[14:15]
	s_add_u32 s14, s14, 0xb000
	s_addc_u32 s15, s15, 0
	global_load_dword v47, v15, s[14:15]
	s_lshl_b32 s14, s11, 8
	s_add_u32 s14, s20, s14
	s_addc_u32 s15, s21, 0
	global_load_dwordx4 v[80:83], v14, s[14:15]
	global_load_dwordx4 v[84:87], v14, s[14:15] offset:16
	s_lshr_b32 s16, s12, 2
	s_lshl_b32 s16, s16, 1
	s_add_u32 s16, s16, 1
	s_lshl_b32 s16, s16, 5
	s_add_u32 s16, s16, s11
	s_lshl_b32 s16, s16, 14
	s_and_b32 s17, s12, 3
	s_lshl_b32 s17, s17, 12
	s_add_u32 s16, s16, s17
	s_add_u32 s16, s6, s16
	s_addc_u32 s17, s7, 0
	s_waitcnt vmcnt(34)
; #define LAS __attribute__((address_space(3)))
; __device__ __forceinline__ unsigned pk2(float lo, float hi) { f32x2 f = {lo, hi}; bf16x2_t b = __builtin_convertvector(f, bf16x2_t); return __builtin_bit_cast(unsigned, b); }
; template <int MAP, bool HASG, bool PERMW>
; __device__ __forceinline__ void tr_store(int K, int N, bf16_t* WT, LAS float* scr, int item, int lane, const float* gk) {
;     const int nblk = N / 32, kb = item / nblk, nb = item % nblk, k0 = 64 * kb, n0 = 32 * nb;
;     asm volatile("s_waitcnt lgkmcnt(0)" ::: "memory");
;     const int c = lane & 7;
;     f32x4 g0 = {1.f, 1.f, 1.f, 1.f}, g1 = {1.f, 1.f, 1.f, 1.f};
;     if (HASG) { g0 = *(const f32x4*)(gk + k0 + 8 * c); g1 = *(const f32x4*)(gk + k0 + 8 * c + 4); }
; #pragma unroll
;     for (int j = 0; j < 4; ++j) { const int n = (lane >> 3) + 8 * j; const LAS float* s = scr + (8 * c) * 33 + n;
;         u32x4 o; o.x = pk2(s[0 * 33] * g0[0], s[1 * 33] * g0[1]); o.y = pk2(s[2 * 33] * g0[2], s[3 * 33] * g0[3]); o.z = pk2(s[4 * 33] * g1[0], s[5 * 33] * g1[1]); o.w = pk2(s[6 * 33] * g1[2], s[7 * 33] * g1[3]);
;         const int wr_ = rowmap<MAP>(n0 + n), slot_ = PERMW ? ((wr_ & ~31) + invperm32(wr_ & 31)) : wr_;
;         *(u32x4*)((char*)WT + tiled_off(slot_, k0 + 8 * c, K / 64)) = o; }
;     asm volatile("s_waitcnt lgkmcnt(0)" ::: "memory");
; }
; template <int MAP, bool HASG = false, bool PERMW = false>
; __device__ __forceinline__ void transpose_mat(const float* W, int K, int N, bf16_t* WT, LAS float* scr, int gw, int ngw, int lane, const float* gk = nullptr) {
;     const int nitems = (K / 64) * (N / 32);
;     int it = gw;
;     if (it >= nitems) return;
;     float wv[32];
;     tr_load(W, N, it, lane, wv);
;     for (;;) {
;         __builtin_amdgcn_sched_barrier(0);
; #pragma unroll
;         for (int i = 0; i < 32; ++i) { const int kk = 2 * i + (lane >> 5); scr[kk * 33 + (lane & 31)] = wv[i]; }
;         __builtin_amdgcn_sched_barrier(0);
;         const int nx = it + ngw;
;         if (nx < nitems) tr_load(W, N, nx, lane, wv);
;         __builtin_amdgcn_sched_barrier(0);
;         tr_store<MAP, HASG, PERMW>(K, N, WT, scr, it, lane, gk);
;         if (nx >= nitems) break;
;         it = nx;
;     }
	ds_write_b32 v4, v88
	ds_write_b32 v4, v89 offset:264
	ds_write_b32 v4, v90 offset:528
	ds_write_b32 v4, v91 offset:792
	ds_write_b32 v4, v92 offset:1056
	ds_write_b32 v4, v93 offset:1320
	ds_write_b32 v4, v94 offset:1584
	ds_write_b32 v4, v95 offset:1848
	ds_write_b32 v4, v96 offset:2112
	ds_write_b32 v4, v97 offset:2376
	ds_write_b32 v4, v98 offset:2640
	ds_write_b32 v4, v99 offset:2904
	ds_write_b32 v4, v100 offset:3168
	ds_write_b32 v4, v101 offset:3432
	ds_write_b32 v4, v102 offset:3696
	ds_write_b32 v4, v103 offset:3960
	ds_write_b32 v4, v104 offset:4224
	ds_write_b32 v4, v105 offset:4488
	ds_write_b32 v4, v106 offset:4752
	ds_write_b32 v4, v107 offset:5016
	ds_write_b32 v4, v108 offset:5280
	ds_write_b32 v4, v109 offset:5544
	ds_write_b32 v4, v110 offset:5808
	ds_write_b32 v4, v111 offset:6072
	ds_write_b32 v4, v112 offset:6336
	ds_write_b32 v4, v113 offset:6600
	ds_write_b32 v4, v114 offset:6864
	ds_write_b32 v4, v115 offset:7128
	ds_write_b32 v4, v116 offset:7392
	ds_write_b32 v4, v117 offset:7656
	ds_write_b32 v4, v118 offset:7920
	ds_write_b32 v4, v119 offset:8184
	s_waitcnt lgkmcnt(0)
	ds_read_b32 v48, v7
	ds_read_b32 v49, v7 offset:132
	ds_read_b32 v50, v7 offset:264
	ds_read_b32 v51, v7 offset:396
	ds_read_b32 v52, v7 offset:528
	ds_read_b32 v53, v7 offset:660
	ds_read_b32 v54, v7 offset:792
	ds_read_b32 v55, v7 offset:924
	ds_read_b32 v56, v7 offset:32
	ds_read_b32 v57, v7 offset:164
	ds_read_b32 v58, v7 offset:296
	ds_read_b32 v59, v7 offset:428
	ds_read_b32 v60, v7 offset:560
	ds_read_b32 v61, v7 offset:692
	ds_read_b32 v62, v7 offset:824
	ds_read_b32 v63, v7 offset:956
	ds_read_b32 v64, v7 offset:64
	ds_read_b32 v65, v7 offset:196
	ds_read_b32 v66, v7 offset:328
	ds_read_b32 v67, v7 offset:460
	ds_read_b32 v68, v7 offset:592
	ds_read_b32 v69, v7 offset:724
	ds_read_b32 v70, v7 offset:856
	ds_read_b32 v71, v7 offset:988
	ds_read_b32 v72, v7 offset:96
	ds_read_b32 v73, v7 offset:228
	ds_read_b32 v74, v7 offset:360
	ds_read_b32 v75, v7 offset:492
	ds_read_b32 v76, v7 offset:624
	ds_read_b32 v77, v7 offset:756
	ds_read_b32 v78, v7 offset:888
	ds_read_b32 v79, v7 offset:1020
	s_waitcnt lgkmcnt(0)
	v_mul_f32_e32 v48, v48, v120
	v_mul_f32_e32 v49, v49, v121
	v_mul_f32_e32 v50, v50, v122
	v_mul_f32_e32 v51, v51, v123
	v_mul_f32_e32 v52, v52, v124
	v_mul_f32_e32 v53, v53, v125
	v_mul_f32_e32 v54, v54, v126
	v_mul_f32_e32 v55, v55, v127
	v_cvt_pk_bf16_f32 v48, v48, v49
	v_cvt_pk_bf16_f32 v49, v50, v51
	v_cvt_pk_bf16_f32 v50, v52, v53
	v_cvt_pk_bf16_f32 v51, v54, v55
	global_store_dwordx4 v10, v[48:51], s[24:25]
	v_mul_f32_e32 v56, v56, v120
	v_mul_f32_e32 v57, v57, v121
	v_mul_f32_e32 v58, v58, v122
	v_mul_f32_e32 v59, v59, v123
	v_mul_f32_e32 v60, v60, v124
	v_mul_f32_e32 v61, v61, v125
	v_mul_f32_e32 v62, v62, v126
	v_mul_f32_e32 v63, v63, v127
	v_cvt_pk_bf16_f32 v56, v56, v57
	v_cvt_pk_bf16_f32 v57, v58, v59
	v_cvt_pk_bf16_f32 v58, v60, v61
	v_cvt_pk_bf16_f32 v59, v62, v63
	global_store_dwordx4 v10, v[56:59], s[24:25] offset:256
	v_mul_f32_e32 v64, v64, v120
	v_mul_f32_e32 v65, v65, v121
	v_mul_f32_e32 v66, v66, v122
	v_mul_f32_e32 v67, v67, v123
	v_mul_f32_e32 v68, v68, v124
	v_mul_f32_e32 v69, v69, v125
	v_mul_f32_e32 v70, v70, v126
	v_mul_f32_e32 v71, v71, v127
	v_cvt_pk_bf16_f32 v64, v64, v65
	v_cvt_pk_bf16_f32 v65, v66, v67
	v_cvt_pk_bf16_f32 v66, v68, v69
	v_cvt_pk_bf16_f32 v67, v70, v71
	global_store_dwordx4 v11, v[64:67], s[24:25] offset:512
	v_mul_f32_e32 v72, v72, v120
	v_mul_f32_e32 v73, v73, v121
	v_mul_f32_e32 v74, v74, v122
	v_mul_f32_e32 v75, v75, v123
	v_mul_f32_e32 v76, v76, v124
	v_mul_f32_e32 v77, v77, v125
	v_mul_f32_e32 v78, v78, v126
	v_mul_f32_e32 v79, v79, v127
	v_cvt_pk_bf16_f32 v72, v72, v73
	v_cvt_pk_bf16_f32 v73, v74, v75
	v_cvt_pk_bf16_f32 v74, v76, v77
	v_cvt_pk_bf16_f32 v75, v78, v79
	global_store_dwordx4 v11, v[72:75], s[24:25] offset:768
	s_branch .Ltc3d_loop

; #define LAS __attribute__((address_space(3)))
; __device__ __forceinline__ void tr_load(const float* W, int N, int item, int lane, float (&wv)[32]) {
;     const int nblk = N / 32, kb = item / nblk, nb = item % nblk, k0 = 64 * kb, n0 = 32 * nb;
; #pragma unroll
;     for (int i = 0; i < 32; ++i) { const int kk = 2 * i + (lane >> 5); wv[i] = __builtin_nontemporal_load(W + (size_t)(k0 + kk) * N + n0 + (lane & 31)); }
; }
; template <int MAP, bool HASG, bool PERMW>
; __device__ __forceinline__ void tr_store(int K, int N, bf16_t* WT, LAS float* scr, int item, int lane, const float* gk) {
;     const int nblk = N / 32, kb = item / nblk, nb = item % nblk, k0 = 64 * kb, n0 = 32 * nb;
;     asm volatile("s_waitcnt lgkmcnt(0)" ::: "memory");
;     const int c = lane & 7;
;     f32x4 g0 = {1.f, 1.f, 1.f, 1.f}, g1 = {1.f, 1.f, 1.f, 1.f};
;     if (HASG) { g0 = *(const f32x4*)(gk + k0 + 8 * c); g1 = *(const f32x4*)(gk + k0 + 8 * c + 4); }
; #pragma unroll
;     for (int j = 0; j < 4; ++j) { const int n = (lane >> 3) + 8 * j; const LAS float* s = scr + (8 * c) * 33 + n;
;         u32x4 o; o.x = pk2(s[0 * 33] * g0[0], s[1 * 33] * g0[1]); o.y = pk2(s[2 * 33] * g0[2], s[3 * 33] * g0[3]); o.z = pk2(s[4 * 33] * g1[0], s[5 * 33] * g1[1]); o.w = pk2(s[6 * 33] * g1[2], s[7 * 33] * g1[3]);
;         const int wr_ = rowmap<MAP>(n0 + n), slot_ = PERMW ? ((wr_ & ~31) + invperm32(wr_ & 31)) : wr_;
;         *(u32x4*)((char*)WT + tiled_off(slot_, k0 + 8 * c, K / 64)) = o; }
;     asm volatile("s_waitcnt lgkmcnt(0)" ::: "memory");
; }
; template <int MAP, bool HASG = false, bool PERMW = false>
; __device__ __forceinline__ void transpose_mat(const float* W, int K, int N, bf16_t* WT, LAS float* scr, int gw, int ngw, int lane, const float* gk = nullptr) {
;     const int nitems = (K / 64) * (N / 32);
;     int it = gw;
;     if (it >= nitems) return;
;     float wv[32];
;     tr_load(W, N, it, lane, wv);
; __global__ void __launch_bounds__(512, 2) mega_fwd(Params p) {
;     ...
;             transpose_mat<1, true, true>(p.in[2] + (size_t)l * D * DFF, D, DFF, P_W(WS_WGU1), scr, gw, ngw, lane, p.in[1] + l * D);
;             transpose_mat<2, true, true>(p.in[3] + (size_t)l * D * DFF, D, DFF, P_W(WS_WGU1), scr, gw, ngw, lane, p.in[1] + l * D);
;             transpose_mat<0>(p.in[4] + (size_t)l * DFF * D, DFF, D, P_W(WS_WD1), scr, gw, ngw, lane);
.LBB0_826:
	s_lshr_b32 vcc_lo, s78, 1
	s_cmp_lt_u32 s2, vcc_lo
	s_cbranch_scc1 .Ltc2_done
	v_writelane_b32 v255, s4, 24
	v_writelane_b32 v255, s5, 25
	v_writelane_b32 v255, s6, 26
	v_writelane_b32 v255, s7, 27
	v_writelane_b32 v255, s8, 28
	v_writelane_b32 v255, s9, 29
	v_writelane_b32 v255, s10, 30
	v_writelane_b32 v255, s11, 31
	v_writelane_b32 v255, s12, 32
	v_writelane_b32 v255, s13, 33
	v_writelane_b32 v255, s14, 34
	v_writelane_b32 v255, s15, 35
	v_writelane_b32 v255, s16, 36
	v_writelane_b32 v255, s17, 37
	v_writelane_b32 v255, s18, 38
	v_writelane_b32 v255, s19, 39
	v_writelane_b32 v255, s20, 40
	v_writelane_b32 v255, s21, 41
	v_writelane_b32 v255, s22, 42
	v_writelane_b32 v255, s23, 43
	v_writelane_b32 v255, s24, 44
	v_writelane_b32 v255, s25, 45
	v_writelane_b32 v255, s26, 46
	v_writelane_b32 v255, s27, 47
	v_writelane_b32 v255, s28, 48
	v_writelane_b32 v255, s29, 49
	v_readfirstlane_b32 s8, v234
	s_nop 3
	s_lshr_b32 s8, s8, 6
	s_lshr_b32 s19, s78, 1
	s_sub_u32 s18, s2, s19
	s_lshl_b32 s18, s18, 3
	s_add_u32 s18, s18, s8
	s_sub_u32 s19, s78, s19
	s_lshl_b32 s19, s19, 3
	s_mul_i32 s10, s8, 0x2100
	v_and_b32_e32 v0, 63, v234
	v_and_b32_e32 v1, 31, v0
	v_lshrrev_b32_e32 v2, 5, v0
	v_lshlrev_b32_e32 v3, 13, v2
	v_lshl_add_u32 v3, v1, 2, v3
	v_mul_u32_u24_e32 v4, 33, v2
	v_add_u32_e32 v4, v4, v1
	v_lshl_add_u32 v4, v4, 2, s10
	v_and_b32_e32 v5, 7, v0
	v_lshrrev_b32_e32 v6, 3, v0
	v_mul_u32_u24_e32 v7, 0x108, v5
	v_add_u32_e32 v7, v7, v6
	v_lshl_add_u32 v7, v7, 2, s10
	v_lshrrev_b32_e32 v12, 2, v5
	v_lshlrev_b32_e32 v12, 10, v12
	v_and_b32_e32 v13, 3, v5
	v_lshl_add_u32 v12, v13, 4, v12
	v_lshl_add_u32 v8, v6, 6, v12
	v_xor_b32_e32 v9, 32, v8
	v_add_u32_e32 v9, 0x200, v9
	v_and_b32_e32 v13, 3, v6
	v_lshl_add_u32 v10, v13, 6, v12
	v_bfe_u32 v13, v6, 2, 1
	v_lshl_add_u32 v10, v13, 11, v10
	v_xor_b32_e32 v11, 32, v10
	v_lshlrev_b32_e32 v14, 5, v5
	v_mul_u32_u24_e32 v15, 0x5800, v2
	v_lshl_add_u32 v15, v1, 2, v15
	v_mul_u32_u24_e32 v12, 0xd000, v2
	v_lshl_add_u32 v12, v1, 2, v12
	v_readlane_b32 s4, v254, 10
	v_readlane_b32 s5, v254, 11
	s_nop 3
	s_and_b32 s6, s60, 0x2c00000
	s_add_u32 s4, s4, s6
	s_addc_u32 s5, s5, 0
	s_add_u32 s6, s76, 0xb600000
	s_addc_u32 s7, s77, 0
	s_mov_b32 s9, s18
	s_cmpk_ge_u32 s9, 0x1600
	s_cbranch_scc1 .Ltc2a_exit
	s_lshr_b32 s11, s9, 6
	s_and_b32 s12, s9, 63
	s_lshl_b32 s13, s11, 19
	s_lshl_b32 s14, s12, 7
	s_add_u32 s13, s13, s14
	s_add_u32 s14, s4, s13
	s_addc_u32 s15, s5, 0
	global_load_dword v16, v3, s[14:15]
	s_add_u32 s14, s14, 0x4000
	s_addc_u32 s15, s15, 0
	global_load_dword v17, v3, s[14:15]
	s_add_u32 s14, s14, 0x4000
	s_addc_u32 s15, s15, 0
	global_load_dword v18, v3, s[14:15]
	s_add_u32 s14, s14, 0x4000
	s_addc_u32 s15, s15, 0
	global_load_dword v19, v3, s[14:15]
	s_add_u32 s14, s14, 0x4000
	s_addc_u32 s15, s15, 0
	global_load_dword v20, v3, s[14:15]
	s_add_u32 s14, s14, 0x4000
	s_addc_u32 s15, s15, 0
	global_load_dword v21, v3, s[14:15]
	s_add_u32 s14, s14, 0x4000
	s_addc_u32 s15, s15, 0
	global_load_dword v22, v3, s[14:15]
	s_add_u32 s14, s14, 0x4000
	s_addc_u32 s15, s15, 0
	global_load_dword v23, v3, s[14:15]
	s_add_u32 s14, s14, 0x4000
	s_addc_u32 s15, s15, 0
	global_load_dword v24, v3, s[14:15]
	s_add_u32 s14, s14, 0x4000
	s_addc_u32 s15, s15, 0
	global_load_dword v25, v3, s[14:15]
	s_add_u32 s14, s14, 0x4000
	s_addc_u32 s15, s15, 0
	global_load_dword v26, v3, s[14:15]
	s_add_u32 s14, s14, 0x4000
	s_addc_u32 s15, s15, 0
	global_load_dword v27, v3, s[14:15]
	s_add_u32 s14, s14, 0x4000
	s_addc_u32 s15, s15, 0
	global_load_dword v28, v3, s[14:15]
	s_add_u32 s14, s14, 0x4000
	s_addc_u32 s15, s15, 0
	global_load_dword v29, v3, s[14:15]
	s_add_u32 s14, s14, 0x4000
	s_addc_u32 s15, s15, 0
	global_load_dword v30, v3, s[14:15]
	s_add_u32 s14, s14, 0x4000
	s_addc_u32 s15, s15, 0
	global_load_dword v31, v3, s[14:15]
	s_add_u32 s14, s14, 0x4000
	s_addc_u32 s15, s15, 0
	global_load_dword v32, v3, s[14:15]
	s_add_u32 s14, s14, 0x4000
	s_addc_u32 s15, s15, 0
	global_load_dword v33, v3, s[14:15]
	s_add_u32 s14, s14, 0x4000
	s_addc_u32 s15, s15, 0
	global_load_dword v34, v3, s[14:15]
	s_add_u32 s14, s14, 0x4000
	s_addc_u32 s15, s15, 0
	global_load_dword v35, v3, s[14:15]
	s_add_u32 s14, s14, 0x4000
	s_addc_u32 s15, s15, 0
	global_load_dword v36, v3, s[14:15]
	s_add_u32 s14, s14, 0x4000
	s_addc_u32 s15, s15, 0
	global_load_dword v37, v3, s[14:15]
	s_add_u32 s14, s14, 0x4000
	s_addc_u32 s15, s15, 0
	global_load_dword v38, v3, s[14:15]
	s_add_u32 s14, s14, 0x4000
	s_addc_u32 s15, s15, 0
	global_load_dword v39, v3, s[14:15]
	s_add_u32 s14, s14, 0x4000
	s_addc_u32 s15, s15, 0
	global_load_dword v40, v3, s[14:15]
	s_add_u32 s14, s14, 0x4000
	s_addc_u32 s15, s15, 0
	global_load_dword v41, v3, s[14:15]
	s_add_u32 s14, s14, 0x4000
	s_addc_u32 s15, s15, 0
	global_load_dword v42, v3, s[14:15]
	s_add_u32 s14, s14, 0x4000
	s_addc_u32 s15, s15, 0
	global_load_dword v43, v3, s[14:15]
	s_add_u32 s14, s14, 0x4000
	s_addc_u32 s15, s15, 0
	global_load_dword v44, v3, s[14:15]
	s_add_u32 s14, s14, 0x4000
	s_addc_u32 s15, s15, 0
	global_load_dword v45, v3, s[14:15]
	s_add_u32 s14, s14, 0x4000
	s_addc_u32 s15, s15, 0
	global_load_dword v46, v3, s[14:15]
	s_add_u32 s14, s14, 0x4000
	s_addc_u32 s15, s15, 0
	global_load_dword v47, v3, s[14:15]
	s_lshr_b32 s16, s12, 2
	s_mul_i32 s16, s16, 0x58
	s_add_u32 s16, s16, s11
	s_lshl_b32 s16, s16, 14
	s_and_b32 s17, s12, 3
	s_lshl_b32 s17, s17, 12
	s_add_u32 s16, s16, s17
	s_add_u32 s16, s6, s16
	s_addc_u32 s17, s7, 0

; #define LAS __attribute__((address_space(3)))
; __device__ __forceinline__ unsigned pk2(float lo, float hi) { f32x2 f = {lo, hi}; bf16x2_t b = __builtin_convertvector(f, bf16x2_t); return __builtin_bit_cast(unsigned, b); }
; __device__ __forceinline__ void tr_load(const float* W, int N, int item, int lane, float (&wv)[32]) {
;     const int nblk = N / 32, kb = item / nblk, nb = item % nblk, k0 = 64 * kb, n0 = 32 * nb;
; #pragma unroll
;     for (int i = 0; i < 32; ++i) { const int kk = 2 * i + (lane >> 5); wv[i] = __builtin_nontemporal_load(W + (size_t)(k0 + kk) * N + n0 + (lane & 31)); }
; }
; template <int MAP, bool HASG, bool PERMW>
; __device__ __forceinline__ void tr_store(int K, int N, bf16_t* WT, LAS float* scr, int item, int lane, const float* gk) {
;     const int nblk = N / 32, kb = item / nblk, nb = item % nblk, k0 = 64 * kb, n0 = 32 * nb;
;     asm volatile("s_waitcnt lgkmcnt(0)" ::: "memory");
;     const int c = lane & 7;
;     f32x4 g0 = {1.f, 1.f, 1.f, 1.f}, g1 = {1.f, 1.f, 1.f, 1.f};
;     if (HASG) { g0 = *(const f32x4*)(gk + k0 + 8 * c); g1 = *(const f32x4*)(gk + k0 + 8 * c + 4); }
; #pragma unroll
;     for (int j = 0; j < 4; ++j) { const int n = (lane >> 3) + 8 * j; const LAS float* s = scr + (8 * c) * 33 + n;
;         u32x4 o; o.x = pk2(s[0 * 33] * g0[0], s[1 * 33] * g0[1]); o.y = pk2(s[2 * 33] * g0[2], s[3 * 33] * g0[3]); o.z = pk2(s[4 * 33] * g1[0], s[5 * 33] * g1[1]); o.w = pk2(s[6 * 33] * g1[2], s[7 * 33] * g1[3]);
;         const int wr_ = rowmap<MAP>(n0 + n), slot_ = PERMW ? ((wr_ & ~31) + invperm32(wr_ & 31)) : wr_;
;         *(u32x4*)((char*)WT + tiled_off(slot_, k0 + 8 * c, K / 64)) = o; }
;     asm volatile("s_waitcnt lgkmcnt(0)" ::: "memory");
; }
; template <int MAP, bool HASG = false, bool PERMW = false>
; __device__ __forceinline__ void transpose_mat(const float* W, int K, int N, bf16_t* WT, LAS float* scr, int gw, int ngw, int lane, const float* gk = nullptr) {
;     const int nitems = (K / 64) * (N / 32);
;     int it = gw;
;     if (it >= nitems) return;
;     float wv[32];
;     tr_load(W, N, it, lane, wv);
; __global__ void __launch_bounds__(512, 2) mega_fwd(Params p) {
;     ...
;             transpose_mat<1, true, true>(p.in[2] + (size_t)l * D * DFF, D, DFF, P_W(WS_WGU1), scr, gw, ngw, lane, p.in[1] + l * D);
.Ltc2a_exit:
	s_cmp_lg_u32 s60, 0
	s_cbranch_scc1 .Ltc2_nonext
	v_readlane_b32 s4, v255, 0
	v_readlane_b32 s5, v255, 1
	v_readlane_b32 s20, v254, 62
	v_readlane_b32 s21, v254, 63
	s_nop 3
	s_andn2_b32 s6, 0x2c00000, s60
	s_add_u32 s4, s4, s6
	s_addc_u32 s5, s5, 0
	s_andn2_b32 s6, 0x2000, s60
	s_add_u32 s20, s20, s6
	s_addc_u32 s21, s21, 0
	s_add_u32 s6, s76, 0x0
	s_addc_u32 s7, s77, 0
	s_mov_b32 s9, s18
	s_cmpk_ge_u32 s9, 0x1600
	s_cbranch_scc1 .Ltc2b_exit
	s_mul_hi_u32 s11, s9, 0x2e8ba2e9
	s_lshr_b32 s11, s11, 5
	s_mul_i32 s12, s11, 0xb0
	s_sub_u32 s12, s9, s12
	s_mul_i32 s13, s11, 0x160000
	s_lshl_b32 s14, s12, 7
	s_add_u32 s13, s13, s14
	s_add_u32 s14, s4, s13
	s_addc_u32 s15, s5, 0
	global_load_dword v16, v15, s[14:15]
	s_add_u32 s14, s14, 0xb000
	s_addc_u32 s15, s15, 0
	global_load_dword v17, v15, s[14:15]
	s_add_u32 s14, s14, 0xb000
	s_addc_u32 s15, s15, 0
	global_load_dword v18, v15, s[14:15]
	s_add_u32 s14, s14, 0xb000
	s_addc_u32 s15, s15, 0
	global_load_dword v19, v15, s[14:15]
	s_add_u32 s14, s14, 0xb000
	s_addc_u32 s15, s15, 0
	global_load_dword v20, v15, s[14:15]
	s_add_u32 s14, s14, 0xb000
	s_addc_u32 s15, s15, 0
	global_load_dword v21, v15, s[14:15]
	s_add_u32 s14, s14, 0xb000
	s_addc_u32 s15, s15, 0
	global_load_dword v22, v15, s[14:15]
	s_add_u32 s14, s14, 0xb000
	s_addc_u32 s15, s15, 0
	global_load_dword v23, v15, s[14:15]
	s_add_u32 s14, s14, 0xb000
	s_addc_u32 s15, s15, 0
	global_load_dword v24, v15, s[14:15]
	s_add_u32 s14, s14, 0xb000
	s_addc_u32 s15, s15, 0
	global_load_dword v25, v15, s[14:15]
	s_add_u32 s14, s14, 0xb000
	s_addc_u32 s15, s15, 0
	global_load_dword v26, v15, s[14:15]
	s_add_u32 s14, s14, 0xb000
	s_addc_u32 s15, s15, 0
	global_load_dword v27, v15, s[14:15]
	s_add_u32 s14, s14, 0xb000
	s_addc_u32 s15, s15, 0
	global_load_dword v28, v15, s[14:15]
	s_add_u32 s14, s14, 0xb000
	s_addc_u32 s15, s15, 0
	global_load_dword v29, v15, s[14:15]
	s_add_u32 s14, s14, 0xb000
	s_addc_u32 s15, s15, 0
	global_load_dword v30, v15, s[14:15]
	s_add_u32 s14, s14, 0xb000
	s_addc_u32 s15, s15, 0
	global_load_dword v31, v15, s[14:15]
	s_add_u32 s14, s14, 0xb000
	s_addc_u32 s15, s15, 0
	global_load_dword v32, v15, s[14:15]
	s_add_u32 s14, s14, 0xb000
	s_addc_u32 s15, s15, 0
	global_load_dword v33, v15, s[14:15]
	s_add_u32 s14, s14, 0xb000
	s_addc_u32 s15, s15, 0
	global_load_dword v34, v15, s[14:15]
	s_add_u32 s14, s14, 0xb000
	s_addc_u32 s15, s15, 0
	global_load_dword v35, v15, s[14:15]
	s_add_u32 s14, s14, 0xb000
	s_addc_u32 s15, s15, 0
	global_load_dword v36, v15, s[14:15]
	s_add_u32 s14, s14, 0xb000
	s_addc_u32 s15, s15, 0
	global_load_dword v37, v15, s[14:15]
	s_add_u32 s14, s14, 0xb000
	s_addc_u32 s15, s15, 0
	global_load_dword v38, v15, s[14:15]
	s_add_u32 s14, s14, 0xb000
	s_addc_u32 s15, s15, 0
	global_load_dword v39, v15, s[14:15]
	s_add_u32 s14, s14, 0xb000
	s_addc_u32 s15, s15, 0
	global_load_dword v40, v15, s[14:15]
	s_add_u32 s14, s14, 0xb000
	s_addc_u32 s15, s15, 0
	global_load_dword v41, v15, s[14:15]
	s_add_u32 s14, s14, 0xb000
	s_addc_u32 s15, s15, 0
	global_load_dword v42, v15, s[14:15]
	s_add_u32 s14, s14, 0xb000
	s_addc_u32 s15, s15, 0
	global_load_dword v43, v15, s[14:15]
	s_add_u32 s14, s14, 0xb000
	s_addc_u32 s15, s15, 0
	global_load_dword v44, v15, s[14:15]
	s_add_u32 s14, s14, 0xb000
	s_addc_u32 s15, s15, 0
	global_load_dword v45, v15, s[14:15]
	s_add_u32 s14, s14, 0xb000
	s_addc_u32 s15, s15, 0
	global_load_dword v46, v15, s[14:15]
	s_add_u32 s14, s14, 0xb000
	s_addc_u32 s15, s15, 0
	global_load_dword v47, v15, s[14:15]
	s_lshl_b32 s14, s11, 8
	s_add_u32 s14, s20, s14
	s_addc_u32 s15, s21, 0
	global_load_dwordx4 v[80:83], v14, s[14:15]
	global_load_dwordx4 v[84:87], v14, s[14:15] offset:16
	s_lshr_b32 s16, s12, 2
	s_lshl_b32 s16, s16, 1
	s_lshl_b32 s16, s16, 5
	s_add_u32 s16, s16, s11
	s_lshl_b32 s16, s16, 14
	s_and_b32 s17, s12, 3
	s_lshl_b32 s17, s17, 12
	s_add_u32 s16, s16, s17
	s_add_u32 s16, s6, s16
	s_addc_u32 s17, s7, 0

; #define LAS __attribute__((address_space(3)))
; __device__ __forceinline__ unsigned pk2(float lo, float hi) { f32x2 f = {lo, hi}; bf16x2_t b = __builtin_convertvector(f, bf16x2_t); return __builtin_bit_cast(unsigned, b); }
; __device__ __forceinline__ void tr_load(const float* W, int N, int item, int lane, float (&wv)[32]) {
;     const int nblk = N / 32, kb = item / nblk, nb = item % nblk, k0 = 64 * kb, n0 = 32 * nb;
; #pragma unroll
;     for (int i = 0; i < 32; ++i) { const int kk = 2 * i + (lane >> 5); wv[i] = __builtin_nontemporal_load(W + (size_t)(k0 + kk) * N + n0 + (lane & 31)); }
; }
; template <int MAP, bool HASG, bool PERMW>
; __device__ __forceinline__ void tr_store(int K, int N, bf16_t* WT, LAS float* scr, int item, int lane, const float* gk) {
;     const int nblk = N / 32, kb = item / nblk, nb = item % nblk, k0 = 64 * kb, n0 = 32 * nb;
;     asm volatile("s_waitcnt lgkmcnt(0)" ::: "memory");
;     const int c = lane & 7;
;     f32x4 g0 = {1.f, 1.f, 1.f, 1.f}, g1 = {1.f, 1.f, 1.f, 1.f};
;     if (HASG) { g0 = *(const f32x4*)(gk + k0 + 8 * c); g1 = *(const f32x4*)(gk + k0 + 8 * c + 4); }
; #pragma unroll
;     for (int j = 0; j < 4; ++j) { const int n = (lane >> 3) + 8 * j; const LAS float* s = scr + (8 * c) * 33 + n;
;         u32x4 o; o.x = pk2(s[0 * 33] * g0[0], s[1 * 33] * g0[1]); o.y = pk2(s[2 * 33] * g0[2], s[3 * 33] * g0[3]); o.z = pk2(s[4 * 33] * g1[0], s[5 * 33] * g1[1]); o.w = pk2(s[6 * 33] * g1[2], s[7 * 33] * g1[3]);
;         const int wr_ = rowmap<MAP>(n0 + n), slot_ = PERMW ? ((wr_ & ~31) + invperm32(wr_ & 31)) : wr_;
;         *(u32x4*)((char*)WT + tiled_off(slot_, k0 + 8 * c, K / 64)) = o; }
;     asm volatile("s_waitcnt lgkmcnt(0)" ::: "memory");
; }
; template <int MAP, bool HASG = false, bool PERMW = false>
; __device__ __forceinline__ void transpose_mat(const float* W, int K, int N, bf16_t* WT, LAS float* scr, int gw, int ngw, int lane, const float* gk = nullptr) {
;     const int nitems = (K / 64) * (N / 32);
;     int it = gw;
;     if (it >= nitems) return;
;     float wv[32];
;     tr_load(W, N, it, lane, wv);
; __global__ void __launch_bounds__(512, 2) mega_fwd(Params p) {
;     ...
;             transpose_mat<2, true, true>(p.in[3] + (size_t)l * D * DFF, D, DFF, P_W(WS_WGU1), scr, gw, ngw, lane, p.in[1] + l * D);
.Ltc2b_exit:
	v_readlane_b32 s4, v255, 2
	v_readlane_b32 s5, v255, 3
	v_readlane_b32 s20, v254, 62
	v_readlane_b32 s21, v254, 63
	s_nop 3
	s_andn2_b32 s6, 0x2c00000, s60
	s_add_u32 s4, s4, s6
	s_addc_u32 s5, s5, 0
	s_andn2_b32 s6, 0x2000, s60
	s_add_u32 s20, s20, s6
	s_addc_u32 s21, s21, 0
	s_add_u32 s6, s76, 0x0
	s_addc_u32 s7, s77, 0
	s_mov_b32 s9, s18
	s_cmpk_ge_u32 s9, 0x1600
	s_cbranch_scc1 .Ltc2c_exit
	s_mul_hi_u32 s11, s9, 0x2e8ba2e9
	s_lshr_b32 s11, s11, 5
	s_mul_i32 s12, s11, 0xb0
	s_sub_u32 s12, s9, s12
	s_mul_i32 s13, s11, 0x160000
	s_lshl_b32 s14, s12, 7
	s_add_u32 s13, s13, s14
	s_add_u32 s14, s4, s13
	s_addc_u32 s15, s5, 0
	global_load_dword v16, v15, s[14:15]
	s_add_u32 s14, s14, 0xb000
	s_addc_u32 s15, s15, 0
	global_load_dword v17, v15, s[14:15]
	s_add_u32 s14, s14, 0xb000
	s_addc_u32 s15, s15, 0
	global_load_dword v18, v15, s[14:15]
	s_add_u32 s14, s14, 0xb000
	s_addc_u32 s15, s15, 0
	global_load_dword v19, v15, s[14:15]
	s_add_u32 s14, s14, 0xb000
	s_addc_u32 s15, s15, 0
	global_load_dword v20, v15, s[14:15]
	s_add_u32 s14, s14, 0xb000
	s_addc_u32 s15, s15, 0
	global_load_dword v21, v15, s[14:15]
	s_add_u32 s14, s14, 0xb000
	s_addc_u32 s15, s15, 0
	global_load_dword v22, v15, s[14:15]
	s_add_u32 s14, s14, 0xb000
	s_addc_u32 s15, s15, 0
	global_load_dword v23, v15, s[14:15]
	s_add_u32 s14, s14, 0xb000
	s_addc_u32 s15, s15, 0
	global_load_dword v24, v15, s[14:15]
	s_add_u32 s14, s14, 0xb000
	s_addc_u32 s15, s15, 0
	global_load_dword v25, v15, s[14:15]
	s_add_u32 s14, s14, 0xb000
	s_addc_u32 s15, s15, 0
	global_load_dword v26, v15, s[14:15]
	s_add_u32 s14, s14, 0xb000
	s_addc_u32 s15, s15, 0
	global_load_dword v27, v15, s[14:15]
	s_add_u32 s14, s14, 0xb000
	s_addc_u32 s15, s15, 0
	global_load_dword v28, v15, s[14:15]
	s_add_u32 s14, s14, 0xb000
	s_addc_u32 s15, s15, 0
	global_load_dword v29, v15, s[14:15]
	s_add_u32 s14, s14, 0xb000
	s_addc_u32 s15, s15, 0
	global_load_dword v30, v15, s[14:15]
	s_add_u32 s14, s14, 0xb000
	s_addc_u32 s15, s15, 0
	global_load_dword v31, v15, s[14:15]
	s_add_u32 s14, s14, 0xb000
	s_addc_u32 s15, s15, 0
	global_load_dword v32, v15, s[14:15]
	s_add_u32 s14, s14, 0xb000
	s_addc_u32 s15, s15, 0
	global_load_dword v33, v15, s[14:15]
	s_add_u32 s14, s14, 0xb000
	s_addc_u32 s15, s15, 0
	global_load_dword v34, v15, s[14:15]
	s_add_u32 s14, s14, 0xb000
	s_addc_u32 s15, s15, 0
	global_load_dword v35, v15, s[14:15]
	s_add_u32 s14, s14, 0xb000
	s_addc_u32 s15, s15, 0
	global_load_dword v36, v15, s[14:15]
	s_add_u32 s14, s14, 0xb000
	s_addc_u32 s15, s15, 0
	global_load_dword v37, v15, s[14:15]
	s_add_u32 s14, s14, 0xb000
	s_addc_u32 s15, s15, 0
	global_load_dword v38, v15, s[14:15]
	s_add_u32 s14, s14, 0xb000
	s_addc_u32 s15, s15, 0
	global_load_dword v39, v15, s[14:15]
	s_add_u32 s14, s14, 0xb000
	s_addc_u32 s15, s15, 0
	global_load_dword v40, v15, s[14:15]
	s_add_u32 s14, s14, 0xb000
	s_addc_u32 s15, s15, 0
	global_load_dword v41, v15, s[14:15]
	s_add_u32 s14, s14, 0xb000
	s_addc_u32 s15, s15, 0
	global_load_dword v42, v15, s[14:15]
	s_add_u32 s14, s14, 0xb000
	s_addc_u32 s15, s15, 0
	global_load_dword v43, v15, s[14:15]
	s_add_u32 s14, s14, 0xb000
	s_addc_u32 s15, s15, 0
	global_load_dword v44, v15, s[14:15]
	s_add_u32 s14, s14, 0xb000
	s_addc_u32 s15, s15, 0
	global_load_dword v45, v15, s[14:15]
	s_add_u32 s14, s14, 0xb000
	s_addc_u32 s15, s15, 0
	global_load_dword v46, v15, s[14:15]
	s_add_u32 s14, s14, 0xb000
	s_addc_u32 s15, s15, 0
	global_load_dword v47, v15, s[14:15]
	s_lshl_b32 s14, s11, 8
	s_add_u32 s14, s20, s14
	s_addc_u32 s15, s21, 0
	global_load_dwordx4 v[80:83], v14, s[14:15]
	global_load_dwordx4 v[84:87], v14, s[14:15] offset:16
	s_lshr_b32 s16, s12, 2
	s_lshl_b32 s16, s16, 1
	s_add_u32 s16, s16, 1
	s_lshl_b32 s16, s16, 5
	s_add_u32 s16, s16, s11
	s_lshl_b32 s16, s16, 14
	s_and_b32 s17, s12, 3
	s_lshl_b32 s17, s17, 12
	s_add_u32 s16, s16, s17
	s_add_u32 s16, s6, s16
	s_addc_u32 s17, s7, 0
